# v16 + GEMM K-loops keep priority raised across both 16-MFMA blocks of a super-phase
# speedup vs baseline: 1.0070x; 1.0048x over previous
.LBB0_394:
	s_add_u32 s0, s24, 0xfff80080
	s_addc_u32 s1, s25, -1
	s_add_i32 s33, 0, 0x10000
	s_cmp_eq_u32 s60, 28
	s_cselect_b32 s29, s7, s1
	s_cselect_b32 s28, s19, s0
	s_cselect_b32 s27, s17, s59
	s_cselect_b32 s26, s49, s58
	s_add_i32 s55, 0, 0x14000
	v_add_u32_e32 v158, s33, v151
	v_add_u32_e32 v174, s55, v151
	ds_read_b128 v[142:145], v158
	ds_read_b128 v[146:149], v158 offset:1024
	ds_read_b128 v[154:157], v158 offset:2048
	ds_read_b128 v[158:161], v158 offset:3072
	ds_read_b128 v[162:165], v174
	ds_read_b128 v[166:169], v174 offset:1024
	ds_read_b128 v[170:173], v174 offset:2048
	ds_read_b128 v[174:177], v174 offset:3072
	v_lshl_add_u64 v[204:205], s[24:25], 0, v[138:139]
	s_add_i32 m0, s9, 0xc000
	ds_read_b128 v[178:181], v153
	ds_read_b128 v[182:185], v153 offset:1024
	ds_read_b128 v[186:189], v153 offset:2048
	ds_read_b128 v[190:193], v153 offset:3072
	ds_read_b128 v[194:197], v153 offset:4096
	ds_read_b128 v[198:201], v153 offset:5120
	ds_read_b128 v[208:211], v153 offset:6144
	ds_read_b128 v[212:215], v153 offset:7168
	global_load_lds_dwordx4 v[204:205], off
	v_lshl_add_u64 v[204:205], s[24:25], 0, v[140:141]
	s_add_i32 m0, s9, 0xe000
	s_nop 0
	global_load_lds_dwordx4 v[204:205], off
	s_waitcnt vmcnt(8)
	s_waitcnt lgkmcnt(0)
	s_barrier
	s_setprio 1
	s_waitcnt lgkmcnt(0)
	v_mfma_f32_16x16x32_bf16 v[126:129], v[142:145], v[178:181], v[126:129]
	v_mfma_f32_16x16x32_bf16 v[122:125], v[154:157], v[178:181], v[122:125]
	v_mfma_f32_16x16x32_bf16 v[110:113], v[142:145], v[186:189], v[110:113]
	v_mfma_f32_16x16x32_bf16 v[106:109], v[154:157], v[186:189], v[106:109]
	v_mfma_f32_16x16x32_bf16 v[94:97], v[142:145], v[194:197], v[94:97]
	v_mfma_f32_16x16x32_bf16 v[90:93], v[154:157], v[194:197], v[90:93]
	v_mfma_f32_16x16x32_bf16 v[78:81], v[142:145], v[208:211], v[78:81]
	v_mfma_f32_16x16x32_bf16 v[74:77], v[154:157], v[208:211], v[74:77]
	v_mfma_f32_16x16x32_bf16 v[126:129], v[146:149], v[182:185], v[126:129]
	v_mfma_f32_16x16x32_bf16 v[122:125], v[158:161], v[182:185], v[122:125]
	v_mfma_f32_16x16x32_bf16 v[110:113], v[146:149], v[190:193], v[110:113]
	v_mfma_f32_16x16x32_bf16 v[106:109], v[158:161], v[190:193], v[106:109]
	v_mfma_f32_16x16x32_bf16 v[94:97], v[146:149], v[198:201], v[94:97]
	v_mfma_f32_16x16x32_bf16 v[90:93], v[158:161], v[198:201], v[90:93]
	v_mfma_f32_16x16x32_bf16 v[78:81], v[146:149], v[212:215], v[78:81]
	v_mfma_f32_16x16x32_bf16 v[74:77], v[158:161], v[212:215], v[74:77]
	v_mfma_f32_16x16x32_bf16 v[118:121], v[162:165], v[178:181], v[118:121]
	v_mfma_f32_16x16x32_bf16 v[114:117], v[170:173], v[178:181], v[114:117]
	v_mfma_f32_16x16x32_bf16 v[102:105], v[162:165], v[186:189], v[102:105]
	v_mfma_f32_16x16x32_bf16 v[98:101], v[170:173], v[186:189], v[98:101]
	v_mfma_f32_16x16x32_bf16 v[86:89], v[162:165], v[194:197], v[86:89]
	v_mfma_f32_16x16x32_bf16 v[82:85], v[170:173], v[194:197], v[82:85]
	v_mfma_f32_16x16x32_bf16 v[70:73], v[162:165], v[208:211], v[70:73]
	v_mfma_f32_16x16x32_bf16 v[66:69], v[170:173], v[208:211], v[66:69]
	v_mfma_f32_16x16x32_bf16 v[118:121], v[166:169], v[182:185], v[118:121]
	v_mfma_f32_16x16x32_bf16 v[114:117], v[174:177], v[182:185], v[114:117]
	v_mfma_f32_16x16x32_bf16 v[102:105], v[166:169], v[190:193], v[102:105]
	v_mfma_f32_16x16x32_bf16 v[98:101], v[174:177], v[190:193], v[98:101]
	v_mfma_f32_16x16x32_bf16 v[86:89], v[166:169], v[198:201], v[86:89]
	v_mfma_f32_16x16x32_bf16 v[82:85], v[174:177], v[198:201], v[82:85]
	v_mfma_f32_16x16x32_bf16 v[70:73], v[166:169], v[212:215], v[70:73]
	v_mfma_f32_16x16x32_bf16 v[66:69], v[174:177], v[212:215], v[66:69]
	s_setprio 0
	s_barrier
	s_add_i32 s0, s33, s34
	v_lshl_add_u64 v[204:205], s[26:27], 0, v[132:133]
	s_mov_b32 m0, s0
	ds_read_b128 v[178:181], v153 offset:16384
	ds_read_b128 v[182:185], v153 offset:17408
	ds_read_b128 v[186:189], v153 offset:18432
	ds_read_b128 v[190:193], v153 offset:19456
	ds_read_b128 v[194:197], v153 offset:20480
	ds_read_b128 v[198:201], v153 offset:21504
	ds_read_b128 v[208:211], v153 offset:22528
	ds_read_b128 v[212:215], v153 offset:23552
	global_load_lds_dwordx4 v[204:205], off
	s_add_i32 m0, s0, 0x2000
	s_add_u32 s0, s26, 0x80000
	v_lshl_add_u64 v[216:217], s[26:27], 0, v[136:137]
	s_addc_u32 s1, s27, 0
	s_add_i32 s33, s55, s34
	global_load_lds_dwordx4 v[216:217], off
	v_lshl_add_u64 v[218:219], s[0:1], 0, v[132:133]
	s_mov_b32 m0, s33
	v_lshl_add_u64 v[220:221], s[28:29], 0, v[134:135]
	global_load_lds_dwordx4 v[218:219], off
	v_lshl_add_u64 v[218:219], s[0:1], 0, v[136:137]
	s_add_i32 m0, s33, 0x2000
	s_nop 0
	global_load_lds_dwordx4 v[218:219], off
	v_lshl_add_u64 v[218:219], s[28:29], 0, v[130:131]
	s_mov_b32 m0, s9
	s_nop 0
	global_load_lds_dwordx4 v[218:219], off
	s_mov_b32 m0, s35
	s_nop 0
	global_load_lds_dwordx4 v[220:221], off
	s_waitcnt vmcnt(8)
	s_waitcnt lgkmcnt(0)
	s_barrier
	s_setprio 1
	s_waitcnt lgkmcnt(0)
	v_mfma_f32_16x16x32_bf16 v[62:65], v[142:145], v[178:181], v[62:65]
	v_mfma_f32_16x16x32_bf16 v[58:61], v[154:157], v[178:181], v[58:61]
	v_mfma_f32_16x16x32_bf16 v[46:49], v[142:145], v[186:189], v[46:49]
	v_mfma_f32_16x16x32_bf16 v[42:45], v[154:157], v[186:189], v[42:45]
	v_mfma_f32_16x16x32_bf16 v[30:33], v[142:145], v[194:197], v[30:33]
	v_mfma_f32_16x16x32_bf16 v[26:29], v[154:157], v[194:197], v[26:29]
	v_mfma_f32_16x16x32_bf16 v[14:17], v[142:145], v[208:211], v[14:17]
	v_mfma_f32_16x16x32_bf16 v[10:13], v[154:157], v[208:211], v[10:13]
	v_mfma_f32_16x16x32_bf16 v[62:65], v[146:149], v[182:185], v[62:65]
	v_mfma_f32_16x16x32_bf16 v[58:61], v[158:161], v[182:185], v[58:61]
	v_mfma_f32_16x16x32_bf16 v[46:49], v[146:149], v[190:193], v[46:49]
	v_mfma_f32_16x16x32_bf16 v[42:45], v[158:161], v[190:193], v[42:45]
	v_mfma_f32_16x16x32_bf16 v[30:33], v[146:149], v[198:201], v[30:33]
	v_mfma_f32_16x16x32_bf16 v[26:29], v[158:161], v[198:201], v[26:29]
	v_mfma_f32_16x16x32_bf16 v[14:17], v[146:149], v[212:215], v[14:17]
	v_mfma_f32_16x16x32_bf16 v[10:13], v[158:161], v[212:215], v[10:13]
	v_mfma_f32_16x16x32_bf16 v[54:57], v[162:165], v[178:181], v[54:57]
	v_mfma_f32_16x16x32_bf16 v[50:53], v[170:173], v[178:181], v[50:53]
	v_mfma_f32_16x16x32_bf16 v[38:41], v[162:165], v[186:189], v[38:41]
	v_mfma_f32_16x16x32_bf16 v[34:37], v[170:173], v[186:189], v[34:37]
	v_mfma_f32_16x16x32_bf16 v[22:25], v[162:165], v[194:197], v[22:25]
	v_mfma_f32_16x16x32_bf16 v[18:21], v[170:173], v[194:197], v[18:21]
	v_mfma_f32_16x16x32_bf16 v[6:9], v[162:165], v[208:211], v[6:9]
	v_mfma_f32_16x16x32_bf16 v[2:5], v[170:173], v[208:211], v[2:5]
	v_mfma_f32_16x16x32_bf16 v[54:57], v[166:169], v[182:185], v[54:57]
	v_mfma_f32_16x16x32_bf16 v[50:53], v[174:177], v[182:185], v[50:53]
	v_mfma_f32_16x16x32_bf16 v[38:41], v[166:169], v[190:193], v[38:41]
	v_mfma_f32_16x16x32_bf16 v[34:37], v[174:177], v[190:193], v[34:37]
	v_mfma_f32_16x16x32_bf16 v[22:25], v[166:169], v[198:201], v[22:25]
	v_mfma_f32_16x16x32_bf16 v[18:21], v[174:177], v[198:201], v[18:21]
	v_mfma_f32_16x16x32_bf16 v[6:9], v[166:169], v[212:215], v[6:9]
	v_mfma_f32_16x16x32_bf16 v[2:5], v[174:177], v[212:215], v[2:5]
	s_setprio 0
	s_barrier
	s_add_i32 s33, 0, 0x18000
	s_add_i32 s55, 0, 0x1c000
	v_add_u32_e32 v158, s33, v151
	v_add_u32_e32 v174, s55, v151
	ds_read_b128 v[142:145], v158
	ds_read_b128 v[146:149], v158 offset:1024
	ds_read_b128 v[154:157], v158 offset:2048
	ds_read_b128 v[158:161], v158 offset:3072
	ds_read_b128 v[162:165], v174
	ds_read_b128 v[166:169], v174 offset:1024
	ds_read_b128 v[170:173], v174 offset:2048
	ds_read_b128 v[174:177], v174 offset:3072
	s_add_u32 s0, s28, 0x80000
	s_addc_u32 s1, s29, 0
	s_mov_b32 m0, s36
	v_lshl_add_u64 v[222:223], s[0:1], 0, v[130:131]
	ds_read_b128 v[178:181], v153 offset:32768
	ds_read_b128 v[182:185], v153 offset:33792
	ds_read_b128 v[186:189], v153 offset:34816
	ds_read_b128 v[190:193], v153 offset:35840
	ds_read_b128 v[194:197], v153 offset:36864
	ds_read_b128 v[198:201], v153 offset:37888
	ds_read_b128 v[208:211], v153 offset:38912
	ds_read_b128 v[212:215], v153 offset:39936
	global_load_lds_dwordx4 v[222:223], off
	v_lshl_add_u64 v[222:223], s[0:1], 0, v[134:135]
	s_mov_b32 m0, s37
	s_nop 0
	global_load_lds_dwordx4 v[222:223], off
	s_waitcnt vmcnt(8)
	s_waitcnt lgkmcnt(0)
	s_barrier
	s_setprio 1
	s_waitcnt lgkmcnt(0)
	v_mfma_f32_16x16x32_bf16 v[126:129], v[142:145], v[178:181], v[126:129]
	v_mfma_f32_16x16x32_bf16 v[122:125], v[154:157], v[178:181], v[122:125]
	v_mfma_f32_16x16x32_bf16 v[110:113], v[142:145], v[186:189], v[110:113]
	v_mfma_f32_16x16x32_bf16 v[106:109], v[154:157], v[186:189], v[106:109]
	v_mfma_f32_16x16x32_bf16 v[94:97], v[142:145], v[194:197], v[94:97]
	v_mfma_f32_16x16x32_bf16 v[90:93], v[154:157], v[194:197], v[90:93]
	v_mfma_f32_16x16x32_bf16 v[78:81], v[142:145], v[208:211], v[78:81]
	v_mfma_f32_16x16x32_bf16 v[74:77], v[154:157], v[208:211], v[74:77]
	v_mfma_f32_16x16x32_bf16 v[126:129], v[146:149], v[182:185], v[126:129]
	v_mfma_f32_16x16x32_bf16 v[122:125], v[158:161], v[182:185], v[122:125]
	v_mfma_f32_16x16x32_bf16 v[110:113], v[146:149], v[190:193], v[110:113]
	v_mfma_f32_16x16x32_bf16 v[106:109], v[158:161], v[190:193], v[106:109]
	v_mfma_f32_16x16x32_bf16 v[94:97], v[146:149], v[198:201], v[94:97]
	v_mfma_f32_16x16x32_bf16 v[90:93], v[158:161], v[198:201], v[90:93]
	v_mfma_f32_16x16x32_bf16 v[78:81], v[146:149], v[212:215], v[78:81]
	v_mfma_f32_16x16x32_bf16 v[74:77], v[158:161], v[212:215], v[74:77]
	v_mfma_f32_16x16x32_bf16 v[118:121], v[162:165], v[178:181], v[118:121]
	v_mfma_f32_16x16x32_bf16 v[114:117], v[170:173], v[178:181], v[114:117]
	v_mfma_f32_16x16x32_bf16 v[102:105], v[162:165], v[186:189], v[102:105]
	v_mfma_f32_16x16x32_bf16 v[98:101], v[170:173], v[186:189], v[98:101]
	v_mfma_f32_16x16x32_bf16 v[86:89], v[162:165], v[194:197], v[86:89]
	v_mfma_f32_16x16x32_bf16 v[82:85], v[170:173], v[194:197], v[82:85]
	v_mfma_f32_16x16x32_bf16 v[70:73], v[162:165], v[208:211], v[70:73]
	v_mfma_f32_16x16x32_bf16 v[66:69], v[170:173], v[208:211], v[66:69]
	v_mfma_f32_16x16x32_bf16 v[118:121], v[166:169], v[182:185], v[118:121]
	v_mfma_f32_16x16x32_bf16 v[114:117], v[174:177], v[182:185], v[114:117]
	v_mfma_f32_16x16x32_bf16 v[102:105], v[166:169], v[190:193], v[102:105]
	v_mfma_f32_16x16x32_bf16 v[98:101], v[174:177], v[190:193], v[98:101]
	v_mfma_f32_16x16x32_bf16 v[86:89], v[166:169], v[198:201], v[86:89]
	v_mfma_f32_16x16x32_bf16 v[82:85], v[174:177], v[198:201], v[82:85]
	v_mfma_f32_16x16x32_bf16 v[70:73], v[166:169], v[212:215], v[70:73]
	v_mfma_f32_16x16x32_bf16 v[66:69], v[174:177], v[212:215], v[66:69]
	s_setprio 0
	s_barrier
	s_add_i32 s0, s33, s34
	v_lshl_add_u64 v[204:205], v[204:205], 0, s[80:81]
	s_mov_b32 m0, s0
	ds_read_b128 v[178:181], v153 offset:49152
	ds_read_b128 v[182:185], v153 offset:50176
	ds_read_b128 v[186:189], v153 offset:51200
	ds_read_b128 v[190:193], v153 offset:52224
	ds_read_b128 v[194:197], v153 offset:53248
	ds_read_b128 v[198:201], v153 offset:54272
	ds_read_b128 v[208:211], v153 offset:55296
	ds_read_b128 v[212:215], v153 offset:56320
	global_load_lds_dwordx4 v[204:205], off
	s_add_i32 m0, s0, 0x2000
	s_add_u32 s0, s26, 0x80080
	v_lshl_add_u64 v[204:205], v[216:217], 0, s[80:81]
	s_addc_u32 s1, s27, 0
	s_add_i32 s26, s55, s34
	global_load_lds_dwordx4 v[204:205], off
	v_lshl_add_u64 v[204:205], s[0:1], 0, v[132:133]
	s_mov_b32 m0, s26
	s_nop 0
	global_load_lds_dwordx4 v[204:205], off
	v_lshl_add_u64 v[204:205], s[0:1], 0, v[136:137]
	s_add_i32 m0, s26, 0x2000
	s_nop 0
	global_load_lds_dwordx4 v[204:205], off
	v_lshl_add_u64 v[204:205], v[218:219], 0, s[80:81]
	s_mov_b32 m0, s39
	s_nop 0
	global_load_lds_dwordx4 v[204:205], off
	v_lshl_add_u64 v[204:205], v[220:221], 0, s[80:81]
	s_mov_b32 m0, s40
	s_nop 0
	global_load_lds_dwordx4 v[204:205], off
	s_waitcnt vmcnt(8)
	s_waitcnt lgkmcnt(0)
	s_barrier
	s_setprio 1
	s_waitcnt lgkmcnt(0)
	v_mfma_f32_16x16x32_bf16 v[62:65], v[142:145], v[178:181], v[62:65]
	v_mfma_f32_16x16x32_bf16 v[58:61], v[154:157], v[178:181], v[58:61]
	v_mfma_f32_16x16x32_bf16 v[46:49], v[142:145], v[186:189], v[46:49]
	v_mfma_f32_16x16x32_bf16 v[42:45], v[154:157], v[186:189], v[42:45]
	v_mfma_f32_16x16x32_bf16 v[30:33], v[142:145], v[194:197], v[30:33]
	v_mfma_f32_16x16x32_bf16 v[26:29], v[154:157], v[194:197], v[26:29]
	v_mfma_f32_16x16x32_bf16 v[14:17], v[142:145], v[208:211], v[14:17]
	v_mfma_f32_16x16x32_bf16 v[10:13], v[154:157], v[208:211], v[10:13]
	v_mfma_f32_16x16x32_bf16 v[62:65], v[146:149], v[182:185], v[62:65]
	v_mfma_f32_16x16x32_bf16 v[58:61], v[158:161], v[182:185], v[58:61]
	v_mfma_f32_16x16x32_bf16 v[46:49], v[146:149], v[190:193], v[46:49]
	v_mfma_f32_16x16x32_bf16 v[42:45], v[158:161], v[190:193], v[42:45]
	v_mfma_f32_16x16x32_bf16 v[30:33], v[146:149], v[198:201], v[30:33]
	v_mfma_f32_16x16x32_bf16 v[26:29], v[158:161], v[198:201], v[26:29]
	v_mfma_f32_16x16x32_bf16 v[14:17], v[146:149], v[212:215], v[14:17]
	v_mfma_f32_16x16x32_bf16 v[10:13], v[158:161], v[212:215], v[10:13]
	v_mfma_f32_16x16x32_bf16 v[54:57], v[162:165], v[178:181], v[54:57]
	v_mfma_f32_16x16x32_bf16 v[50:53], v[170:173], v[178:181], v[50:53]
	v_mfma_f32_16x16x32_bf16 v[38:41], v[162:165], v[186:189], v[38:41]
	v_mfma_f32_16x16x32_bf16 v[34:37], v[170:173], v[186:189], v[34:37]
	v_mfma_f32_16x16x32_bf16 v[22:25], v[162:165], v[194:197], v[22:25]
	v_mfma_f32_16x16x32_bf16 v[18:21], v[170:173], v[194:197], v[18:21]
	v_mfma_f32_16x16x32_bf16 v[6:9], v[162:165], v[208:211], v[6:9]
	v_mfma_f32_16x16x32_bf16 v[2:5], v[170:173], v[208:211], v[2:5]
	v_mfma_f32_16x16x32_bf16 v[54:57], v[166:169], v[182:185], v[54:57]
	v_mfma_f32_16x16x32_bf16 v[50:53], v[174:177], v[182:185], v[50:53]
	v_mfma_f32_16x16x32_bf16 v[38:41], v[166:169], v[190:193], v[38:41]
	v_mfma_f32_16x16x32_bf16 v[34:37], v[174:177], v[190:193], v[34:37]
	v_mfma_f32_16x16x32_bf16 v[22:25], v[166:169], v[198:201], v[22:25]
	v_mfma_f32_16x16x32_bf16 v[18:21], v[174:177], v[198:201], v[18:21]
	v_mfma_f32_16x16x32_bf16 v[6:9], v[166:169], v[212:215], v[6:9]
	v_mfma_f32_16x16x32_bf16 v[2:5], v[174:177], v[212:215], v[2:5]
	s_setprio 0
	s_barrier
	s_add_i32 s60, s60, 2
	s_add_u32 s24, s24, 0x100
	s_addc_u32 s25, s25, 0
	s_add_u32 s58, s58, 0x100
	s_addc_u32 s59, s59, 0
	s_cmp_gt_u32 s60, 29
	s_cbranch_scc0 .LBB0_394
	s_and_b64 vcc, exec, s[14:15]
	s_cbranch_vccz .LBB0_397
	s_barrier

.LBB0_692:
	s_add_u32 s0, s18, 0xfff00080
	s_addc_u32 s1, s19, -1
	s_add_i32 s33, 0, 0x10000
	s_cmp_eq_u32 s61, 60
	s_cselect_b32 s23, s11, s1
	s_cselect_b32 s22, s49, s0
	s_cselect_b32 s21, s9, s60
	s_cselect_b32 s20, s58, s59
	s_add_i32 s55, 0, 0x14000
	v_add_u32_e32 v98, s33, v205
	v_add_u32_e32 v134, s55, v205
	ds_read_b128 v[78:81], v98
	ds_read_b128 v[86:89], v98 offset:1024
	ds_read_b128 v[94:97], v98 offset:2048
	ds_read_b128 v[98:101], v98 offset:3072
	ds_read_b128 v[106:109], v134
	ds_read_b128 v[110:113], v134 offset:1024
	ds_read_b128 v[126:129], v134 offset:2048
	ds_read_b128 v[134:137], v134 offset:3072
	v_lshl_add_u64 v[194:195], s[18:19], 0, v[214:215]
	s_add_i32 m0, s27, 0xc000
	ds_read_b128 v[146:149], v239
	ds_read_b128 v[158:161], v239 offset:1024
	ds_read_b128 v[166:169], v239 offset:2048
	ds_read_b128 v[174:177], v239 offset:3072
	ds_read_b128 v[178:181], v239 offset:4096
	ds_read_b128 v[182:185], v239 offset:5120
	ds_read_b128 v[186:189], v239 offset:6144
	ds_read_b128 v[190:193], v239 offset:7168
	global_load_lds_dwordx4 v[194:195], off
	v_lshl_add_u64 v[194:195], s[18:19], 0, v[216:217]
	s_add_i32 m0, s27, 0xe000
	s_nop 0
	global_load_lds_dwordx4 v[194:195], off
	s_waitcnt vmcnt(8)
	s_waitcnt lgkmcnt(0)
	s_barrier
	s_setprio 1
	s_waitcnt lgkmcnt(0)
	v_mfma_f32_16x16x32_bf16 v[170:173], v[78:81], v[146:149], v[170:173]
	v_mfma_f32_16x16x32_bf16 v[162:165], v[94:97], v[146:149], v[162:165]
	v_mfma_f32_16x16x32_bf16 v[142:145], v[78:81], v[166:169], v[142:145]
	v_mfma_f32_16x16x32_bf16 v[138:141], v[94:97], v[166:169], v[138:141]
	v_mfma_f32_16x16x32_bf16 v[118:121], v[78:81], v[178:181], v[118:121]
	v_mfma_f32_16x16x32_bf16 v[114:117], v[94:97], v[178:181], v[114:117]
	v_mfma_f32_16x16x32_bf16 v[82:85], v[78:81], v[186:189], v[82:85]
	v_mfma_f32_16x16x32_bf16 v[74:77], v[94:97], v[186:189], v[74:77]
	v_mfma_f32_16x16x32_bf16 v[170:173], v[86:89], v[158:161], v[170:173]
	v_mfma_f32_16x16x32_bf16 v[162:165], v[98:101], v[158:161], v[162:165]
	v_mfma_f32_16x16x32_bf16 v[142:145], v[86:89], v[174:177], v[142:145]
	v_mfma_f32_16x16x32_bf16 v[138:141], v[98:101], v[174:177], v[138:141]
	v_mfma_f32_16x16x32_bf16 v[118:121], v[86:89], v[182:185], v[118:121]
	v_mfma_f32_16x16x32_bf16 v[114:117], v[98:101], v[182:185], v[114:117]
	v_mfma_f32_16x16x32_bf16 v[82:85], v[86:89], v[190:193], v[82:85]
	v_mfma_f32_16x16x32_bf16 v[74:77], v[98:101], v[190:193], v[74:77]
	v_mfma_f32_16x16x32_bf16 v[154:157], v[106:109], v[146:149], v[154:157]
	v_mfma_f32_16x16x32_bf16 v[130:133], v[106:109], v[166:169], v[130:133]
	v_mfma_f32_16x16x32_bf16 v[122:125], v[126:129], v[166:169], v[122:125]
	v_mfma_f32_16x16x32_bf16 v[102:105], v[106:109], v[178:181], v[102:105]
	v_mfma_f32_16x16x32_bf16 v[90:93], v[126:129], v[178:181], v[90:93]
	v_mfma_f32_16x16x32_bf16 v[70:73], v[106:109], v[186:189], v[70:73]
	v_mfma_f32_16x16x32_bf16 v[66:69], v[126:129], v[186:189], v[66:69]
	v_mfma_f32_16x16x32_bf16 v[154:157], v[110:113], v[158:161], v[154:157]
	v_mfma_f32_16x16x32_bf16 v[146:149], v[126:129], v[146:149], v[150:153]
	v_mfma_f32_16x16x32_bf16 v[130:133], v[110:113], v[174:177], v[130:133]
	v_mfma_f32_16x16x32_bf16 v[122:125], v[134:137], v[174:177], v[122:125]
	v_mfma_f32_16x16x32_bf16 v[102:105], v[110:113], v[182:185], v[102:105]
	v_mfma_f32_16x16x32_bf16 v[90:93], v[134:137], v[182:185], v[90:93]
	v_mfma_f32_16x16x32_bf16 v[70:73], v[110:113], v[190:193], v[70:73]
	v_mfma_f32_16x16x32_bf16 v[66:69], v[134:137], v[190:193], v[66:69]
	v_mfma_f32_16x16x32_bf16 v[146:149], v[134:137], v[158:161], v[146:149]
	s_setprio 0
	s_barrier
	s_add_i32 s0, s33, s26
	v_lshl_add_u64 v[194:195], s[20:21], 0, v[202:203]
	s_mov_b32 m0, s0
	ds_read_b128 v[150:153], v239 offset:16384
	ds_read_b128 v[158:161], v239 offset:17408
	ds_read_b128 v[166:169], v239 offset:18432
	ds_read_b128 v[174:177], v239 offset:19456
	ds_read_b128 v[178:181], v239 offset:20480
	ds_read_b128 v[182:185], v239 offset:21504
	ds_read_b128 v[186:189], v239 offset:22528
	ds_read_b128 v[190:193], v239 offset:23552
	global_load_lds_dwordx4 v[194:195], off
	s_add_i32 m0, s0, 0x2000
	s_add_u32 s0, s20, 0x100000
	v_lshl_add_u64 v[196:197], s[20:21], 0, v[208:209]
	s_addc_u32 s1, s21, 0
	s_add_i32 s33, s55, s26
	global_load_lds_dwordx4 v[196:197], off
	v_lshl_add_u64 v[198:199], s[0:1], 0, v[202:203]
	s_mov_b32 m0, s33
	v_lshl_add_u64 v[200:201], s[22:23], 0, v[210:211]
	global_load_lds_dwordx4 v[198:199], off
	v_lshl_add_u64 v[198:199], s[0:1], 0, v[208:209]
	s_add_i32 m0, s33, 0x2000
	s_nop 0
	global_load_lds_dwordx4 v[198:199], off
	v_lshl_add_u64 v[198:199], s[22:23], 0, v[212:213]
	s_mov_b32 m0, s27
	s_nop 0
	global_load_lds_dwordx4 v[198:199], off
	s_mov_b32 m0, s28
	s_nop 0
	global_load_lds_dwordx4 v[200:201], off
	s_waitcnt vmcnt(8)
	s_waitcnt lgkmcnt(0)
	s_barrier
	s_setprio 1
	s_waitcnt lgkmcnt(0)
	v_mfma_f32_16x16x32_bf16 v[62:65], v[78:81], v[150:153], v[62:65]
	v_mfma_f32_16x16x32_bf16 v[58:61], v[94:97], v[150:153], v[58:61]
	v_mfma_f32_16x16x32_bf16 v[46:49], v[78:81], v[166:169], v[46:49]
	v_mfma_f32_16x16x32_bf16 v[42:45], v[94:97], v[166:169], v[42:45]
	v_mfma_f32_16x16x32_bf16 v[30:33], v[78:81], v[178:181], v[30:33]
	v_mfma_f32_16x16x32_bf16 v[26:29], v[94:97], v[178:181], v[26:29]
	v_mfma_f32_16x16x32_bf16 v[14:17], v[78:81], v[186:189], v[14:17]
	v_mfma_f32_16x16x32_bf16 v[10:13], v[94:97], v[186:189], v[10:13]
	v_mfma_f32_16x16x32_bf16 v[62:65], v[86:89], v[158:161], v[62:65]
	v_mfma_f32_16x16x32_bf16 v[58:61], v[98:101], v[158:161], v[58:61]
	v_mfma_f32_16x16x32_bf16 v[46:49], v[86:89], v[174:177], v[46:49]
	v_mfma_f32_16x16x32_bf16 v[42:45], v[98:101], v[174:177], v[42:45]
	v_mfma_f32_16x16x32_bf16 v[30:33], v[86:89], v[182:185], v[30:33]
	v_mfma_f32_16x16x32_bf16 v[26:29], v[98:101], v[182:185], v[26:29]
	v_mfma_f32_16x16x32_bf16 v[14:17], v[86:89], v[190:193], v[14:17]
	v_mfma_f32_16x16x32_bf16 v[10:13], v[98:101], v[190:193], v[10:13]
	v_mfma_f32_16x16x32_bf16 v[54:57], v[106:109], v[150:153], v[54:57]
	v_mfma_f32_16x16x32_bf16 v[50:53], v[126:129], v[150:153], v[50:53]
	v_mfma_f32_16x16x32_bf16 v[38:41], v[106:109], v[166:169], v[38:41]
	v_mfma_f32_16x16x32_bf16 v[34:37], v[126:129], v[166:169], v[34:37]
	v_mfma_f32_16x16x32_bf16 v[22:25], v[106:109], v[178:181], v[22:25]
	v_mfma_f32_16x16x32_bf16 v[18:21], v[126:129], v[178:181], v[18:21]
	v_mfma_f32_16x16x32_bf16 v[6:9], v[106:109], v[186:189], v[6:9]
	v_mfma_f32_16x16x32_bf16 v[2:5], v[126:129], v[186:189], v[2:5]
	v_mfma_f32_16x16x32_bf16 v[54:57], v[110:113], v[158:161], v[54:57]
	v_mfma_f32_16x16x32_bf16 v[50:53], v[134:137], v[158:161], v[50:53]
	v_mfma_f32_16x16x32_bf16 v[38:41], v[110:113], v[174:177], v[38:41]
	v_mfma_f32_16x16x32_bf16 v[34:37], v[134:137], v[174:177], v[34:37]
	v_mfma_f32_16x16x32_bf16 v[22:25], v[110:113], v[182:185], v[22:25]
	v_mfma_f32_16x16x32_bf16 v[18:21], v[134:137], v[182:185], v[18:21]
	v_mfma_f32_16x16x32_bf16 v[6:9], v[110:113], v[190:193], v[6:9]
	v_mfma_f32_16x16x32_bf16 v[2:5], v[134:137], v[190:193], v[2:5]
	s_setprio 0
	s_barrier
	s_add_i32 s33, 0, 0x18000
	s_add_i32 s55, 0, 0x1c000
	v_add_u32_e32 v98, s33, v205
	v_add_u32_e32 v134, s55, v205
	ds_read_b128 v[78:81], v98
	ds_read_b128 v[86:89], v98 offset:1024
	ds_read_b128 v[94:97], v98 offset:2048
	ds_read_b128 v[98:101], v98 offset:3072
	ds_read_b128 v[106:109], v134
	ds_read_b128 v[110:113], v134 offset:1024
	ds_read_b128 v[126:129], v134 offset:2048
	ds_read_b128 v[134:137], v134 offset:3072
	s_add_u32 s0, s22, 0x100000
	s_addc_u32 s1, s23, 0
	s_mov_b32 m0, s29
	v_lshl_add_u64 v[206:207], s[0:1], 0, v[212:213]
	ds_read_b128 v[150:153], v239 offset:32768
	ds_read_b128 v[158:161], v239 offset:33792
	ds_read_b128 v[166:169], v239 offset:34816
	ds_read_b128 v[174:177], v239 offset:35840
	ds_read_b128 v[178:181], v239 offset:36864
	ds_read_b128 v[182:185], v239 offset:37888
	ds_read_b128 v[186:189], v239 offset:38912
	ds_read_b128 v[190:193], v239 offset:39936
	global_load_lds_dwordx4 v[206:207], off
	v_lshl_add_u64 v[206:207], s[0:1], 0, v[210:211]
	s_mov_b32 m0, s30
	s_nop 0
	global_load_lds_dwordx4 v[206:207], off
	s_waitcnt vmcnt(8)
	s_waitcnt lgkmcnt(0)
	s_barrier
	s_setprio 1
	s_waitcnt lgkmcnt(0)
	v_mfma_f32_16x16x32_bf16 v[170:173], v[78:81], v[150:153], v[170:173]
	v_mfma_f32_16x16x32_bf16 v[162:165], v[94:97], v[150:153], v[162:165]
	v_mfma_f32_16x16x32_bf16 v[142:145], v[78:81], v[166:169], v[142:145]
	v_mfma_f32_16x16x32_bf16 v[138:141], v[94:97], v[166:169], v[138:141]
	v_mfma_f32_16x16x32_bf16 v[118:121], v[78:81], v[178:181], v[118:121]
	v_mfma_f32_16x16x32_bf16 v[114:117], v[94:97], v[178:181], v[114:117]
	v_mfma_f32_16x16x32_bf16 v[82:85], v[78:81], v[186:189], v[82:85]
	v_mfma_f32_16x16x32_bf16 v[74:77], v[94:97], v[186:189], v[74:77]
	v_mfma_f32_16x16x32_bf16 v[170:173], v[86:89], v[158:161], v[170:173]
	v_mfma_f32_16x16x32_bf16 v[162:165], v[98:101], v[158:161], v[162:165]
	v_mfma_f32_16x16x32_bf16 v[142:145], v[86:89], v[174:177], v[142:145]
	v_mfma_f32_16x16x32_bf16 v[138:141], v[98:101], v[174:177], v[138:141]
	v_mfma_f32_16x16x32_bf16 v[118:121], v[86:89], v[182:185], v[118:121]
	v_mfma_f32_16x16x32_bf16 v[114:117], v[98:101], v[182:185], v[114:117]
	v_mfma_f32_16x16x32_bf16 v[82:85], v[86:89], v[190:193], v[82:85]
	v_mfma_f32_16x16x32_bf16 v[74:77], v[98:101], v[190:193], v[74:77]
	v_mfma_f32_16x16x32_bf16 v[154:157], v[106:109], v[150:153], v[154:157]
	v_mfma_f32_16x16x32_bf16 v[146:149], v[126:129], v[150:153], v[146:149]
	v_mfma_f32_16x16x32_bf16 v[130:133], v[106:109], v[166:169], v[130:133]
	v_mfma_f32_16x16x32_bf16 v[122:125], v[126:129], v[166:169], v[122:125]
	v_mfma_f32_16x16x32_bf16 v[102:105], v[106:109], v[178:181], v[102:105]
	v_mfma_f32_16x16x32_bf16 v[90:93], v[126:129], v[178:181], v[90:93]
	v_mfma_f32_16x16x32_bf16 v[70:73], v[106:109], v[186:189], v[70:73]
	v_mfma_f32_16x16x32_bf16 v[66:69], v[126:129], v[186:189], v[66:69]
	v_mfma_f32_16x16x32_bf16 v[154:157], v[110:113], v[158:161], v[154:157]
	v_mfma_f32_16x16x32_bf16 v[150:153], v[134:137], v[158:161], v[146:149]
	v_mfma_f32_16x16x32_bf16 v[130:133], v[110:113], v[174:177], v[130:133]
	v_mfma_f32_16x16x32_bf16 v[122:125], v[134:137], v[174:177], v[122:125]
	v_mfma_f32_16x16x32_bf16 v[102:105], v[110:113], v[182:185], v[102:105]
	v_mfma_f32_16x16x32_bf16 v[90:93], v[134:137], v[182:185], v[90:93]
	v_mfma_f32_16x16x32_bf16 v[70:73], v[110:113], v[190:193], v[70:73]
	v_mfma_f32_16x16x32_bf16 v[66:69], v[134:137], v[190:193], v[66:69]
	s_setprio 0
	s_barrier
	s_add_i32 s0, s33, s26
	v_lshl_add_u64 v[194:195], v[194:195], 0, s[80:81]
	s_mov_b32 m0, s0
	ds_read_b128 v[146:149], v239 offset:49152
	ds_read_b128 v[158:161], v239 offset:50176
	ds_read_b128 v[166:169], v239 offset:51200
	ds_read_b128 v[174:177], v239 offset:52224
	ds_read_b128 v[178:181], v239 offset:53248
	ds_read_b128 v[182:185], v239 offset:54272
	ds_read_b128 v[186:189], v239 offset:55296
	ds_read_b128 v[190:193], v239 offset:56320
	global_load_lds_dwordx4 v[194:195], off
	s_add_i32 m0, s0, 0x2000
	s_add_u32 s0, s20, 0x100080
	v_lshl_add_u64 v[194:195], v[196:197], 0, s[80:81]
	s_addc_u32 s1, s21, 0
	s_add_i32 s20, s55, s26
	global_load_lds_dwordx4 v[194:195], off
	v_lshl_add_u64 v[194:195], s[0:1], 0, v[202:203]
	s_mov_b32 m0, s20
	s_nop 0
	global_load_lds_dwordx4 v[194:195], off
	v_lshl_add_u64 v[194:195], s[0:1], 0, v[208:209]
	s_add_i32 m0, s20, 0x2000
	s_nop 0
	global_load_lds_dwordx4 v[194:195], off
	v_lshl_add_u64 v[194:195], v[198:199], 0, s[80:81]
	s_mov_b32 m0, s35
	s_nop 0
	global_load_lds_dwordx4 v[194:195], off
	v_lshl_add_u64 v[194:195], v[200:201], 0, s[80:81]
	s_mov_b32 m0, s36
	s_nop 0
	global_load_lds_dwordx4 v[194:195], off
	s_waitcnt vmcnt(8)
	s_waitcnt lgkmcnt(0)
	s_barrier
	s_setprio 1
	s_waitcnt lgkmcnt(0)
	v_mfma_f32_16x16x32_bf16 v[62:65], v[78:81], v[146:149], v[62:65]
	v_mfma_f32_16x16x32_bf16 v[58:61], v[94:97], v[146:149], v[58:61]
	v_mfma_f32_16x16x32_bf16 v[46:49], v[78:81], v[166:169], v[46:49]
	v_mfma_f32_16x16x32_bf16 v[42:45], v[94:97], v[166:169], v[42:45]
	v_mfma_f32_16x16x32_bf16 v[30:33], v[78:81], v[178:181], v[30:33]
	v_mfma_f32_16x16x32_bf16 v[26:29], v[94:97], v[178:181], v[26:29]
	v_mfma_f32_16x16x32_bf16 v[14:17], v[78:81], v[186:189], v[14:17]
	v_mfma_f32_16x16x32_bf16 v[10:13], v[94:97], v[186:189], v[10:13]
	v_mfma_f32_16x16x32_bf16 v[62:65], v[86:89], v[158:161], v[62:65]
	v_mfma_f32_16x16x32_bf16 v[58:61], v[98:101], v[158:161], v[58:61]
	v_mfma_f32_16x16x32_bf16 v[46:49], v[86:89], v[174:177], v[46:49]
	v_mfma_f32_16x16x32_bf16 v[42:45], v[98:101], v[174:177], v[42:45]
	v_mfma_f32_16x16x32_bf16 v[30:33], v[86:89], v[182:185], v[30:33]
	v_mfma_f32_16x16x32_bf16 v[26:29], v[98:101], v[182:185], v[26:29]
	v_mfma_f32_16x16x32_bf16 v[14:17], v[86:89], v[190:193], v[14:17]
	v_mfma_f32_16x16x32_bf16 v[10:13], v[98:101], v[190:193], v[10:13]
	v_mfma_f32_16x16x32_bf16 v[54:57], v[106:109], v[146:149], v[54:57]
	v_mfma_f32_16x16x32_bf16 v[50:53], v[126:129], v[146:149], v[50:53]
	v_mfma_f32_16x16x32_bf16 v[38:41], v[106:109], v[166:169], v[38:41]
	v_mfma_f32_16x16x32_bf16 v[34:37], v[126:129], v[166:169], v[34:37]
	v_mfma_f32_16x16x32_bf16 v[22:25], v[106:109], v[178:181], v[22:25]
	v_mfma_f32_16x16x32_bf16 v[18:21], v[126:129], v[178:181], v[18:21]
	v_mfma_f32_16x16x32_bf16 v[6:9], v[106:109], v[186:189], v[6:9]
	v_mfma_f32_16x16x32_bf16 v[2:5], v[126:129], v[186:189], v[2:5]
	v_mfma_f32_16x16x32_bf16 v[54:57], v[110:113], v[158:161], v[54:57]
	v_mfma_f32_16x16x32_bf16 v[50:53], v[134:137], v[158:161], v[50:53]
	v_mfma_f32_16x16x32_bf16 v[38:41], v[110:113], v[174:177], v[38:41]
	v_mfma_f32_16x16x32_bf16 v[34:37], v[134:137], v[174:177], v[34:37]
	v_mfma_f32_16x16x32_bf16 v[22:25], v[110:113], v[182:185], v[22:25]
	v_mfma_f32_16x16x32_bf16 v[18:21], v[134:137], v[182:185], v[18:21]
	v_mfma_f32_16x16x32_bf16 v[6:9], v[110:113], v[190:193], v[6:9]
	v_mfma_f32_16x16x32_bf16 v[2:5], v[134:137], v[190:193], v[2:5]
	s_setprio 0
	s_barrier
	s_add_i32 s61, s61, 2
	s_add_u32 s18, s18, 0x100
	s_addc_u32 s19, s19, 0
	s_add_u32 s59, s59, 0x100
	s_addc_u32 s60, s60, 0
	s_cmp_gt_u32 s61, 61
	s_cbranch_scc0 .LBB0_692
	s_and_b64 vcc, exec, s[6:7]
	s_cbranch_vccz .LBB0_695
	s_barrier

.LBB0_712:
	s_add_u32 s0, s18, 0xfff00080
	s_addc_u32 s1, s19, -1
	s_add_i32 s33, 0, 0x10000
	s_cmp_eq_u32 s49, 4
	s_cselect_b32 s23, s15, s1
	s_cselect_b32 s22, s14, s0
	s_cselect_b32 s21, s17, s11
	s_cselect_b32 s20, s16, s9
	s_add_i32 s55, 0, 0x14000
	v_add_u32_e32 v152, s33, v136
	v_add_u32_e32 v168, s55, v136
	ds_read_b128 v[140:143], v152
	ds_read_b128 v[144:147], v152 offset:1024
	ds_read_b128 v[148:151], v152 offset:2048
	ds_read_b128 v[152:155], v152 offset:3072
	ds_read_b128 v[156:159], v168
	ds_read_b128 v[160:163], v168 offset:1024
	ds_read_b128 v[164:167], v168 offset:2048
	ds_read_b128 v[168:171], v168 offset:3072
	v_lshl_add_u64 v[200:201], s[18:19], 0, v[132:133]
	s_add_i32 m0, s27, 0xc000
	ds_read_b128 v[172:175], v139
	ds_read_b128 v[176:179], v139 offset:1024
	ds_read_b128 v[180:183], v139 offset:2048
	ds_read_b128 v[184:187], v139 offset:3072
	ds_read_b128 v[188:191], v139 offset:4096
	ds_read_b128 v[192:195], v139 offset:5120
	ds_read_b128 v[196:199], v139 offset:6144
	ds_read_b128 v[208:211], v139 offset:7168
	global_load_lds_dwordx4 v[200:201], off
	v_lshl_add_u64 v[200:201], s[18:19], 0, v[134:135]
	s_add_i32 m0, s27, 0xe000
	s_nop 0
	global_load_lds_dwordx4 v[200:201], off
	s_waitcnt vmcnt(8)
	s_waitcnt lgkmcnt(0)
	s_barrier
	s_setprio 1
	s_waitcnt lgkmcnt(0)
	v_mfma_f32_16x16x32_bf16 v[126:129], v[140:143], v[172:175], v[126:129]
	v_mfma_f32_16x16x32_bf16 v[122:125], v[148:151], v[172:175], v[122:125]
	v_mfma_f32_16x16x32_bf16 v[118:121], v[140:143], v[180:183], v[118:121]
	v_mfma_f32_16x16x32_bf16 v[114:117], v[148:151], v[180:183], v[114:117]
	v_mfma_f32_16x16x32_bf16 v[106:109], v[140:143], v[188:191], v[106:109]
	v_mfma_f32_16x16x32_bf16 v[98:101], v[148:151], v[188:191], v[98:101]
	v_mfma_f32_16x16x32_bf16 v[90:93], v[140:143], v[196:199], v[90:93]
	v_mfma_f32_16x16x32_bf16 v[82:85], v[148:151], v[196:199], v[82:85]
	v_mfma_f32_16x16x32_bf16 v[126:129], v[144:147], v[176:179], v[126:129]
	v_mfma_f32_16x16x32_bf16 v[122:125], v[152:155], v[176:179], v[122:125]
	v_mfma_f32_16x16x32_bf16 v[118:121], v[144:147], v[184:187], v[118:121]
	v_mfma_f32_16x16x32_bf16 v[114:117], v[152:155], v[184:187], v[114:117]
	v_mfma_f32_16x16x32_bf16 v[106:109], v[144:147], v[192:195], v[106:109]
	v_mfma_f32_16x16x32_bf16 v[98:101], v[152:155], v[192:195], v[98:101]
	v_mfma_f32_16x16x32_bf16 v[90:93], v[144:147], v[208:211], v[90:93]
	v_mfma_f32_16x16x32_bf16 v[82:85], v[152:155], v[208:211], v[82:85]
	v_mfma_f32_16x16x32_bf16 v[110:113], v[156:159], v[172:175], v[110:113]
	v_mfma_f32_16x16x32_bf16 v[102:105], v[164:167], v[172:175], v[102:105]
	v_mfma_f32_16x16x32_bf16 v[94:97], v[156:159], v[180:183], v[94:97]
	v_mfma_f32_16x16x32_bf16 v[86:89], v[164:167], v[180:183], v[86:89]
	v_mfma_f32_16x16x32_bf16 v[78:81], v[156:159], v[188:191], v[78:81]
	v_mfma_f32_16x16x32_bf16 v[74:77], v[164:167], v[188:191], v[74:77]
	v_mfma_f32_16x16x32_bf16 v[70:73], v[156:159], v[196:199], v[70:73]
	v_mfma_f32_16x16x32_bf16 v[66:69], v[164:167], v[196:199], v[66:69]
	v_mfma_f32_16x16x32_bf16 v[110:113], v[160:163], v[176:179], v[110:113]
	v_mfma_f32_16x16x32_bf16 v[102:105], v[168:171], v[176:179], v[102:105]
	v_mfma_f32_16x16x32_bf16 v[94:97], v[160:163], v[184:187], v[94:97]
	v_mfma_f32_16x16x32_bf16 v[86:89], v[168:171], v[184:187], v[86:89]
	v_mfma_f32_16x16x32_bf16 v[78:81], v[160:163], v[192:195], v[78:81]
	v_mfma_f32_16x16x32_bf16 v[74:77], v[168:171], v[192:195], v[74:77]
	v_mfma_f32_16x16x32_bf16 v[70:73], v[160:163], v[208:211], v[70:73]
	v_mfma_f32_16x16x32_bf16 v[66:69], v[168:171], v[208:211], v[66:69]
	s_setprio 0
	s_barrier
	s_add_i32 s0, s33, s26
	v_lshl_add_u64 v[200:201], s[20:21], 0, v[202:203]
	s_mov_b32 m0, s0
	ds_read_b128 v[172:175], v139 offset:16384
	ds_read_b128 v[176:179], v139 offset:17408
	ds_read_b128 v[180:183], v139 offset:18432
	ds_read_b128 v[184:187], v139 offset:19456
	ds_read_b128 v[188:191], v139 offset:20480
	ds_read_b128 v[192:195], v139 offset:21504
	ds_read_b128 v[196:199], v139 offset:22528
	ds_read_b128 v[208:211], v139 offset:23552
	global_load_lds_dwordx4 v[200:201], off
	s_add_i32 m0, s0, 0x2000
	s_add_u32 s0, s20, 0x100000
	v_lshl_add_u64 v[204:205], s[20:21], 0, v[130:131]
	s_addc_u32 s1, s21, 0
	s_add_i32 s33, s55, s26
	global_load_lds_dwordx4 v[204:205], off
	v_lshl_add_u64 v[206:207], s[0:1], 0, v[202:203]
	s_mov_b32 m0, s33
	v_lshl_add_u64 v[212:213], s[22:23], 0, v[130:131]
	global_load_lds_dwordx4 v[206:207], off
	v_lshl_add_u64 v[206:207], s[0:1], 0, v[130:131]
	s_add_i32 m0, s33, 0x2000
	s_nop 0
	global_load_lds_dwordx4 v[206:207], off
	v_lshl_add_u64 v[206:207], s[22:23], 0, v[202:203]
	s_mov_b32 m0, s27
	s_nop 0
	global_load_lds_dwordx4 v[206:207], off
	s_mov_b32 m0, s28
	s_nop 0
	global_load_lds_dwordx4 v[212:213], off
	s_waitcnt vmcnt(8)
	s_waitcnt lgkmcnt(0)
	s_barrier
	s_setprio 1
	s_waitcnt lgkmcnt(0)
	v_mfma_f32_16x16x32_bf16 v[62:65], v[140:143], v[172:175], v[62:65]
	v_mfma_f32_16x16x32_bf16 v[58:61], v[148:151], v[172:175], v[58:61]
	v_mfma_f32_16x16x32_bf16 v[54:57], v[140:143], v[180:183], v[54:57]
	v_mfma_f32_16x16x32_bf16 v[50:53], v[148:151], v[180:183], v[50:53]
	v_mfma_f32_16x16x32_bf16 v[38:41], v[140:143], v[188:191], v[38:41]
	v_mfma_f32_16x16x32_bf16 v[34:37], v[148:151], v[188:191], v[34:37]
	v_mfma_f32_16x16x32_bf16 v[22:25], v[140:143], v[196:199], v[22:25]
	v_mfma_f32_16x16x32_bf16 v[18:21], v[148:151], v[196:199], v[18:21]
	v_mfma_f32_16x16x32_bf16 v[62:65], v[144:147], v[176:179], v[62:65]
	v_mfma_f32_16x16x32_bf16 v[58:61], v[152:155], v[176:179], v[58:61]
	v_mfma_f32_16x16x32_bf16 v[54:57], v[144:147], v[184:187], v[54:57]
	v_mfma_f32_16x16x32_bf16 v[50:53], v[152:155], v[184:187], v[50:53]
	v_mfma_f32_16x16x32_bf16 v[38:41], v[144:147], v[192:195], v[38:41]
	v_mfma_f32_16x16x32_bf16 v[34:37], v[152:155], v[192:195], v[34:37]
	v_mfma_f32_16x16x32_bf16 v[22:25], v[144:147], v[208:211], v[22:25]
	v_mfma_f32_16x16x32_bf16 v[18:21], v[152:155], v[208:211], v[18:21]
	v_mfma_f32_16x16x32_bf16 v[46:49], v[156:159], v[172:175], v[46:49]
	v_mfma_f32_16x16x32_bf16 v[42:45], v[164:167], v[172:175], v[42:45]
	v_mfma_f32_16x16x32_bf16 v[30:33], v[156:159], v[180:183], v[30:33]
	v_mfma_f32_16x16x32_bf16 v[26:29], v[164:167], v[180:183], v[26:29]
	v_mfma_f32_16x16x32_bf16 v[14:17], v[156:159], v[188:191], v[14:17]
	v_mfma_f32_16x16x32_bf16 v[10:13], v[164:167], v[188:191], v[10:13]
	v_mfma_f32_16x16x32_bf16 v[6:9], v[156:159], v[196:199], v[6:9]
	v_mfma_f32_16x16x32_bf16 v[2:5], v[164:167], v[196:199], v[2:5]
	v_mfma_f32_16x16x32_bf16 v[46:49], v[160:163], v[176:179], v[46:49]
	v_mfma_f32_16x16x32_bf16 v[42:45], v[168:171], v[176:179], v[42:45]
	v_mfma_f32_16x16x32_bf16 v[30:33], v[160:163], v[184:187], v[30:33]
	v_mfma_f32_16x16x32_bf16 v[26:29], v[168:171], v[184:187], v[26:29]
	v_mfma_f32_16x16x32_bf16 v[14:17], v[160:163], v[192:195], v[14:17]
	v_mfma_f32_16x16x32_bf16 v[10:13], v[168:171], v[192:195], v[10:13]
	v_mfma_f32_16x16x32_bf16 v[6:9], v[160:163], v[208:211], v[6:9]
	v_mfma_f32_16x16x32_bf16 v[2:5], v[168:171], v[208:211], v[2:5]
	s_setprio 0
	s_barrier
	s_add_i32 s33, 0, 0x18000
	s_add_i32 s55, 0, 0x1c000
	v_add_u32_e32 v152, s33, v136
	v_add_u32_e32 v168, s55, v136
	ds_read_b128 v[140:143], v152
	ds_read_b128 v[144:147], v152 offset:1024
	ds_read_b128 v[148:151], v152 offset:2048
	ds_read_b128 v[152:155], v152 offset:3072
	ds_read_b128 v[156:159], v168
	ds_read_b128 v[160:163], v168 offset:1024
	ds_read_b128 v[164:167], v168 offset:2048
	ds_read_b128 v[168:171], v168 offset:3072
	s_add_u32 s0, s22, 0x100000
	s_addc_u32 s1, s23, 0
	s_mov_b32 m0, s29
	v_lshl_add_u64 v[214:215], s[0:1], 0, v[202:203]
	ds_read_b128 v[172:175], v139 offset:32768
	ds_read_b128 v[176:179], v139 offset:33792
	ds_read_b128 v[180:183], v139 offset:34816
	ds_read_b128 v[184:187], v139 offset:35840
	ds_read_b128 v[188:191], v139 offset:36864
	ds_read_b128 v[192:195], v139 offset:37888
	ds_read_b128 v[196:199], v139 offset:38912
	ds_read_b128 v[208:211], v139 offset:39936
	global_load_lds_dwordx4 v[214:215], off
	v_lshl_add_u64 v[214:215], s[0:1], 0, v[130:131]
	s_mov_b32 m0, s30
	s_nop 0
	global_load_lds_dwordx4 v[214:215], off
	s_waitcnt vmcnt(8)
	s_waitcnt lgkmcnt(0)
	s_barrier
	s_setprio 1
	s_waitcnt lgkmcnt(0)
	v_mfma_f32_16x16x32_bf16 v[126:129], v[140:143], v[172:175], v[126:129]
	v_mfma_f32_16x16x32_bf16 v[122:125], v[148:151], v[172:175], v[122:125]
	v_mfma_f32_16x16x32_bf16 v[118:121], v[140:143], v[180:183], v[118:121]
	v_mfma_f32_16x16x32_bf16 v[114:117], v[148:151], v[180:183], v[114:117]
	v_mfma_f32_16x16x32_bf16 v[106:109], v[140:143], v[188:191], v[106:109]
	v_mfma_f32_16x16x32_bf16 v[98:101], v[148:151], v[188:191], v[98:101]
	v_mfma_f32_16x16x32_bf16 v[90:93], v[140:143], v[196:199], v[90:93]
	v_mfma_f32_16x16x32_bf16 v[82:85], v[148:151], v[196:199], v[82:85]
	v_mfma_f32_16x16x32_bf16 v[126:129], v[144:147], v[176:179], v[126:129]
	v_mfma_f32_16x16x32_bf16 v[122:125], v[152:155], v[176:179], v[122:125]
	v_mfma_f32_16x16x32_bf16 v[118:121], v[144:147], v[184:187], v[118:121]
	v_mfma_f32_16x16x32_bf16 v[114:117], v[152:155], v[184:187], v[114:117]
	v_mfma_f32_16x16x32_bf16 v[106:109], v[144:147], v[192:195], v[106:109]
	v_mfma_f32_16x16x32_bf16 v[98:101], v[152:155], v[192:195], v[98:101]
	v_mfma_f32_16x16x32_bf16 v[90:93], v[144:147], v[208:211], v[90:93]
	v_mfma_f32_16x16x32_bf16 v[82:85], v[152:155], v[208:211], v[82:85]
	v_mfma_f32_16x16x32_bf16 v[110:113], v[156:159], v[172:175], v[110:113]
	v_mfma_f32_16x16x32_bf16 v[102:105], v[164:167], v[172:175], v[102:105]
	v_mfma_f32_16x16x32_bf16 v[94:97], v[156:159], v[180:183], v[94:97]
	v_mfma_f32_16x16x32_bf16 v[86:89], v[164:167], v[180:183], v[86:89]
	v_mfma_f32_16x16x32_bf16 v[78:81], v[156:159], v[188:191], v[78:81]
	v_mfma_f32_16x16x32_bf16 v[74:77], v[164:167], v[188:191], v[74:77]
	v_mfma_f32_16x16x32_bf16 v[70:73], v[156:159], v[196:199], v[70:73]
	v_mfma_f32_16x16x32_bf16 v[66:69], v[164:167], v[196:199], v[66:69]
	v_mfma_f32_16x16x32_bf16 v[110:113], v[160:163], v[176:179], v[110:113]
	v_mfma_f32_16x16x32_bf16 v[102:105], v[168:171], v[176:179], v[102:105]
	v_mfma_f32_16x16x32_bf16 v[94:97], v[160:163], v[184:187], v[94:97]
	v_mfma_f32_16x16x32_bf16 v[86:89], v[168:171], v[184:187], v[86:89]
	v_mfma_f32_16x16x32_bf16 v[78:81], v[160:163], v[192:195], v[78:81]
	v_mfma_f32_16x16x32_bf16 v[74:77], v[168:171], v[192:195], v[74:77]
	v_mfma_f32_16x16x32_bf16 v[70:73], v[160:163], v[208:211], v[70:73]
	v_mfma_f32_16x16x32_bf16 v[66:69], v[168:171], v[208:211], v[66:69]
	s_setprio 0
	s_barrier
	s_add_i32 s0, s33, s26
	v_lshl_add_u64 v[200:201], v[200:201], 0, s[80:81]
	s_mov_b32 m0, s0
	ds_read_b128 v[172:175], v139 offset:49152
	ds_read_b128 v[176:179], v139 offset:50176
	ds_read_b128 v[180:183], v139 offset:51200
	ds_read_b128 v[184:187], v139 offset:52224
	ds_read_b128 v[188:191], v139 offset:53248
	ds_read_b128 v[192:195], v139 offset:54272
	ds_read_b128 v[196:199], v139 offset:55296
	ds_read_b128 v[208:211], v139 offset:56320
	global_load_lds_dwordx4 v[200:201], off
	s_add_i32 m0, s0, 0x2000
	s_add_u32 s0, s20, 0x100080
	v_lshl_add_u64 v[200:201], v[204:205], 0, s[80:81]
	s_addc_u32 s1, s21, 0
	s_add_i32 s20, s55, s26
	global_load_lds_dwordx4 v[200:201], off
	v_lshl_add_u64 v[200:201], s[0:1], 0, v[202:203]
	s_mov_b32 m0, s20
	s_nop 0
	global_load_lds_dwordx4 v[200:201], off
	v_lshl_add_u64 v[200:201], s[0:1], 0, v[130:131]
	s_add_i32 m0, s20, 0x2000
	s_nop 0
	global_load_lds_dwordx4 v[200:201], off
	v_lshl_add_u64 v[200:201], v[206:207], 0, s[80:81]
	s_mov_b32 m0, s31
	s_nop 0
	global_load_lds_dwordx4 v[200:201], off
	v_lshl_add_u64 v[200:201], v[212:213], 0, s[80:81]
	s_mov_b32 m0, s34
	s_nop 0
	global_load_lds_dwordx4 v[200:201], off
	s_waitcnt vmcnt(8)
	s_waitcnt lgkmcnt(0)
	s_barrier
	s_setprio 1
	s_waitcnt lgkmcnt(0)
	v_mfma_f32_16x16x32_bf16 v[62:65], v[140:143], v[172:175], v[62:65]
	v_mfma_f32_16x16x32_bf16 v[58:61], v[148:151], v[172:175], v[58:61]
	v_mfma_f32_16x16x32_bf16 v[54:57], v[140:143], v[180:183], v[54:57]
	v_mfma_f32_16x16x32_bf16 v[50:53], v[148:151], v[180:183], v[50:53]
	v_mfma_f32_16x16x32_bf16 v[38:41], v[140:143], v[188:191], v[38:41]
	v_mfma_f32_16x16x32_bf16 v[34:37], v[148:151], v[188:191], v[34:37]
	v_mfma_f32_16x16x32_bf16 v[22:25], v[140:143], v[196:199], v[22:25]
	v_mfma_f32_16x16x32_bf16 v[18:21], v[148:151], v[196:199], v[18:21]
	v_mfma_f32_16x16x32_bf16 v[62:65], v[144:147], v[176:179], v[62:65]
	v_mfma_f32_16x16x32_bf16 v[58:61], v[152:155], v[176:179], v[58:61]
	v_mfma_f32_16x16x32_bf16 v[54:57], v[144:147], v[184:187], v[54:57]
	v_mfma_f32_16x16x32_bf16 v[50:53], v[152:155], v[184:187], v[50:53]
	v_mfma_f32_16x16x32_bf16 v[38:41], v[144:147], v[192:195], v[38:41]
	v_mfma_f32_16x16x32_bf16 v[34:37], v[152:155], v[192:195], v[34:37]
	v_mfma_f32_16x16x32_bf16 v[22:25], v[144:147], v[208:211], v[22:25]
	v_mfma_f32_16x16x32_bf16 v[18:21], v[152:155], v[208:211], v[18:21]
	v_mfma_f32_16x16x32_bf16 v[46:49], v[156:159], v[172:175], v[46:49]
	v_mfma_f32_16x16x32_bf16 v[42:45], v[164:167], v[172:175], v[42:45]
	v_mfma_f32_16x16x32_bf16 v[30:33], v[156:159], v[180:183], v[30:33]
	v_mfma_f32_16x16x32_bf16 v[26:29], v[164:167], v[180:183], v[26:29]
	v_mfma_f32_16x16x32_bf16 v[14:17], v[156:159], v[188:191], v[14:17]
	v_mfma_f32_16x16x32_bf16 v[10:13], v[164:167], v[188:191], v[10:13]
	v_mfma_f32_16x16x32_bf16 v[6:9], v[156:159], v[196:199], v[6:9]
	v_mfma_f32_16x16x32_bf16 v[2:5], v[164:167], v[196:199], v[2:5]
	v_mfma_f32_16x16x32_bf16 v[46:49], v[160:163], v[176:179], v[46:49]
	v_mfma_f32_16x16x32_bf16 v[42:45], v[168:171], v[176:179], v[42:45]
	v_mfma_f32_16x16x32_bf16 v[30:33], v[160:163], v[184:187], v[30:33]
	v_mfma_f32_16x16x32_bf16 v[26:29], v[168:171], v[184:187], v[26:29]
	v_mfma_f32_16x16x32_bf16 v[14:17], v[160:163], v[192:195], v[14:17]
	v_mfma_f32_16x16x32_bf16 v[10:13], v[168:171], v[192:195], v[10:13]
	v_mfma_f32_16x16x32_bf16 v[6:9], v[160:163], v[208:211], v[6:9]
	v_mfma_f32_16x16x32_bf16 v[2:5], v[168:171], v[208:211], v[2:5]
	s_setprio 0
	s_barrier
	s_add_i32 s49, s49, 2
	s_add_u32 s18, s18, 0x100
	s_addc_u32 s19, s19, 0
	s_add_u32 s9, s9, 0x100
	s_addc_u32 s11, s11, 0
	s_cmp_gt_u32 s49, 5
	s_cbranch_scc0 .LBB0_712
	s_and_b64 vcc, exec, s[6:7]
	s_cbranch_vccz .LBB0_715
	s_barrier

.LBB0_837:
	s_add_u32 s0, s18, 0xfff80080
	s_addc_u32 s1, s19, -1
	s_add_i32 s33, 0, 0x10000
	s_cmp_eq_u32 s59, 28
	s_cselect_b32 s23, s11, s1
	s_cselect_b32 s22, s38, s0
	v_add_u32_e32 v140, s33, v143
	s_cselect_b32 s21, s9, s58
	s_cselect_b32 s20, s39, s49
	s_add_i32 s55, 0, 0x14000
	ds_read_b128 v[146:149], v140
	ds_read_b128 v[150:153], v140 offset:1024
	ds_read_b128 v[154:157], v140 offset:2048
	ds_read_b128 v[158:161], v140 offset:3072
	v_add_u32_e32 v140, s55, v143
	ds_read_b128 v[162:165], v140
	ds_read_b128 v[166:169], v140 offset:1024
	ds_read_b128 v[170:173], v140 offset:2048
	ds_read_b128 v[174:177], v140 offset:3072
	v_lshl_add_u64 v[140:141], s[18:19], 0, v[136:137]
	s_add_i32 m0, s27, 0xc000
	ds_read_b128 v[178:181], v145
	ds_read_b128 v[182:185], v145 offset:1024
	ds_read_b128 v[186:189], v145 offset:2048
	ds_read_b128 v[190:193], v145 offset:3072
	ds_read_b128 v[194:197], v145 offset:4096
	ds_read_b128 v[198:201], v145 offset:5120
	ds_read_b128 v[208:211], v145 offset:6144
	ds_read_b128 v[212:215], v145 offset:7168
	global_load_lds_dwordx4 v[140:141], off
	v_lshl_add_u64 v[140:141], s[18:19], 0, v[138:139]
	s_add_i32 m0, s27, 0xe000
	s_nop 0
	global_load_lds_dwordx4 v[140:141], off
	s_waitcnt vmcnt(8)
	s_waitcnt lgkmcnt(0)
	s_barrier
	s_setprio 1
	s_waitcnt lgkmcnt(0)
	v_mfma_f32_16x16x32_bf16 v[126:129], v[146:149], v[178:181], v[126:129]
	v_mfma_f32_16x16x32_bf16 v[118:121], v[154:157], v[178:181], v[118:121]
	v_mfma_f32_16x16x32_bf16 v[110:113], v[146:149], v[186:189], v[110:113]
	v_mfma_f32_16x16x32_bf16 v[102:105], v[154:157], v[186:189], v[102:105]
	v_mfma_f32_16x16x32_bf16 v[94:97], v[146:149], v[194:197], v[94:97]
	v_mfma_f32_16x16x32_bf16 v[86:89], v[154:157], v[194:197], v[86:89]
	v_mfma_f32_16x16x32_bf16 v[78:81], v[146:149], v[208:211], v[78:81]
	v_mfma_f32_16x16x32_bf16 v[70:73], v[154:157], v[208:211], v[70:73]
	v_mfma_f32_16x16x32_bf16 v[126:129], v[150:153], v[182:185], v[126:129]
	v_mfma_f32_16x16x32_bf16 v[118:121], v[158:161], v[182:185], v[118:121]
	v_mfma_f32_16x16x32_bf16 v[110:113], v[150:153], v[190:193], v[110:113]
	v_mfma_f32_16x16x32_bf16 v[102:105], v[158:161], v[190:193], v[102:105]
	v_mfma_f32_16x16x32_bf16 v[94:97], v[150:153], v[198:201], v[94:97]
	v_mfma_f32_16x16x32_bf16 v[86:89], v[158:161], v[198:201], v[86:89]
	v_mfma_f32_16x16x32_bf16 v[78:81], v[150:153], v[212:215], v[78:81]
	v_mfma_f32_16x16x32_bf16 v[70:73], v[158:161], v[212:215], v[70:73]
	v_mfma_f32_16x16x32_bf16 v[122:125], v[162:165], v[178:181], v[122:125]
	v_mfma_f32_16x16x32_bf16 v[114:117], v[170:173], v[178:181], v[114:117]
	v_mfma_f32_16x16x32_bf16 v[106:109], v[162:165], v[186:189], v[106:109]
	v_mfma_f32_16x16x32_bf16 v[98:101], v[170:173], v[186:189], v[98:101]
	v_mfma_f32_16x16x32_bf16 v[90:93], v[162:165], v[194:197], v[90:93]
	v_mfma_f32_16x16x32_bf16 v[82:85], v[170:173], v[194:197], v[82:85]
	v_mfma_f32_16x16x32_bf16 v[74:77], v[162:165], v[208:211], v[74:77]
	v_mfma_f32_16x16x32_bf16 v[66:69], v[170:173], v[208:211], v[66:69]
	v_mfma_f32_16x16x32_bf16 v[122:125], v[166:169], v[182:185], v[122:125]
	v_mfma_f32_16x16x32_bf16 v[114:117], v[174:177], v[182:185], v[114:117]
	v_mfma_f32_16x16x32_bf16 v[106:109], v[166:169], v[190:193], v[106:109]
	v_mfma_f32_16x16x32_bf16 v[98:101], v[174:177], v[190:193], v[98:101]
	v_mfma_f32_16x16x32_bf16 v[90:93], v[166:169], v[198:201], v[90:93]
	v_mfma_f32_16x16x32_bf16 v[82:85], v[174:177], v[198:201], v[82:85]
	v_mfma_f32_16x16x32_bf16 v[74:77], v[166:169], v[212:215], v[74:77]
	v_mfma_f32_16x16x32_bf16 v[66:69], v[174:177], v[212:215], v[66:69]
	s_setprio 0
	s_barrier
	s_add_i32 s0, s33, s26
	v_lshl_add_u64 v[140:141], s[20:21], 0, v[202:203]
	s_mov_b32 m0, s0
	ds_read_b128 v[178:181], v145 offset:16384
	ds_read_b128 v[182:185], v145 offset:17408
	ds_read_b128 v[186:189], v145 offset:18432
	ds_read_b128 v[190:193], v145 offset:19456
	ds_read_b128 v[194:197], v145 offset:20480
	ds_read_b128 v[198:201], v145 offset:21504
	ds_read_b128 v[208:211], v145 offset:22528
	ds_read_b128 v[212:215], v145 offset:23552
	global_load_lds_dwordx4 v[140:141], off
	s_add_i32 m0, s0, 0x2000
	s_add_u32 s0, s20, 0x80000
	v_lshl_add_u64 v[204:205], s[20:21], 0, v[130:131]
	s_addc_u32 s1, s21, 0
	s_add_i32 s33, s55, s26
	global_load_lds_dwordx4 v[204:205], off
	v_lshl_add_u64 v[206:207], s[0:1], 0, v[202:203]
	s_mov_b32 m0, s33
	v_lshl_add_u64 v[216:217], s[22:23], 0, v[132:133]
	global_load_lds_dwordx4 v[206:207], off
	v_lshl_add_u64 v[206:207], s[0:1], 0, v[130:131]
	s_add_i32 m0, s33, 0x2000
	s_nop 0
	global_load_lds_dwordx4 v[206:207], off
	v_lshl_add_u64 v[206:207], s[22:23], 0, v[134:135]
	s_mov_b32 m0, s27
	s_nop 0
	global_load_lds_dwordx4 v[206:207], off
	s_mov_b32 m0, s28
	s_nop 0
	global_load_lds_dwordx4 v[216:217], off
	s_waitcnt vmcnt(8)
	s_waitcnt lgkmcnt(0)
	s_barrier
	s_setprio 1
	s_waitcnt lgkmcnt(0)
	v_mfma_f32_16x16x32_bf16 v[62:65], v[146:149], v[178:181], v[62:65]
	v_mfma_f32_16x16x32_bf16 v[54:57], v[154:157], v[178:181], v[54:57]
	v_mfma_f32_16x16x32_bf16 v[46:49], v[146:149], v[186:189], v[46:49]
	v_mfma_f32_16x16x32_bf16 v[38:41], v[154:157], v[186:189], v[38:41]
	v_mfma_f32_16x16x32_bf16 v[30:33], v[146:149], v[194:197], v[30:33]
	v_mfma_f32_16x16x32_bf16 v[22:25], v[154:157], v[194:197], v[22:25]
	v_mfma_f32_16x16x32_bf16 v[14:17], v[146:149], v[208:211], v[14:17]
	v_mfma_f32_16x16x32_bf16 v[6:9], v[154:157], v[208:211], v[6:9]
	v_mfma_f32_16x16x32_bf16 v[62:65], v[150:153], v[182:185], v[62:65]
	v_mfma_f32_16x16x32_bf16 v[54:57], v[158:161], v[182:185], v[54:57]
	v_mfma_f32_16x16x32_bf16 v[46:49], v[150:153], v[190:193], v[46:49]
	v_mfma_f32_16x16x32_bf16 v[38:41], v[158:161], v[190:193], v[38:41]
	v_mfma_f32_16x16x32_bf16 v[30:33], v[150:153], v[198:201], v[30:33]
	v_mfma_f32_16x16x32_bf16 v[22:25], v[158:161], v[198:201], v[22:25]
	v_mfma_f32_16x16x32_bf16 v[14:17], v[150:153], v[212:215], v[14:17]
	v_mfma_f32_16x16x32_bf16 v[6:9], v[158:161], v[212:215], v[6:9]
	v_mfma_f32_16x16x32_bf16 v[58:61], v[162:165], v[178:181], v[58:61]
	v_mfma_f32_16x16x32_bf16 v[50:53], v[170:173], v[178:181], v[50:53]
	v_mfma_f32_16x16x32_bf16 v[42:45], v[162:165], v[186:189], v[42:45]
	v_mfma_f32_16x16x32_bf16 v[34:37], v[170:173], v[186:189], v[34:37]
	v_mfma_f32_16x16x32_bf16 v[26:29], v[162:165], v[194:197], v[26:29]
	v_mfma_f32_16x16x32_bf16 v[18:21], v[170:173], v[194:197], v[18:21]
	v_mfma_f32_16x16x32_bf16 v[10:13], v[162:165], v[208:211], v[10:13]
	v_mfma_f32_16x16x32_bf16 v[2:5], v[170:173], v[208:211], v[2:5]
	v_mfma_f32_16x16x32_bf16 v[58:61], v[166:169], v[182:185], v[58:61]
	v_mfma_f32_16x16x32_bf16 v[50:53], v[174:177], v[182:185], v[50:53]
	v_mfma_f32_16x16x32_bf16 v[42:45], v[166:169], v[190:193], v[42:45]
	v_mfma_f32_16x16x32_bf16 v[34:37], v[174:177], v[190:193], v[34:37]
	v_mfma_f32_16x16x32_bf16 v[26:29], v[166:169], v[198:201], v[26:29]
	v_mfma_f32_16x16x32_bf16 v[18:21], v[174:177], v[198:201], v[18:21]
	v_mfma_f32_16x16x32_bf16 v[10:13], v[166:169], v[212:215], v[10:13]
	v_mfma_f32_16x16x32_bf16 v[2:5], v[174:177], v[212:215], v[2:5]
	s_setprio 0
	s_barrier
	s_add_i32 s33, 0, 0x18000
	s_add_i32 s55, 0, 0x1c000
	v_add_u32_e32 v158, s33, v143
	v_add_u32_e32 v174, s55, v143
	ds_read_b128 v[146:149], v158
	ds_read_b128 v[150:153], v158 offset:1024
	ds_read_b128 v[154:157], v158 offset:2048
	ds_read_b128 v[158:161], v158 offset:3072
	ds_read_b128 v[162:165], v174
	ds_read_b128 v[166:169], v174 offset:1024
	ds_read_b128 v[170:173], v174 offset:2048
	ds_read_b128 v[174:177], v174 offset:3072
	s_add_u32 s0, s22, 0x80000
	s_addc_u32 s1, s23, 0
	s_mov_b32 m0, s29
	v_lshl_add_u64 v[218:219], s[0:1], 0, v[134:135]
	ds_read_b128 v[178:181], v145 offset:32768
	ds_read_b128 v[182:185], v145 offset:33792
	ds_read_b128 v[186:189], v145 offset:34816
	ds_read_b128 v[190:193], v145 offset:35840
	ds_read_b128 v[194:197], v145 offset:36864
	ds_read_b128 v[198:201], v145 offset:37888
	ds_read_b128 v[208:211], v145 offset:38912
	ds_read_b128 v[212:215], v145 offset:39936
	global_load_lds_dwordx4 v[218:219], off
	v_lshl_add_u64 v[218:219], s[0:1], 0, v[132:133]
	s_mov_b32 m0, s30
	s_nop 0
	global_load_lds_dwordx4 v[218:219], off
	s_waitcnt vmcnt(8)
	s_waitcnt lgkmcnt(0)
	s_barrier
	s_setprio 1
	s_waitcnt lgkmcnt(0)
	v_mfma_f32_16x16x32_bf16 v[126:129], v[146:149], v[178:181], v[126:129]
	v_mfma_f32_16x16x32_bf16 v[118:121], v[154:157], v[178:181], v[118:121]
	v_mfma_f32_16x16x32_bf16 v[110:113], v[146:149], v[186:189], v[110:113]
	v_mfma_f32_16x16x32_bf16 v[102:105], v[154:157], v[186:189], v[102:105]
	v_mfma_f32_16x16x32_bf16 v[94:97], v[146:149], v[194:197], v[94:97]
	v_mfma_f32_16x16x32_bf16 v[86:89], v[154:157], v[194:197], v[86:89]
	v_mfma_f32_16x16x32_bf16 v[78:81], v[146:149], v[208:211], v[78:81]
	v_mfma_f32_16x16x32_bf16 v[70:73], v[154:157], v[208:211], v[70:73]
	v_mfma_f32_16x16x32_bf16 v[126:129], v[150:153], v[182:185], v[126:129]
	v_mfma_f32_16x16x32_bf16 v[118:121], v[158:161], v[182:185], v[118:121]
	v_mfma_f32_16x16x32_bf16 v[110:113], v[150:153], v[190:193], v[110:113]
	v_mfma_f32_16x16x32_bf16 v[102:105], v[158:161], v[190:193], v[102:105]
	v_mfma_f32_16x16x32_bf16 v[94:97], v[150:153], v[198:201], v[94:97]
	v_mfma_f32_16x16x32_bf16 v[86:89], v[158:161], v[198:201], v[86:89]
	v_mfma_f32_16x16x32_bf16 v[78:81], v[150:153], v[212:215], v[78:81]
	v_mfma_f32_16x16x32_bf16 v[70:73], v[158:161], v[212:215], v[70:73]
	v_mfma_f32_16x16x32_bf16 v[122:125], v[162:165], v[178:181], v[122:125]
	v_mfma_f32_16x16x32_bf16 v[114:117], v[170:173], v[178:181], v[114:117]
	v_mfma_f32_16x16x32_bf16 v[106:109], v[162:165], v[186:189], v[106:109]
	v_mfma_f32_16x16x32_bf16 v[98:101], v[170:173], v[186:189], v[98:101]
	v_mfma_f32_16x16x32_bf16 v[90:93], v[162:165], v[194:197], v[90:93]
	v_mfma_f32_16x16x32_bf16 v[82:85], v[170:173], v[194:197], v[82:85]
	v_mfma_f32_16x16x32_bf16 v[74:77], v[162:165], v[208:211], v[74:77]
	v_mfma_f32_16x16x32_bf16 v[66:69], v[170:173], v[208:211], v[66:69]
	v_mfma_f32_16x16x32_bf16 v[122:125], v[166:169], v[182:185], v[122:125]
	v_mfma_f32_16x16x32_bf16 v[114:117], v[174:177], v[182:185], v[114:117]
	v_mfma_f32_16x16x32_bf16 v[106:109], v[166:169], v[190:193], v[106:109]
	v_mfma_f32_16x16x32_bf16 v[98:101], v[174:177], v[190:193], v[98:101]
	v_mfma_f32_16x16x32_bf16 v[90:93], v[166:169], v[198:201], v[90:93]
	v_mfma_f32_16x16x32_bf16 v[82:85], v[174:177], v[198:201], v[82:85]
	v_mfma_f32_16x16x32_bf16 v[74:77], v[166:169], v[212:215], v[74:77]
	v_mfma_f32_16x16x32_bf16 v[66:69], v[174:177], v[212:215], v[66:69]
	s_setprio 0
	s_barrier
	s_add_i32 s0, s33, s26
	v_lshl_add_u64 v[140:141], v[140:141], 0, s[80:81]
	s_mov_b32 m0, s0
	ds_read_b128 v[178:181], v145 offset:49152
	ds_read_b128 v[182:185], v145 offset:50176
	ds_read_b128 v[186:189], v145 offset:51200
	ds_read_b128 v[190:193], v145 offset:52224
	ds_read_b128 v[194:197], v145 offset:53248
	ds_read_b128 v[198:201], v145 offset:54272
	ds_read_b128 v[208:211], v145 offset:55296
	ds_read_b128 v[212:215], v145 offset:56320
	global_load_lds_dwordx4 v[140:141], off
	s_add_i32 m0, s0, 0x2000
	s_add_u32 s0, s20, 0x80080
	v_lshl_add_u64 v[140:141], v[204:205], 0, s[80:81]
	s_addc_u32 s1, s21, 0
	s_add_i32 s20, s55, s26
	global_load_lds_dwordx4 v[140:141], off
	v_lshl_add_u64 v[140:141], s[0:1], 0, v[202:203]
	s_mov_b32 m0, s20
	s_nop 0
	global_load_lds_dwordx4 v[140:141], off
	v_lshl_add_u64 v[140:141], s[0:1], 0, v[130:131]
	s_add_i32 m0, s20, 0x2000
	s_nop 0
	global_load_lds_dwordx4 v[140:141], off
	v_lshl_add_u64 v[140:141], v[206:207], 0, s[80:81]
	s_mov_b32 m0, s31
	s_nop 0
	global_load_lds_dwordx4 v[140:141], off
	v_lshl_add_u64 v[140:141], v[216:217], 0, s[80:81]
	s_mov_b32 m0, s34
	s_nop 0
	global_load_lds_dwordx4 v[140:141], off
	s_waitcnt vmcnt(8)
	s_waitcnt lgkmcnt(0)
	s_barrier
	s_setprio 1
	s_waitcnt lgkmcnt(0)
	v_mfma_f32_16x16x32_bf16 v[62:65], v[146:149], v[178:181], v[62:65]
	v_mfma_f32_16x16x32_bf16 v[54:57], v[154:157], v[178:181], v[54:57]
	v_mfma_f32_16x16x32_bf16 v[46:49], v[146:149], v[186:189], v[46:49]
	v_mfma_f32_16x16x32_bf16 v[38:41], v[154:157], v[186:189], v[38:41]
	v_mfma_f32_16x16x32_bf16 v[30:33], v[146:149], v[194:197], v[30:33]
	v_mfma_f32_16x16x32_bf16 v[22:25], v[154:157], v[194:197], v[22:25]
	v_mfma_f32_16x16x32_bf16 v[14:17], v[146:149], v[208:211], v[14:17]
	v_mfma_f32_16x16x32_bf16 v[6:9], v[154:157], v[208:211], v[6:9]
	v_mfma_f32_16x16x32_bf16 v[62:65], v[150:153], v[182:185], v[62:65]
	v_mfma_f32_16x16x32_bf16 v[54:57], v[158:161], v[182:185], v[54:57]
	v_mfma_f32_16x16x32_bf16 v[46:49], v[150:153], v[190:193], v[46:49]
	v_mfma_f32_16x16x32_bf16 v[38:41], v[158:161], v[190:193], v[38:41]
	v_mfma_f32_16x16x32_bf16 v[30:33], v[150:153], v[198:201], v[30:33]
	v_mfma_f32_16x16x32_bf16 v[22:25], v[158:161], v[198:201], v[22:25]
	v_mfma_f32_16x16x32_bf16 v[14:17], v[150:153], v[212:215], v[14:17]
	v_mfma_f32_16x16x32_bf16 v[6:9], v[158:161], v[212:215], v[6:9]
	v_mfma_f32_16x16x32_bf16 v[58:61], v[162:165], v[178:181], v[58:61]
	v_mfma_f32_16x16x32_bf16 v[50:53], v[170:173], v[178:181], v[50:53]
	v_mfma_f32_16x16x32_bf16 v[42:45], v[162:165], v[186:189], v[42:45]
	v_mfma_f32_16x16x32_bf16 v[34:37], v[170:173], v[186:189], v[34:37]
	v_mfma_f32_16x16x32_bf16 v[26:29], v[162:165], v[194:197], v[26:29]
	v_mfma_f32_16x16x32_bf16 v[18:21], v[170:173], v[194:197], v[18:21]
	v_mfma_f32_16x16x32_bf16 v[10:13], v[162:165], v[208:211], v[10:13]
	v_mfma_f32_16x16x32_bf16 v[2:5], v[170:173], v[208:211], v[2:5]
	v_mfma_f32_16x16x32_bf16 v[58:61], v[166:169], v[182:185], v[58:61]
	v_mfma_f32_16x16x32_bf16 v[50:53], v[174:177], v[182:185], v[50:53]
	v_mfma_f32_16x16x32_bf16 v[42:45], v[166:169], v[190:193], v[42:45]
	v_mfma_f32_16x16x32_bf16 v[34:37], v[174:177], v[190:193], v[34:37]
	v_mfma_f32_16x16x32_bf16 v[26:29], v[166:169], v[198:201], v[26:29]
	v_mfma_f32_16x16x32_bf16 v[18:21], v[174:177], v[198:201], v[18:21]
	v_mfma_f32_16x16x32_bf16 v[10:13], v[166:169], v[212:215], v[10:13]
	v_mfma_f32_16x16x32_bf16 v[2:5], v[174:177], v[212:215], v[2:5]
	s_setprio 0
	s_barrier
	s_add_i32 s59, s59, 2
	s_add_u32 s18, s18, 0x100
	s_addc_u32 s19, s19, 0
	s_add_u32 s49, s49, 0x100
	s_addc_u32 s58, s58, 0
	s_cmp_gt_u32 s59, 29
	s_cbranch_scc0 .LBB0_837
	s_and_b64 vcc, exec, s[6:7]
	s_cbranch_vccz .LBB0_840
	s_barrier

.LBB0_970:
	s_add_u32 s16, s2, 0x100
	s_addc_u32 s17, s3, 0
	s_add_i32 s0, 0, 0x10000
	s_cmpk_eq_i32 s59, 0x54
	s_cselect_b32 s21, s7, s17
	s_cselect_b32 s20, s6, s16
	s_cselect_b32 s19, s15, s58
	s_cselect_b32 s18, s14, s49
	s_add_i32 s33, 0, 0x14000
	v_add_u32_e32 v98, s0, v205
	v_add_u32_e32 v134, s33, v205
	ds_read_b128 v[78:81], v98
	ds_read_b128 v[82:85], v98 offset:1024
	ds_read_b128 v[94:97], v98 offset:2048
	ds_read_b128 v[98:101], v98 offset:3072
	ds_read_b128 v[106:109], v134
	ds_read_b128 v[110:113], v134 offset:1024
	ds_read_b128 v[126:129], v134 offset:2048
	ds_read_b128 v[134:137], v134 offset:3072
	v_lshl_add_u64 v[194:195], s[2:3], 0, v[214:215]
	s_add_i32 m0, s25, 0xc000
	ds_read_b128 v[146:149], v239
	ds_read_b128 v[158:161], v239 offset:1024
	ds_read_b128 v[166:169], v239 offset:2048
	ds_read_b128 v[174:177], v239 offset:3072
	ds_read_b128 v[178:181], v239 offset:4096
	ds_read_b128 v[182:185], v239 offset:5120
	ds_read_b128 v[186:189], v239 offset:6144
	ds_read_b128 v[190:193], v239 offset:7168
	global_load_lds_dwordx4 v[194:195], off
	v_lshl_add_u64 v[194:195], s[2:3], 0, v[216:217]
	s_add_i32 m0, s25, 0xe000
	s_nop 0
	global_load_lds_dwordx4 v[194:195], off
	s_waitcnt vmcnt(8)
	s_waitcnt lgkmcnt(0)
	s_barrier
	s_setprio 1
	s_waitcnt lgkmcnt(0)
	v_mfma_f32_16x16x32_bf16 v[170:173], v[78:81], v[146:149], v[170:173]
	v_mfma_f32_16x16x32_bf16 v[162:165], v[94:97], v[146:149], v[162:165]
	v_mfma_f32_16x16x32_bf16 v[142:145], v[78:81], v[166:169], v[142:145]
	v_mfma_f32_16x16x32_bf16 v[138:141], v[94:97], v[166:169], v[138:141]
	v_mfma_f32_16x16x32_bf16 v[118:121], v[78:81], v[178:181], v[118:121]
	v_mfma_f32_16x16x32_bf16 v[114:117], v[94:97], v[178:181], v[114:117]
	v_mfma_f32_16x16x32_bf16 v[86:89], v[78:81], v[186:189], v[86:89]
	v_mfma_f32_16x16x32_bf16 v[74:77], v[94:97], v[186:189], v[74:77]
	v_mfma_f32_16x16x32_bf16 v[170:173], v[82:85], v[158:161], v[170:173]
	v_mfma_f32_16x16x32_bf16 v[162:165], v[98:101], v[158:161], v[162:165]
	v_mfma_f32_16x16x32_bf16 v[142:145], v[82:85], v[174:177], v[142:145]
	v_mfma_f32_16x16x32_bf16 v[138:141], v[98:101], v[174:177], v[138:141]
	v_mfma_f32_16x16x32_bf16 v[118:121], v[82:85], v[182:185], v[118:121]
	v_mfma_f32_16x16x32_bf16 v[114:117], v[98:101], v[182:185], v[114:117]
	v_mfma_f32_16x16x32_bf16 v[86:89], v[82:85], v[190:193], v[86:89]
	v_mfma_f32_16x16x32_bf16 v[74:77], v[98:101], v[190:193], v[74:77]
	v_mfma_f32_16x16x32_bf16 v[154:157], v[106:109], v[146:149], v[154:157]
	v_mfma_f32_16x16x32_bf16 v[130:133], v[106:109], v[166:169], v[130:133]
	v_mfma_f32_16x16x32_bf16 v[122:125], v[126:129], v[166:169], v[122:125]
	v_mfma_f32_16x16x32_bf16 v[102:105], v[106:109], v[178:181], v[102:105]
	v_mfma_f32_16x16x32_bf16 v[90:93], v[126:129], v[178:181], v[90:93]
	v_mfma_f32_16x16x32_bf16 v[70:73], v[106:109], v[186:189], v[70:73]
	v_mfma_f32_16x16x32_bf16 v[66:69], v[126:129], v[186:189], v[66:69]
	v_mfma_f32_16x16x32_bf16 v[154:157], v[110:113], v[158:161], v[154:157]
	v_mfma_f32_16x16x32_bf16 v[146:149], v[126:129], v[146:149], v[150:153]
	v_mfma_f32_16x16x32_bf16 v[130:133], v[110:113], v[174:177], v[130:133]
	v_mfma_f32_16x16x32_bf16 v[122:125], v[134:137], v[174:177], v[122:125]
	v_mfma_f32_16x16x32_bf16 v[102:105], v[110:113], v[182:185], v[102:105]
	v_mfma_f32_16x16x32_bf16 v[90:93], v[134:137], v[182:185], v[90:93]
	v_mfma_f32_16x16x32_bf16 v[70:73], v[110:113], v[190:193], v[70:73]
	v_mfma_f32_16x16x32_bf16 v[66:69], v[134:137], v[190:193], v[66:69]
	v_mfma_f32_16x16x32_bf16 v[146:149], v[134:137], v[158:161], v[146:149]
	s_setprio 0
	s_barrier
	s_add_i32 s0, s0, s24
	v_lshl_add_u64 v[194:195], s[18:19], 0, v[202:203]
	s_mov_b32 m0, s0
	ds_read_b128 v[150:153], v239 offset:16384
	ds_read_b128 v[158:161], v239 offset:17408
	ds_read_b128 v[166:169], v239 offset:18432
	ds_read_b128 v[174:177], v239 offset:19456
	ds_read_b128 v[178:181], v239 offset:20480
	ds_read_b128 v[182:185], v239 offset:21504
	ds_read_b128 v[186:189], v239 offset:22528
	ds_read_b128 v[190:193], v239 offset:23552
	global_load_lds_dwordx4 v[194:195], off
	s_add_i32 m0, s0, 0x2000
	s_add_u32 s0, s18, 0x160000
	v_lshl_add_u64 v[196:197], s[18:19], 0, v[208:209]
	s_addc_u32 s1, s19, 0
	s_add_i32 s2, s33, s24
	global_load_lds_dwordx4 v[196:197], off
	v_lshl_add_u64 v[198:199], s[0:1], 0, v[202:203]
	s_mov_b32 m0, s2
	v_lshl_add_u64 v[200:201], s[20:21], 0, v[210:211]
	global_load_lds_dwordx4 v[198:199], off
	v_lshl_add_u64 v[198:199], s[0:1], 0, v[208:209]
	s_add_i32 m0, s2, 0x2000
	s_nop 0
	global_load_lds_dwordx4 v[198:199], off
	v_lshl_add_u64 v[198:199], s[20:21], 0, v[212:213]
	s_mov_b32 m0, s25
	s_nop 0
	global_load_lds_dwordx4 v[198:199], off
	s_mov_b32 m0, s26
	s_nop 0
	global_load_lds_dwordx4 v[200:201], off
	s_waitcnt vmcnt(8)
	s_waitcnt lgkmcnt(0)
	s_barrier
	s_setprio 1
	s_waitcnt lgkmcnt(0)
	v_mfma_f32_16x16x32_bf16 v[62:65], v[78:81], v[150:153], v[62:65]
	v_mfma_f32_16x16x32_bf16 v[58:61], v[94:97], v[150:153], v[58:61]
	v_mfma_f32_16x16x32_bf16 v[46:49], v[78:81], v[166:169], v[46:49]
	v_mfma_f32_16x16x32_bf16 v[42:45], v[94:97], v[166:169], v[42:45]
	v_mfma_f32_16x16x32_bf16 v[30:33], v[78:81], v[178:181], v[30:33]
	v_mfma_f32_16x16x32_bf16 v[26:29], v[94:97], v[178:181], v[26:29]
	v_mfma_f32_16x16x32_bf16 v[14:17], v[78:81], v[186:189], v[14:17]
	v_mfma_f32_16x16x32_bf16 v[10:13], v[94:97], v[186:189], v[10:13]
	v_mfma_f32_16x16x32_bf16 v[62:65], v[82:85], v[158:161], v[62:65]
	v_mfma_f32_16x16x32_bf16 v[58:61], v[98:101], v[158:161], v[58:61]
	v_mfma_f32_16x16x32_bf16 v[46:49], v[82:85], v[174:177], v[46:49]
	v_mfma_f32_16x16x32_bf16 v[42:45], v[98:101], v[174:177], v[42:45]
	v_mfma_f32_16x16x32_bf16 v[30:33], v[82:85], v[182:185], v[30:33]
	v_mfma_f32_16x16x32_bf16 v[26:29], v[98:101], v[182:185], v[26:29]
	v_mfma_f32_16x16x32_bf16 v[14:17], v[82:85], v[190:193], v[14:17]
	v_mfma_f32_16x16x32_bf16 v[10:13], v[98:101], v[190:193], v[10:13]
	v_mfma_f32_16x16x32_bf16 v[54:57], v[106:109], v[150:153], v[54:57]
	v_mfma_f32_16x16x32_bf16 v[50:53], v[126:129], v[150:153], v[50:53]
	v_mfma_f32_16x16x32_bf16 v[38:41], v[106:109], v[166:169], v[38:41]
	v_mfma_f32_16x16x32_bf16 v[34:37], v[126:129], v[166:169], v[34:37]
	v_mfma_f32_16x16x32_bf16 v[22:25], v[106:109], v[178:181], v[22:25]
	v_mfma_f32_16x16x32_bf16 v[18:21], v[126:129], v[178:181], v[18:21]
	v_mfma_f32_16x16x32_bf16 v[6:9], v[106:109], v[186:189], v[6:9]
	v_mfma_f32_16x16x32_bf16 v[2:5], v[126:129], v[186:189], v[2:5]
	v_mfma_f32_16x16x32_bf16 v[54:57], v[110:113], v[158:161], v[54:57]
	v_mfma_f32_16x16x32_bf16 v[50:53], v[134:137], v[158:161], v[50:53]
	v_mfma_f32_16x16x32_bf16 v[38:41], v[110:113], v[174:177], v[38:41]
	v_mfma_f32_16x16x32_bf16 v[34:37], v[134:137], v[174:177], v[34:37]
	v_mfma_f32_16x16x32_bf16 v[22:25], v[110:113], v[182:185], v[22:25]
	v_mfma_f32_16x16x32_bf16 v[18:21], v[134:137], v[182:185], v[18:21]
	v_mfma_f32_16x16x32_bf16 v[6:9], v[110:113], v[190:193], v[6:9]
	v_mfma_f32_16x16x32_bf16 v[2:5], v[134:137], v[190:193], v[2:5]
	s_setprio 0
	s_barrier
	s_add_i32 s2, 0, 0x18000
	s_add_i32 s3, 0, 0x1c000
	v_add_u32_e32 v98, s2, v205
	v_add_u32_e32 v134, s3, v205
	ds_read_b128 v[78:81], v98
	ds_read_b128 v[82:85], v98 offset:1024
	ds_read_b128 v[94:97], v98 offset:2048
	ds_read_b128 v[98:101], v98 offset:3072
	ds_read_b128 v[106:109], v134
	ds_read_b128 v[110:113], v134 offset:1024
	ds_read_b128 v[126:129], v134 offset:2048
	ds_read_b128 v[134:137], v134 offset:3072
	s_add_u32 s0, s20, 0x160000
	s_addc_u32 s1, s21, 0
	s_mov_b32 m0, s27
	v_lshl_add_u64 v[206:207], s[0:1], 0, v[212:213]
	ds_read_b128 v[150:153], v239 offset:32768
	ds_read_b128 v[158:161], v239 offset:33792
	ds_read_b128 v[166:169], v239 offset:34816
	ds_read_b128 v[174:177], v239 offset:35840
	ds_read_b128 v[178:181], v239 offset:36864
	ds_read_b128 v[182:185], v239 offset:37888
	ds_read_b128 v[186:189], v239 offset:38912
	ds_read_b128 v[190:193], v239 offset:39936
	global_load_lds_dwordx4 v[206:207], off
	v_lshl_add_u64 v[206:207], s[0:1], 0, v[210:211]
	s_mov_b32 m0, s28
	s_nop 0
	global_load_lds_dwordx4 v[206:207], off
	s_waitcnt vmcnt(8)
	s_waitcnt lgkmcnt(0)
	s_barrier
	s_setprio 1
	s_waitcnt lgkmcnt(0)
	v_mfma_f32_16x16x32_bf16 v[170:173], v[78:81], v[150:153], v[170:173]
	v_mfma_f32_16x16x32_bf16 v[162:165], v[94:97], v[150:153], v[162:165]
	v_mfma_f32_16x16x32_bf16 v[142:145], v[78:81], v[166:169], v[142:145]
	v_mfma_f32_16x16x32_bf16 v[138:141], v[94:97], v[166:169], v[138:141]
	v_mfma_f32_16x16x32_bf16 v[118:121], v[78:81], v[178:181], v[118:121]
	v_mfma_f32_16x16x32_bf16 v[114:117], v[94:97], v[178:181], v[114:117]
	v_mfma_f32_16x16x32_bf16 v[86:89], v[78:81], v[186:189], v[86:89]
	v_mfma_f32_16x16x32_bf16 v[74:77], v[94:97], v[186:189], v[74:77]
	v_mfma_f32_16x16x32_bf16 v[170:173], v[82:85], v[158:161], v[170:173]
	v_mfma_f32_16x16x32_bf16 v[162:165], v[98:101], v[158:161], v[162:165]
	v_mfma_f32_16x16x32_bf16 v[142:145], v[82:85], v[174:177], v[142:145]
	v_mfma_f32_16x16x32_bf16 v[138:141], v[98:101], v[174:177], v[138:141]
	v_mfma_f32_16x16x32_bf16 v[118:121], v[82:85], v[182:185], v[118:121]
	v_mfma_f32_16x16x32_bf16 v[114:117], v[98:101], v[182:185], v[114:117]
	v_mfma_f32_16x16x32_bf16 v[86:89], v[82:85], v[190:193], v[86:89]
	v_mfma_f32_16x16x32_bf16 v[74:77], v[98:101], v[190:193], v[74:77]
	v_mfma_f32_16x16x32_bf16 v[154:157], v[106:109], v[150:153], v[154:157]
	v_mfma_f32_16x16x32_bf16 v[146:149], v[126:129], v[150:153], v[146:149]
	v_mfma_f32_16x16x32_bf16 v[130:133], v[106:109], v[166:169], v[130:133]
	v_mfma_f32_16x16x32_bf16 v[122:125], v[126:129], v[166:169], v[122:125]
	v_mfma_f32_16x16x32_bf16 v[102:105], v[106:109], v[178:181], v[102:105]
	v_mfma_f32_16x16x32_bf16 v[90:93], v[126:129], v[178:181], v[90:93]
	v_mfma_f32_16x16x32_bf16 v[70:73], v[106:109], v[186:189], v[70:73]
	v_mfma_f32_16x16x32_bf16 v[66:69], v[126:129], v[186:189], v[66:69]
	v_mfma_f32_16x16x32_bf16 v[154:157], v[110:113], v[158:161], v[154:157]
	v_mfma_f32_16x16x32_bf16 v[150:153], v[134:137], v[158:161], v[146:149]
	v_mfma_f32_16x16x32_bf16 v[130:133], v[110:113], v[174:177], v[130:133]
	v_mfma_f32_16x16x32_bf16 v[122:125], v[134:137], v[174:177], v[122:125]
	v_mfma_f32_16x16x32_bf16 v[102:105], v[110:113], v[182:185], v[102:105]
	v_mfma_f32_16x16x32_bf16 v[90:93], v[134:137], v[182:185], v[90:93]
	v_mfma_f32_16x16x32_bf16 v[70:73], v[110:113], v[190:193], v[70:73]
	v_mfma_f32_16x16x32_bf16 v[66:69], v[134:137], v[190:193], v[66:69]
	s_setprio 0
	s_barrier
	s_add_i32 s0, s2, s24
	v_lshl_add_u64 v[194:195], v[194:195], 0, s[80:81]
	s_mov_b32 m0, s0
	ds_read_b128 v[146:149], v239 offset:49152
	ds_read_b128 v[158:161], v239 offset:50176
	ds_read_b128 v[166:169], v239 offset:51200
	ds_read_b128 v[174:177], v239 offset:52224
	ds_read_b128 v[178:181], v239 offset:53248
	ds_read_b128 v[182:185], v239 offset:54272
	ds_read_b128 v[186:189], v239 offset:55296
	ds_read_b128 v[190:193], v239 offset:56320
	global_load_lds_dwordx4 v[194:195], off
	s_add_i32 m0, s0, 0x2000
	s_add_u32 s0, s18, 0x160080
	v_lshl_add_u64 v[194:195], v[196:197], 0, s[80:81]
	s_addc_u32 s1, s19, 0
	s_add_i32 s2, s3, s24
	global_load_lds_dwordx4 v[194:195], off
	v_lshl_add_u64 v[194:195], s[0:1], 0, v[202:203]
	s_mov_b32 m0, s2
	s_nop 0
	global_load_lds_dwordx4 v[194:195], off
	v_lshl_add_u64 v[194:195], s[0:1], 0, v[208:209]
	s_add_i32 m0, s2, 0x2000
	s_nop 0
	global_load_lds_dwordx4 v[194:195], off
	v_lshl_add_u64 v[194:195], v[198:199], 0, s[80:81]
	s_mov_b32 m0, s31
	s_nop 0
	global_load_lds_dwordx4 v[194:195], off
	v_lshl_add_u64 v[194:195], v[200:201], 0, s[80:81]
	s_mov_b32 m0, s34
	s_nop 0
	global_load_lds_dwordx4 v[194:195], off
	s_waitcnt vmcnt(8)
	s_waitcnt lgkmcnt(0)
	s_barrier
	s_setprio 1
	s_waitcnt lgkmcnt(0)
	v_mfma_f32_16x16x32_bf16 v[62:65], v[78:81], v[146:149], v[62:65]
	v_mfma_f32_16x16x32_bf16 v[58:61], v[94:97], v[146:149], v[58:61]
	v_mfma_f32_16x16x32_bf16 v[46:49], v[78:81], v[166:169], v[46:49]
	v_mfma_f32_16x16x32_bf16 v[42:45], v[94:97], v[166:169], v[42:45]
	v_mfma_f32_16x16x32_bf16 v[30:33], v[78:81], v[178:181], v[30:33]
	v_mfma_f32_16x16x32_bf16 v[26:29], v[94:97], v[178:181], v[26:29]
	v_mfma_f32_16x16x32_bf16 v[14:17], v[78:81], v[186:189], v[14:17]
	v_mfma_f32_16x16x32_bf16 v[10:13], v[94:97], v[186:189], v[10:13]
	v_mfma_f32_16x16x32_bf16 v[62:65], v[82:85], v[158:161], v[62:65]
	v_mfma_f32_16x16x32_bf16 v[58:61], v[98:101], v[158:161], v[58:61]
	v_mfma_f32_16x16x32_bf16 v[46:49], v[82:85], v[174:177], v[46:49]
	v_mfma_f32_16x16x32_bf16 v[42:45], v[98:101], v[174:177], v[42:45]
	v_mfma_f32_16x16x32_bf16 v[30:33], v[82:85], v[182:185], v[30:33]
	v_mfma_f32_16x16x32_bf16 v[26:29], v[98:101], v[182:185], v[26:29]
	v_mfma_f32_16x16x32_bf16 v[14:17], v[82:85], v[190:193], v[14:17]
	v_mfma_f32_16x16x32_bf16 v[10:13], v[98:101], v[190:193], v[10:13]
	v_mfma_f32_16x16x32_bf16 v[54:57], v[106:109], v[146:149], v[54:57]
	v_mfma_f32_16x16x32_bf16 v[50:53], v[126:129], v[146:149], v[50:53]
	v_mfma_f32_16x16x32_bf16 v[38:41], v[106:109], v[166:169], v[38:41]
	v_mfma_f32_16x16x32_bf16 v[34:37], v[126:129], v[166:169], v[34:37]
	v_mfma_f32_16x16x32_bf16 v[22:25], v[106:109], v[178:181], v[22:25]
	v_mfma_f32_16x16x32_bf16 v[18:21], v[126:129], v[178:181], v[18:21]
	v_mfma_f32_16x16x32_bf16 v[6:9], v[106:109], v[186:189], v[6:9]
	v_mfma_f32_16x16x32_bf16 v[2:5], v[126:129], v[186:189], v[2:5]
	v_mfma_f32_16x16x32_bf16 v[54:57], v[110:113], v[158:161], v[54:57]
	v_mfma_f32_16x16x32_bf16 v[50:53], v[134:137], v[158:161], v[50:53]
	v_mfma_f32_16x16x32_bf16 v[38:41], v[110:113], v[174:177], v[38:41]
	v_mfma_f32_16x16x32_bf16 v[34:37], v[134:137], v[174:177], v[34:37]
	v_mfma_f32_16x16x32_bf16 v[22:25], v[110:113], v[182:185], v[22:25]
	v_mfma_f32_16x16x32_bf16 v[18:21], v[134:137], v[182:185], v[18:21]
	v_mfma_f32_16x16x32_bf16 v[6:9], v[110:113], v[190:193], v[6:9]
	v_mfma_f32_16x16x32_bf16 v[2:5], v[134:137], v[190:193], v[2:5]
	s_setprio 0
	s_barrier
	s_add_i32 s59, s59, 2
	s_add_u32 s49, s49, 0x100
	s_addc_u32 s58, s58, 0
	s_cmpk_gt_u32 s59, 0x55
	s_mov_b64 s[2:3], s[16:17]
	s_cbranch_scc0 .LBB0_970
	s_and_b64 vcc, exec, s[10:11]
	s_cbranch_vccz .LBB0_973
	s_barrier

.LBB0_990:
	s_add_u32 s4, s2, 0x100
	s_addc_u32 s5, s3, 0
	s_add_i32 s0, 0, 0x10000
	s_cmp_eq_u32 s59, 4
	s_cselect_b32 s21, s15, s5
	s_cselect_b32 s20, s14, s4
	s_cselect_b32 s19, s17, s58
	s_cselect_b32 s18, s16, s49
	s_add_i32 s33, 0, 0x14000
	v_add_u32_e32 v152, s0, v136
	v_add_u32_e32 v168, s33, v136
	ds_read_b128 v[140:143], v152
	ds_read_b128 v[144:147], v152 offset:1024
	ds_read_b128 v[148:151], v152 offset:2048
	ds_read_b128 v[152:155], v152 offset:3072
	ds_read_b128 v[156:159], v168
	ds_read_b128 v[160:163], v168 offset:1024
	ds_read_b128 v[164:167], v168 offset:2048
	ds_read_b128 v[168:171], v168 offset:3072
	v_lshl_add_u64 v[200:201], s[2:3], 0, v[132:133]
	s_add_i32 m0, s25, 0xc000
	ds_read_b128 v[172:175], v139
	ds_read_b128 v[176:179], v139 offset:1024
	ds_read_b128 v[180:183], v139 offset:2048
	ds_read_b128 v[184:187], v139 offset:3072
	ds_read_b128 v[188:191], v139 offset:4096
	ds_read_b128 v[192:195], v139 offset:5120
	ds_read_b128 v[196:199], v139 offset:6144
	ds_read_b128 v[208:211], v139 offset:7168
	global_load_lds_dwordx4 v[200:201], off
	v_lshl_add_u64 v[200:201], s[2:3], 0, v[134:135]
	s_add_i32 m0, s25, 0xe000
	s_nop 0
	global_load_lds_dwordx4 v[200:201], off
	s_waitcnt vmcnt(8)
	s_waitcnt lgkmcnt(0)
	s_barrier
	s_setprio 1
	s_waitcnt lgkmcnt(0)
	v_mfma_f32_16x16x32_bf16 v[126:129], v[140:143], v[172:175], v[126:129]
	v_mfma_f32_16x16x32_bf16 v[122:125], v[148:151], v[172:175], v[122:125]
	v_mfma_f32_16x16x32_bf16 v[118:121], v[140:143], v[180:183], v[118:121]
	v_mfma_f32_16x16x32_bf16 v[114:117], v[148:151], v[180:183], v[114:117]
	v_mfma_f32_16x16x32_bf16 v[106:109], v[140:143], v[188:191], v[106:109]
	v_mfma_f32_16x16x32_bf16 v[98:101], v[148:151], v[188:191], v[98:101]
	v_mfma_f32_16x16x32_bf16 v[90:93], v[140:143], v[196:199], v[90:93]
	v_mfma_f32_16x16x32_bf16 v[82:85], v[148:151], v[196:199], v[82:85]
	v_mfma_f32_16x16x32_bf16 v[126:129], v[144:147], v[176:179], v[126:129]
	v_mfma_f32_16x16x32_bf16 v[122:125], v[152:155], v[176:179], v[122:125]
	v_mfma_f32_16x16x32_bf16 v[118:121], v[144:147], v[184:187], v[118:121]
	v_mfma_f32_16x16x32_bf16 v[114:117], v[152:155], v[184:187], v[114:117]
	v_mfma_f32_16x16x32_bf16 v[106:109], v[144:147], v[192:195], v[106:109]
	v_mfma_f32_16x16x32_bf16 v[98:101], v[152:155], v[192:195], v[98:101]
	v_mfma_f32_16x16x32_bf16 v[90:93], v[144:147], v[208:211], v[90:93]
	v_mfma_f32_16x16x32_bf16 v[82:85], v[152:155], v[208:211], v[82:85]
	v_mfma_f32_16x16x32_bf16 v[110:113], v[156:159], v[172:175], v[110:113]
	v_mfma_f32_16x16x32_bf16 v[102:105], v[164:167], v[172:175], v[102:105]
	v_mfma_f32_16x16x32_bf16 v[94:97], v[156:159], v[180:183], v[94:97]
	v_mfma_f32_16x16x32_bf16 v[86:89], v[164:167], v[180:183], v[86:89]
	v_mfma_f32_16x16x32_bf16 v[78:81], v[156:159], v[188:191], v[78:81]
	v_mfma_f32_16x16x32_bf16 v[74:77], v[164:167], v[188:191], v[74:77]
	v_mfma_f32_16x16x32_bf16 v[70:73], v[156:159], v[196:199], v[70:73]
	v_mfma_f32_16x16x32_bf16 v[66:69], v[164:167], v[196:199], v[66:69]
	v_mfma_f32_16x16x32_bf16 v[110:113], v[160:163], v[176:179], v[110:113]
	v_mfma_f32_16x16x32_bf16 v[102:105], v[168:171], v[176:179], v[102:105]
	v_mfma_f32_16x16x32_bf16 v[94:97], v[160:163], v[184:187], v[94:97]
	v_mfma_f32_16x16x32_bf16 v[86:89], v[168:171], v[184:187], v[86:89]
	v_mfma_f32_16x16x32_bf16 v[78:81], v[160:163], v[192:195], v[78:81]
	v_mfma_f32_16x16x32_bf16 v[74:77], v[168:171], v[192:195], v[74:77]
	v_mfma_f32_16x16x32_bf16 v[70:73], v[160:163], v[208:211], v[70:73]
	v_mfma_f32_16x16x32_bf16 v[66:69], v[168:171], v[208:211], v[66:69]
	s_setprio 0
	s_barrier
	s_add_i32 s0, s0, s24
	v_lshl_add_u64 v[200:201], s[18:19], 0, v[202:203]
	s_mov_b32 m0, s0
	ds_read_b128 v[172:175], v139 offset:16384
	ds_read_b128 v[176:179], v139 offset:17408
	ds_read_b128 v[180:183], v139 offset:18432
	ds_read_b128 v[184:187], v139 offset:19456
	ds_read_b128 v[188:191], v139 offset:20480
	ds_read_b128 v[192:195], v139 offset:21504
	ds_read_b128 v[196:199], v139 offset:22528
	ds_read_b128 v[208:211], v139 offset:23552
	global_load_lds_dwordx4 v[200:201], off
	s_add_i32 m0, s0, 0x2000
	s_add_u32 s0, s18, 0x160000
	v_lshl_add_u64 v[204:205], s[18:19], 0, v[130:131]
	s_addc_u32 s1, s19, 0
	s_add_i32 s2, s33, s24
	global_load_lds_dwordx4 v[204:205], off
	v_lshl_add_u64 v[206:207], s[0:1], 0, v[202:203]
	s_mov_b32 m0, s2
	v_lshl_add_u64 v[212:213], s[20:21], 0, v[130:131]
	global_load_lds_dwordx4 v[206:207], off
	v_lshl_add_u64 v[206:207], s[0:1], 0, v[130:131]
	s_add_i32 m0, s2, 0x2000
	s_nop 0
	global_load_lds_dwordx4 v[206:207], off
	v_lshl_add_u64 v[206:207], s[20:21], 0, v[202:203]
	s_mov_b32 m0, s25
	s_nop 0
	global_load_lds_dwordx4 v[206:207], off
	s_mov_b32 m0, s26
	s_nop 0
	global_load_lds_dwordx4 v[212:213], off
	s_waitcnt vmcnt(8)
	s_waitcnt lgkmcnt(0)
	s_barrier
	s_setprio 1
	s_waitcnt lgkmcnt(0)
	v_mfma_f32_16x16x32_bf16 v[62:65], v[140:143], v[172:175], v[62:65]
	v_mfma_f32_16x16x32_bf16 v[58:61], v[148:151], v[172:175], v[58:61]
	v_mfma_f32_16x16x32_bf16 v[54:57], v[140:143], v[180:183], v[54:57]
	v_mfma_f32_16x16x32_bf16 v[50:53], v[148:151], v[180:183], v[50:53]
	v_mfma_f32_16x16x32_bf16 v[38:41], v[140:143], v[188:191], v[38:41]
	v_mfma_f32_16x16x32_bf16 v[34:37], v[148:151], v[188:191], v[34:37]
	v_mfma_f32_16x16x32_bf16 v[22:25], v[140:143], v[196:199], v[22:25]
	v_mfma_f32_16x16x32_bf16 v[18:21], v[148:151], v[196:199], v[18:21]
	v_mfma_f32_16x16x32_bf16 v[62:65], v[144:147], v[176:179], v[62:65]
	v_mfma_f32_16x16x32_bf16 v[58:61], v[152:155], v[176:179], v[58:61]
	v_mfma_f32_16x16x32_bf16 v[54:57], v[144:147], v[184:187], v[54:57]
	v_mfma_f32_16x16x32_bf16 v[50:53], v[152:155], v[184:187], v[50:53]
	v_mfma_f32_16x16x32_bf16 v[38:41], v[144:147], v[192:195], v[38:41]
	v_mfma_f32_16x16x32_bf16 v[34:37], v[152:155], v[192:195], v[34:37]
	v_mfma_f32_16x16x32_bf16 v[22:25], v[144:147], v[208:211], v[22:25]
	v_mfma_f32_16x16x32_bf16 v[18:21], v[152:155], v[208:211], v[18:21]
	v_mfma_f32_16x16x32_bf16 v[46:49], v[156:159], v[172:175], v[46:49]
	v_mfma_f32_16x16x32_bf16 v[42:45], v[164:167], v[172:175], v[42:45]
	v_mfma_f32_16x16x32_bf16 v[30:33], v[156:159], v[180:183], v[30:33]
	v_mfma_f32_16x16x32_bf16 v[26:29], v[164:167], v[180:183], v[26:29]
	v_mfma_f32_16x16x32_bf16 v[14:17], v[156:159], v[188:191], v[14:17]
	v_mfma_f32_16x16x32_bf16 v[10:13], v[164:167], v[188:191], v[10:13]
	v_mfma_f32_16x16x32_bf16 v[6:9], v[156:159], v[196:199], v[6:9]
	v_mfma_f32_16x16x32_bf16 v[2:5], v[164:167], v[196:199], v[2:5]
	v_mfma_f32_16x16x32_bf16 v[46:49], v[160:163], v[176:179], v[46:49]
	v_mfma_f32_16x16x32_bf16 v[42:45], v[168:171], v[176:179], v[42:45]
	v_mfma_f32_16x16x32_bf16 v[30:33], v[160:163], v[184:187], v[30:33]
	v_mfma_f32_16x16x32_bf16 v[26:29], v[168:171], v[184:187], v[26:29]
	v_mfma_f32_16x16x32_bf16 v[14:17], v[160:163], v[192:195], v[14:17]
	v_mfma_f32_16x16x32_bf16 v[10:13], v[168:171], v[192:195], v[10:13]
	v_mfma_f32_16x16x32_bf16 v[6:9], v[160:163], v[208:211], v[6:9]
	v_mfma_f32_16x16x32_bf16 v[2:5], v[168:171], v[208:211], v[2:5]
	s_setprio 0
	s_barrier
	s_add_i32 s2, 0, 0x18000
	s_add_i32 s3, 0, 0x1c000
	v_add_u32_e32 v152, s2, v136
	v_add_u32_e32 v168, s3, v136
	ds_read_b128 v[140:143], v152
	ds_read_b128 v[144:147], v152 offset:1024
	ds_read_b128 v[148:151], v152 offset:2048
	ds_read_b128 v[152:155], v152 offset:3072
	ds_read_b128 v[156:159], v168
	ds_read_b128 v[160:163], v168 offset:1024
	ds_read_b128 v[164:167], v168 offset:2048
	ds_read_b128 v[168:171], v168 offset:3072
	s_add_u32 s0, s20, 0x160000
	s_addc_u32 s1, s21, 0
	s_mov_b32 m0, s27
	v_lshl_add_u64 v[214:215], s[0:1], 0, v[202:203]
	ds_read_b128 v[172:175], v139 offset:32768
	ds_read_b128 v[176:179], v139 offset:33792
	ds_read_b128 v[180:183], v139 offset:34816
	ds_read_b128 v[184:187], v139 offset:35840
	ds_read_b128 v[188:191], v139 offset:36864
	ds_read_b128 v[192:195], v139 offset:37888
	ds_read_b128 v[196:199], v139 offset:38912
	ds_read_b128 v[208:211], v139 offset:39936
	global_load_lds_dwordx4 v[214:215], off
	v_lshl_add_u64 v[214:215], s[0:1], 0, v[130:131]
	s_mov_b32 m0, s28
	s_nop 0
	global_load_lds_dwordx4 v[214:215], off
	s_waitcnt vmcnt(8)
	s_waitcnt lgkmcnt(0)
	s_barrier
	s_setprio 1
	s_waitcnt lgkmcnt(0)
	v_mfma_f32_16x16x32_bf16 v[126:129], v[140:143], v[172:175], v[126:129]
	v_mfma_f32_16x16x32_bf16 v[122:125], v[148:151], v[172:175], v[122:125]
	v_mfma_f32_16x16x32_bf16 v[118:121], v[140:143], v[180:183], v[118:121]
	v_mfma_f32_16x16x32_bf16 v[114:117], v[148:151], v[180:183], v[114:117]
	v_mfma_f32_16x16x32_bf16 v[106:109], v[140:143], v[188:191], v[106:109]
	v_mfma_f32_16x16x32_bf16 v[98:101], v[148:151], v[188:191], v[98:101]
	v_mfma_f32_16x16x32_bf16 v[90:93], v[140:143], v[196:199], v[90:93]
	v_mfma_f32_16x16x32_bf16 v[82:85], v[148:151], v[196:199], v[82:85]
	v_mfma_f32_16x16x32_bf16 v[126:129], v[144:147], v[176:179], v[126:129]
	v_mfma_f32_16x16x32_bf16 v[122:125], v[152:155], v[176:179], v[122:125]
	v_mfma_f32_16x16x32_bf16 v[118:121], v[144:147], v[184:187], v[118:121]
	v_mfma_f32_16x16x32_bf16 v[114:117], v[152:155], v[184:187], v[114:117]
	v_mfma_f32_16x16x32_bf16 v[106:109], v[144:147], v[192:195], v[106:109]
	v_mfma_f32_16x16x32_bf16 v[98:101], v[152:155], v[192:195], v[98:101]
	v_mfma_f32_16x16x32_bf16 v[90:93], v[144:147], v[208:211], v[90:93]
	v_mfma_f32_16x16x32_bf16 v[82:85], v[152:155], v[208:211], v[82:85]
	v_mfma_f32_16x16x32_bf16 v[110:113], v[156:159], v[172:175], v[110:113]
	v_mfma_f32_16x16x32_bf16 v[102:105], v[164:167], v[172:175], v[102:105]
	v_mfma_f32_16x16x32_bf16 v[94:97], v[156:159], v[180:183], v[94:97]
	v_mfma_f32_16x16x32_bf16 v[86:89], v[164:167], v[180:183], v[86:89]
	v_mfma_f32_16x16x32_bf16 v[78:81], v[156:159], v[188:191], v[78:81]
	v_mfma_f32_16x16x32_bf16 v[74:77], v[164:167], v[188:191], v[74:77]
	v_mfma_f32_16x16x32_bf16 v[70:73], v[156:159], v[196:199], v[70:73]
	v_mfma_f32_16x16x32_bf16 v[66:69], v[164:167], v[196:199], v[66:69]
	v_mfma_f32_16x16x32_bf16 v[110:113], v[160:163], v[176:179], v[110:113]
	v_mfma_f32_16x16x32_bf16 v[102:105], v[168:171], v[176:179], v[102:105]
	v_mfma_f32_16x16x32_bf16 v[94:97], v[160:163], v[184:187], v[94:97]
	v_mfma_f32_16x16x32_bf16 v[86:89], v[168:171], v[184:187], v[86:89]
	v_mfma_f32_16x16x32_bf16 v[78:81], v[160:163], v[192:195], v[78:81]
	v_mfma_f32_16x16x32_bf16 v[74:77], v[168:171], v[192:195], v[74:77]
	v_mfma_f32_16x16x32_bf16 v[70:73], v[160:163], v[208:211], v[70:73]
	v_mfma_f32_16x16x32_bf16 v[66:69], v[168:171], v[208:211], v[66:69]
	s_setprio 0
	s_barrier
	s_add_i32 s0, s2, s24
	v_lshl_add_u64 v[200:201], v[200:201], 0, s[80:81]
	s_mov_b32 m0, s0
	ds_read_b128 v[172:175], v139 offset:49152
	ds_read_b128 v[176:179], v139 offset:50176
	ds_read_b128 v[180:183], v139 offset:51200
	ds_read_b128 v[184:187], v139 offset:52224
	ds_read_b128 v[188:191], v139 offset:53248
	ds_read_b128 v[192:195], v139 offset:54272
	ds_read_b128 v[196:199], v139 offset:55296
	ds_read_b128 v[208:211], v139 offset:56320
	global_load_lds_dwordx4 v[200:201], off
	s_add_i32 m0, s0, 0x2000
	s_add_u32 s0, s18, 0x160080
	v_lshl_add_u64 v[200:201], v[204:205], 0, s[80:81]
	s_addc_u32 s1, s19, 0
	s_add_i32 s2, s3, s24
	global_load_lds_dwordx4 v[200:201], off
	v_lshl_add_u64 v[200:201], s[0:1], 0, v[202:203]
	s_mov_b32 m0, s2
	s_nop 0
	global_load_lds_dwordx4 v[200:201], off
	v_lshl_add_u64 v[200:201], s[0:1], 0, v[130:131]
	s_add_i32 m0, s2, 0x2000
	s_nop 0
	global_load_lds_dwordx4 v[200:201], off
	v_lshl_add_u64 v[200:201], v[206:207], 0, s[80:81]
	s_mov_b32 m0, s29
	s_nop 0
	global_load_lds_dwordx4 v[200:201], off
	v_lshl_add_u64 v[200:201], v[212:213], 0, s[80:81]
	s_mov_b32 m0, s30
	s_nop 0
	global_load_lds_dwordx4 v[200:201], off
	s_waitcnt vmcnt(8)
	s_waitcnt lgkmcnt(0)
	s_barrier
	s_setprio 1
	s_waitcnt lgkmcnt(0)
	v_mfma_f32_16x16x32_bf16 v[62:65], v[140:143], v[172:175], v[62:65]
	v_mfma_f32_16x16x32_bf16 v[58:61], v[148:151], v[172:175], v[58:61]
	v_mfma_f32_16x16x32_bf16 v[54:57], v[140:143], v[180:183], v[54:57]
	v_mfma_f32_16x16x32_bf16 v[50:53], v[148:151], v[180:183], v[50:53]
	v_mfma_f32_16x16x32_bf16 v[38:41], v[140:143], v[188:191], v[38:41]
	v_mfma_f32_16x16x32_bf16 v[34:37], v[148:151], v[188:191], v[34:37]
	v_mfma_f32_16x16x32_bf16 v[22:25], v[140:143], v[196:199], v[22:25]
	v_mfma_f32_16x16x32_bf16 v[18:21], v[148:151], v[196:199], v[18:21]
	v_mfma_f32_16x16x32_bf16 v[62:65], v[144:147], v[176:179], v[62:65]
	v_mfma_f32_16x16x32_bf16 v[58:61], v[152:155], v[176:179], v[58:61]
	v_mfma_f32_16x16x32_bf16 v[54:57], v[144:147], v[184:187], v[54:57]
	v_mfma_f32_16x16x32_bf16 v[50:53], v[152:155], v[184:187], v[50:53]
	v_mfma_f32_16x16x32_bf16 v[38:41], v[144:147], v[192:195], v[38:41]
	v_mfma_f32_16x16x32_bf16 v[34:37], v[152:155], v[192:195], v[34:37]
	v_mfma_f32_16x16x32_bf16 v[22:25], v[144:147], v[208:211], v[22:25]
	v_mfma_f32_16x16x32_bf16 v[18:21], v[152:155], v[208:211], v[18:21]
	v_mfma_f32_16x16x32_bf16 v[46:49], v[156:159], v[172:175], v[46:49]
	v_mfma_f32_16x16x32_bf16 v[42:45], v[164:167], v[172:175], v[42:45]
	v_mfma_f32_16x16x32_bf16 v[30:33], v[156:159], v[180:183], v[30:33]
	v_mfma_f32_16x16x32_bf16 v[26:29], v[164:167], v[180:183], v[26:29]
	v_mfma_f32_16x16x32_bf16 v[14:17], v[156:159], v[188:191], v[14:17]
	v_mfma_f32_16x16x32_bf16 v[10:13], v[164:167], v[188:191], v[10:13]
	v_mfma_f32_16x16x32_bf16 v[6:9], v[156:159], v[196:199], v[6:9]
	v_mfma_f32_16x16x32_bf16 v[2:5], v[164:167], v[196:199], v[2:5]
	v_mfma_f32_16x16x32_bf16 v[46:49], v[160:163], v[176:179], v[46:49]
	v_mfma_f32_16x16x32_bf16 v[42:45], v[168:171], v[176:179], v[42:45]
	v_mfma_f32_16x16x32_bf16 v[30:33], v[160:163], v[184:187], v[30:33]
	v_mfma_f32_16x16x32_bf16 v[26:29], v[168:171], v[184:187], v[26:29]
	v_mfma_f32_16x16x32_bf16 v[14:17], v[160:163], v[192:195], v[14:17]
	v_mfma_f32_16x16x32_bf16 v[10:13], v[168:171], v[192:195], v[10:13]
	v_mfma_f32_16x16x32_bf16 v[6:9], v[160:163], v[208:211], v[6:9]
	v_mfma_f32_16x16x32_bf16 v[2:5], v[168:171], v[208:211], v[2:5]
	s_setprio 0
	s_barrier
	s_add_i32 s59, s59, 2
	s_add_u32 s49, s49, 0x100
	s_addc_u32 s58, s58, 0
	s_cmp_gt_u32 s59, 5
	s_mov_b64 s[2:3], s[4:5]
	s_cbranch_scc0 .LBB0_990
	s_and_b64 vcc, exec, s[10:11]
	s_cbranch_vccz .LBB0_993
	s_barrier

.LBB0_1115:
	s_add_u32 s0, s22, 0xfff80080
	s_addc_u32 s1, s23, -1
	s_add_i32 s33, 0, 0x10000
	s_cmp_eq_u32 s58, 28
	s_cselect_b32 s5, s17, s1
	s_cselect_b32 s4, s39, s0
	v_add_u32_e32 v143, s33, v145
	s_cselect_b32 s3, s15, s49
	s_cselect_b32 s2, s40, s41
	s_add_i32 s55, 0, 0x14000
	ds_read_b128 v[148:151], v143
	ds_read_b128 v[152:155], v143 offset:1024
	ds_read_b128 v[156:159], v143 offset:2048
	ds_read_b128 v[160:163], v143 offset:3072
	v_add_u32_e32 v143, s55, v145
	ds_read_b128 v[164:167], v143
	ds_read_b128 v[168:171], v143 offset:1024
	ds_read_b128 v[172:175], v143 offset:2048
	ds_read_b128 v[176:179], v143 offset:3072
	v_lshl_add_u64 v[200:201], s[22:23], 0, v[138:139]
	s_add_i32 m0, s27, 0xc000
	ds_read_b128 v[180:183], v147
	ds_read_b128 v[184:187], v147 offset:1024
	ds_read_b128 v[188:191], v147 offset:2048
	ds_read_b128 v[192:195], v147 offset:3072
	ds_read_b128 v[196:199], v147 offset:4096
	ds_read_b128 v[208:211], v147 offset:5120
	ds_read_b128 v[212:215], v147 offset:6144
	ds_read_b128 v[216:219], v147 offset:7168
	global_load_lds_dwordx4 v[200:201], off
	v_lshl_add_u64 v[200:201], s[22:23], 0, v[140:141]
	s_add_i32 m0, s27, 0xe000
	s_nop 0
	global_load_lds_dwordx4 v[200:201], off
	s_waitcnt vmcnt(8)
	s_waitcnt lgkmcnt(0)
	s_barrier
	s_setprio 1
	s_waitcnt lgkmcnt(0)
	v_mfma_f32_16x16x32_bf16 v[126:129], v[148:151], v[180:183], v[126:129]
	v_mfma_f32_16x16x32_bf16 v[122:125], v[156:159], v[180:183], v[122:125]
	v_mfma_f32_16x16x32_bf16 v[110:113], v[148:151], v[188:191], v[110:113]
	v_mfma_f32_16x16x32_bf16 v[106:109], v[156:159], v[188:191], v[106:109]
	v_mfma_f32_16x16x32_bf16 v[94:97], v[148:151], v[196:199], v[94:97]
	v_mfma_f32_16x16x32_bf16 v[90:93], v[156:159], v[196:199], v[90:93]
	v_mfma_f32_16x16x32_bf16 v[78:81], v[148:151], v[212:215], v[78:81]
	v_mfma_f32_16x16x32_bf16 v[74:77], v[156:159], v[212:215], v[74:77]
	v_mfma_f32_16x16x32_bf16 v[126:129], v[152:155], v[184:187], v[126:129]
	v_mfma_f32_16x16x32_bf16 v[122:125], v[160:163], v[184:187], v[122:125]
	v_mfma_f32_16x16x32_bf16 v[110:113], v[152:155], v[192:195], v[110:113]
	v_mfma_f32_16x16x32_bf16 v[106:109], v[160:163], v[192:195], v[106:109]
	v_mfma_f32_16x16x32_bf16 v[94:97], v[152:155], v[208:211], v[94:97]
	v_mfma_f32_16x16x32_bf16 v[90:93], v[160:163], v[208:211], v[90:93]
	v_mfma_f32_16x16x32_bf16 v[78:81], v[152:155], v[216:219], v[78:81]
	v_mfma_f32_16x16x32_bf16 v[74:77], v[160:163], v[216:219], v[74:77]
	v_mfma_f32_16x16x32_bf16 v[118:121], v[164:167], v[180:183], v[118:121]
	v_mfma_f32_16x16x32_bf16 v[114:117], v[172:175], v[180:183], v[114:117]
	v_mfma_f32_16x16x32_bf16 v[102:105], v[164:167], v[188:191], v[102:105]
	v_mfma_f32_16x16x32_bf16 v[98:101], v[172:175], v[188:191], v[98:101]
	v_mfma_f32_16x16x32_bf16 v[86:89], v[164:167], v[196:199], v[86:89]
	v_mfma_f32_16x16x32_bf16 v[82:85], v[172:175], v[196:199], v[82:85]
	v_mfma_f32_16x16x32_bf16 v[70:73], v[164:167], v[212:215], v[70:73]
	v_mfma_f32_16x16x32_bf16 v[66:69], v[172:175], v[212:215], v[66:69]
	v_mfma_f32_16x16x32_bf16 v[118:121], v[168:171], v[184:187], v[118:121]
	v_mfma_f32_16x16x32_bf16 v[114:117], v[176:179], v[184:187], v[114:117]
	v_mfma_f32_16x16x32_bf16 v[102:105], v[168:171], v[192:195], v[102:105]
	v_mfma_f32_16x16x32_bf16 v[98:101], v[176:179], v[192:195], v[98:101]
	v_mfma_f32_16x16x32_bf16 v[86:89], v[168:171], v[208:211], v[86:89]
	v_mfma_f32_16x16x32_bf16 v[82:85], v[176:179], v[208:211], v[82:85]
	v_mfma_f32_16x16x32_bf16 v[70:73], v[168:171], v[216:219], v[70:73]
	v_mfma_f32_16x16x32_bf16 v[66:69], v[176:179], v[216:219], v[66:69]
	s_setprio 0
	s_barrier
	s_add_i32 s0, s33, s26
	v_lshl_add_u64 v[200:201], s[2:3], 0, v[134:135]
	s_mov_b32 m0, s0
	ds_read_b128 v[180:183], v147 offset:16384
	ds_read_b128 v[184:187], v147 offset:17408
	ds_read_b128 v[188:191], v147 offset:18432
	ds_read_b128 v[192:195], v147 offset:19456
	ds_read_b128 v[196:199], v147 offset:20480
	ds_read_b128 v[208:211], v147 offset:21504
	ds_read_b128 v[212:215], v147 offset:22528
	ds_read_b128 v[216:219], v147 offset:23552
	global_load_lds_dwordx4 v[200:201], off
	s_add_i32 m0, s0, 0x2000
	s_add_u32 s0, s2, 0x80000
	v_lshl_add_u64 v[204:205], s[2:3], 0, v[130:131]
	s_addc_u32 s1, s3, 0
	s_add_i32 s33, s55, s26
	global_load_lds_dwordx4 v[204:205], off
	v_lshl_add_u64 v[206:207], s[0:1], 0, v[134:135]
	s_mov_b32 m0, s33
	v_lshl_add_u64 v[220:221], s[4:5], 0, v[132:133]
	global_load_lds_dwordx4 v[206:207], off
	v_lshl_add_u64 v[206:207], s[0:1], 0, v[130:131]
	s_add_i32 m0, s33, 0x2000
	s_nop 0
	global_load_lds_dwordx4 v[206:207], off
	v_lshl_add_u64 v[206:207], s[4:5], 0, v[136:137]
	s_mov_b32 m0, s27
	s_nop 0
	global_load_lds_dwordx4 v[206:207], off
	s_mov_b32 m0, s28
	s_nop 0
	global_load_lds_dwordx4 v[220:221], off
	s_waitcnt vmcnt(8)
	s_waitcnt lgkmcnt(0)
	s_barrier
	s_setprio 1
	s_waitcnt lgkmcnt(0)
	v_mfma_f32_16x16x32_bf16 v[62:65], v[148:151], v[180:183], v[62:65]
	v_mfma_f32_16x16x32_bf16 v[58:61], v[156:159], v[180:183], v[58:61]
	v_mfma_f32_16x16x32_bf16 v[46:49], v[148:151], v[188:191], v[46:49]
	v_mfma_f32_16x16x32_bf16 v[42:45], v[156:159], v[188:191], v[42:45]
	v_mfma_f32_16x16x32_bf16 v[30:33], v[148:151], v[196:199], v[30:33]
	v_mfma_f32_16x16x32_bf16 v[26:29], v[156:159], v[196:199], v[26:29]
	v_mfma_f32_16x16x32_bf16 v[14:17], v[148:151], v[212:215], v[14:17]
	v_mfma_f32_16x16x32_bf16 v[10:13], v[156:159], v[212:215], v[10:13]
	v_mfma_f32_16x16x32_bf16 v[62:65], v[152:155], v[184:187], v[62:65]
	v_mfma_f32_16x16x32_bf16 v[58:61], v[160:163], v[184:187], v[58:61]
	v_mfma_f32_16x16x32_bf16 v[46:49], v[152:155], v[192:195], v[46:49]
	v_mfma_f32_16x16x32_bf16 v[42:45], v[160:163], v[192:195], v[42:45]
	v_mfma_f32_16x16x32_bf16 v[30:33], v[152:155], v[208:211], v[30:33]
	v_mfma_f32_16x16x32_bf16 v[26:29], v[160:163], v[208:211], v[26:29]
	v_mfma_f32_16x16x32_bf16 v[14:17], v[152:155], v[216:219], v[14:17]
	v_mfma_f32_16x16x32_bf16 v[10:13], v[160:163], v[216:219], v[10:13]
	v_mfma_f32_16x16x32_bf16 v[54:57], v[164:167], v[180:183], v[54:57]
	v_mfma_f32_16x16x32_bf16 v[50:53], v[172:175], v[180:183], v[50:53]
	v_mfma_f32_16x16x32_bf16 v[38:41], v[164:167], v[188:191], v[38:41]
	v_mfma_f32_16x16x32_bf16 v[34:37], v[172:175], v[188:191], v[34:37]
	v_mfma_f32_16x16x32_bf16 v[22:25], v[164:167], v[196:199], v[22:25]
	v_mfma_f32_16x16x32_bf16 v[18:21], v[172:175], v[196:199], v[18:21]
	v_mfma_f32_16x16x32_bf16 v[6:9], v[164:167], v[212:215], v[6:9]
	v_mfma_f32_16x16x32_bf16 v[2:5], v[172:175], v[212:215], v[2:5]
	v_mfma_f32_16x16x32_bf16 v[54:57], v[168:171], v[184:187], v[54:57]
	v_mfma_f32_16x16x32_bf16 v[50:53], v[176:179], v[184:187], v[50:53]
	v_mfma_f32_16x16x32_bf16 v[38:41], v[168:171], v[192:195], v[38:41]
	v_mfma_f32_16x16x32_bf16 v[34:37], v[176:179], v[192:195], v[34:37]
	v_mfma_f32_16x16x32_bf16 v[22:25], v[168:171], v[208:211], v[22:25]
	v_mfma_f32_16x16x32_bf16 v[18:21], v[176:179], v[208:211], v[18:21]
	v_mfma_f32_16x16x32_bf16 v[6:9], v[168:171], v[216:219], v[6:9]
	v_mfma_f32_16x16x32_bf16 v[2:5], v[176:179], v[216:219], v[2:5]
	s_setprio 0
	s_barrier
	s_add_i32 s33, 0, 0x18000
	v_add_u32_e32 v143, s33, v145
	s_add_i32 s55, 0, 0x1c000
	ds_read_b128 v[148:151], v143
	ds_read_b128 v[152:155], v143 offset:1024
	ds_read_b128 v[156:159], v143 offset:2048
	ds_read_b128 v[160:163], v143 offset:3072
	v_add_u32_e32 v143, s55, v145
	ds_read_b128 v[164:167], v143
	ds_read_b128 v[168:171], v143 offset:1024
	ds_read_b128 v[172:175], v143 offset:2048
	ds_read_b128 v[176:179], v143 offset:3072
	s_add_u32 s0, s4, 0x80000
	s_addc_u32 s1, s5, 0
	s_mov_b32 m0, s29
	v_lshl_add_u64 v[222:223], s[0:1], 0, v[136:137]
	ds_read_b128 v[180:183], v147 offset:32768
	ds_read_b128 v[184:187], v147 offset:33792
	ds_read_b128 v[188:191], v147 offset:34816
	ds_read_b128 v[192:195], v147 offset:35840
	ds_read_b128 v[196:199], v147 offset:36864
	ds_read_b128 v[208:211], v147 offset:37888
	ds_read_b128 v[212:215], v147 offset:38912
	ds_read_b128 v[216:219], v147 offset:39936
	global_load_lds_dwordx4 v[222:223], off
	v_lshl_add_u64 v[222:223], s[0:1], 0, v[132:133]
	s_mov_b32 m0, s30
	s_nop 0
	global_load_lds_dwordx4 v[222:223], off
	s_waitcnt vmcnt(8)
	s_waitcnt lgkmcnt(0)
	s_barrier
	s_setprio 1
	s_waitcnt lgkmcnt(0)
	v_mfma_f32_16x16x32_bf16 v[126:129], v[148:151], v[180:183], v[126:129]
	v_mfma_f32_16x16x32_bf16 v[122:125], v[156:159], v[180:183], v[122:125]
	v_mfma_f32_16x16x32_bf16 v[110:113], v[148:151], v[188:191], v[110:113]
	v_mfma_f32_16x16x32_bf16 v[106:109], v[156:159], v[188:191], v[106:109]
	v_mfma_f32_16x16x32_bf16 v[94:97], v[148:151], v[196:199], v[94:97]
	v_mfma_f32_16x16x32_bf16 v[90:93], v[156:159], v[196:199], v[90:93]
	v_mfma_f32_16x16x32_bf16 v[78:81], v[148:151], v[212:215], v[78:81]
	v_mfma_f32_16x16x32_bf16 v[74:77], v[156:159], v[212:215], v[74:77]
	v_mfma_f32_16x16x32_bf16 v[126:129], v[152:155], v[184:187], v[126:129]
	v_mfma_f32_16x16x32_bf16 v[122:125], v[160:163], v[184:187], v[122:125]
	v_mfma_f32_16x16x32_bf16 v[110:113], v[152:155], v[192:195], v[110:113]
	v_mfma_f32_16x16x32_bf16 v[106:109], v[160:163], v[192:195], v[106:109]
	v_mfma_f32_16x16x32_bf16 v[94:97], v[152:155], v[208:211], v[94:97]
	v_mfma_f32_16x16x32_bf16 v[90:93], v[160:163], v[208:211], v[90:93]
	v_mfma_f32_16x16x32_bf16 v[78:81], v[152:155], v[216:219], v[78:81]
	v_mfma_f32_16x16x32_bf16 v[74:77], v[160:163], v[216:219], v[74:77]
	v_mfma_f32_16x16x32_bf16 v[118:121], v[164:167], v[180:183], v[118:121]
	v_mfma_f32_16x16x32_bf16 v[114:117], v[172:175], v[180:183], v[114:117]
	v_mfma_f32_16x16x32_bf16 v[102:105], v[164:167], v[188:191], v[102:105]
	v_mfma_f32_16x16x32_bf16 v[98:101], v[172:175], v[188:191], v[98:101]
	v_mfma_f32_16x16x32_bf16 v[86:89], v[164:167], v[196:199], v[86:89]
	v_mfma_f32_16x16x32_bf16 v[82:85], v[172:175], v[196:199], v[82:85]
	v_mfma_f32_16x16x32_bf16 v[70:73], v[164:167], v[212:215], v[70:73]
	v_mfma_f32_16x16x32_bf16 v[66:69], v[172:175], v[212:215], v[66:69]
	v_mfma_f32_16x16x32_bf16 v[118:121], v[168:171], v[184:187], v[118:121]
	v_mfma_f32_16x16x32_bf16 v[114:117], v[176:179], v[184:187], v[114:117]
	v_mfma_f32_16x16x32_bf16 v[102:105], v[168:171], v[192:195], v[102:105]
	v_mfma_f32_16x16x32_bf16 v[98:101], v[176:179], v[192:195], v[98:101]
	v_mfma_f32_16x16x32_bf16 v[86:89], v[168:171], v[208:211], v[86:89]
	v_mfma_f32_16x16x32_bf16 v[82:85], v[176:179], v[208:211], v[82:85]
	v_mfma_f32_16x16x32_bf16 v[70:73], v[168:171], v[216:219], v[70:73]
	v_mfma_f32_16x16x32_bf16 v[66:69], v[176:179], v[216:219], v[66:69]
	s_setprio 0
	s_barrier
	s_add_i32 s0, s33, s26
	v_lshl_add_u64 v[200:201], v[200:201], 0, s[80:81]
	s_mov_b32 m0, s0
	ds_read_b128 v[180:183], v147 offset:49152
	ds_read_b128 v[184:187], v147 offset:50176
	ds_read_b128 v[188:191], v147 offset:51200
	ds_read_b128 v[192:195], v147 offset:52224
	ds_read_b128 v[196:199], v147 offset:53248
	ds_read_b128 v[208:211], v147 offset:54272
	ds_read_b128 v[212:215], v147 offset:55296
	ds_read_b128 v[216:219], v147 offset:56320
	global_load_lds_dwordx4 v[200:201], off
	s_add_i32 m0, s0, 0x2000
	s_add_u32 s0, s2, 0x80080
	v_lshl_add_u64 v[200:201], v[204:205], 0, s[80:81]
	s_addc_u32 s1, s3, 0
	s_add_i32 s2, s55, s26
	global_load_lds_dwordx4 v[200:201], off
	v_lshl_add_u64 v[200:201], s[0:1], 0, v[134:135]
	s_mov_b32 m0, s2
	s_nop 0
	global_load_lds_dwordx4 v[200:201], off
	v_lshl_add_u64 v[200:201], s[0:1], 0, v[130:131]
	s_add_i32 m0, s2, 0x2000
	s_nop 0
	global_load_lds_dwordx4 v[200:201], off
	v_lshl_add_u64 v[200:201], v[206:207], 0, s[80:81]
	s_mov_b32 m0, s34
	s_nop 0
	global_load_lds_dwordx4 v[200:201], off
	v_lshl_add_u64 v[200:201], v[220:221], 0, s[80:81]
	s_mov_b32 m0, s35
	s_nop 0
	global_load_lds_dwordx4 v[200:201], off
	s_waitcnt vmcnt(8)
	s_waitcnt lgkmcnt(0)
	s_barrier
	s_setprio 1
	s_waitcnt lgkmcnt(0)
	v_mfma_f32_16x16x32_bf16 v[62:65], v[148:151], v[180:183], v[62:65]
	v_mfma_f32_16x16x32_bf16 v[58:61], v[156:159], v[180:183], v[58:61]
	v_mfma_f32_16x16x32_bf16 v[46:49], v[148:151], v[188:191], v[46:49]
	v_mfma_f32_16x16x32_bf16 v[42:45], v[156:159], v[188:191], v[42:45]
	v_mfma_f32_16x16x32_bf16 v[30:33], v[148:151], v[196:199], v[30:33]
	v_mfma_f32_16x16x32_bf16 v[26:29], v[156:159], v[196:199], v[26:29]
	v_mfma_f32_16x16x32_bf16 v[14:17], v[148:151], v[212:215], v[14:17]
	v_mfma_f32_16x16x32_bf16 v[10:13], v[156:159], v[212:215], v[10:13]
	v_mfma_f32_16x16x32_bf16 v[62:65], v[152:155], v[184:187], v[62:65]
	v_mfma_f32_16x16x32_bf16 v[58:61], v[160:163], v[184:187], v[58:61]
	v_mfma_f32_16x16x32_bf16 v[46:49], v[152:155], v[192:195], v[46:49]
	v_mfma_f32_16x16x32_bf16 v[42:45], v[160:163], v[192:195], v[42:45]
	v_mfma_f32_16x16x32_bf16 v[30:33], v[152:155], v[208:211], v[30:33]
	v_mfma_f32_16x16x32_bf16 v[26:29], v[160:163], v[208:211], v[26:29]
	v_mfma_f32_16x16x32_bf16 v[14:17], v[152:155], v[216:219], v[14:17]
	v_mfma_f32_16x16x32_bf16 v[10:13], v[160:163], v[216:219], v[10:13]
	v_mfma_f32_16x16x32_bf16 v[54:57], v[164:167], v[180:183], v[54:57]
	v_mfma_f32_16x16x32_bf16 v[50:53], v[172:175], v[180:183], v[50:53]
	v_mfma_f32_16x16x32_bf16 v[38:41], v[164:167], v[188:191], v[38:41]
	v_mfma_f32_16x16x32_bf16 v[34:37], v[172:175], v[188:191], v[34:37]
	v_mfma_f32_16x16x32_bf16 v[22:25], v[164:167], v[196:199], v[22:25]
	v_mfma_f32_16x16x32_bf16 v[18:21], v[172:175], v[196:199], v[18:21]
	v_mfma_f32_16x16x32_bf16 v[6:9], v[164:167], v[212:215], v[6:9]
	v_mfma_f32_16x16x32_bf16 v[2:5], v[172:175], v[212:215], v[2:5]
	v_mfma_f32_16x16x32_bf16 v[54:57], v[168:171], v[184:187], v[54:57]
	v_mfma_f32_16x16x32_bf16 v[50:53], v[176:179], v[184:187], v[50:53]
	v_mfma_f32_16x16x32_bf16 v[38:41], v[168:171], v[192:195], v[38:41]
	v_mfma_f32_16x16x32_bf16 v[34:37], v[176:179], v[192:195], v[34:37]
	v_mfma_f32_16x16x32_bf16 v[22:25], v[168:171], v[208:211], v[22:25]
	v_mfma_f32_16x16x32_bf16 v[18:21], v[176:179], v[208:211], v[18:21]
	v_mfma_f32_16x16x32_bf16 v[6:9], v[168:171], v[216:219], v[6:9]
	v_mfma_f32_16x16x32_bf16 v[2:5], v[176:179], v[216:219], v[2:5]
	s_setprio 0
	s_barrier
	s_add_i32 s58, s58, 2
	s_add_u32 s22, s22, 0x100
	s_addc_u32 s23, s23, 0
	s_add_u32 s41, s41, 0x100
	s_addc_u32 s49, s49, 0
	s_cmp_gt_u32 s58, 29
	s_cbranch_scc0 .LBB0_1115
	s_and_b64 vcc, exec, s[10:11]
	s_cbranch_vccz .LBB0_1118
	s_barrier

.LBB0_1242:
	s_add_u32 s28, s18, s4
	s_addc_u32 s29, s19, s5
	s_add_u32 s24, s28, 0x100
	s_addc_u32 s25, s29, 0
	s_and_b64 s[0:1], s[2:3], exec
	s_cselect_b32 s25, s49, s25
	s_cselect_b32 s24, s58, s24
	s_add_u32 s0, s20, s4
	s_addc_u32 s1, s21, s5
	s_add_u32 s4, s0, 0x100
	s_addc_u32 s5, s1, 0
	s_add_i32 s55, 0, 0x10000
	s_and_b64 s[0:1], s[2:3], exec
	s_cselect_b32 s27, s59, s5
	s_cselect_b32 s26, s60, s4
	s_add_i32 s0, 0, 0x14000
	s_add_u32 s30, s28, 0x20080
	s_addc_u32 s31, s29, 0
	s_add_i32 s57, s55, s36
	s_add_i32 m0, s37, 0xc000
	s_add_i32 s1, s37, 0xe000
	s_add_i32 s63, s57, 0x2000
	v_add_u32_e32 v138, s55, v141
	s_add_u32 s28, s26, 0x10000
	ds_read_b128 v[144:147], v138
	ds_read_b128 v[148:151], v138 offset:1024
	ds_read_b128 v[152:155], v138 offset:2048
	ds_read_b128 v[156:159], v138 offset:3072
	v_add_u32_e32 v138, s0, v141
	s_addc_u32 s29, s27, 0
	s_add_i32 s33, s0, s36
	ds_read_b128 v[160:163], v138
	ds_read_b128 v[164:167], v138 offset:1024
	ds_read_b128 v[168:171], v138 offset:2048
	ds_read_b128 v[172:175], v138 offset:3072
	s_add_i32 s56, s33, 0x2000
	s_add_i32 vcc_lo, 0, 0x18000
	s_add_i32 vcc_hi, 0, 0x1c000
	s_add_u32 s4, s24, 0x20000
	s_addc_u32 s5, s25, 0
	s_add_i32 s61, vcc_lo, s36
	s_add_i32 s62, s61, 0x2000
	s_add_u32 s2, s26, 0x10080
	s_addc_u32 s3, s27, 0
	s_add_i32 s55, vcc_hi, s36
	s_add_i32 s0, s55, 0x2000
	v_lshl_add_u64 v[138:139], s[30:31], 0, v[134:135]
	ds_read_b128 v[176:179], v142
	ds_read_b128 v[180:183], v142 offset:1024
	ds_read_b128 v[184:187], v142 offset:2048
	ds_read_b128 v[188:191], v142 offset:3072
	ds_read_b128 v[192:195], v142 offset:4096
	ds_read_b128 v[196:199], v142 offset:5120
	ds_read_b128 v[208:211], v142 offset:6144
	ds_read_b128 v[212:215], v142 offset:7168
	global_load_lds_dwordx4 v[138:139], off
	v_lshl_add_u64 v[138:139], s[30:31], 0, v[132:133]
	s_mov_b32 m0, s1
	s_nop 0
	global_load_lds_dwordx4 v[138:139], off
	s_waitcnt vmcnt(8)
	s_waitcnt lgkmcnt(0)
	s_barrier
	s_setprio 1
	s_waitcnt lgkmcnt(0)
	v_mfma_f32_16x16x32_bf16 v[126:129], v[144:147], v[176:179], v[126:129]
	v_mfma_f32_16x16x32_bf16 v[122:125], v[152:155], v[176:179], v[122:125]
	v_mfma_f32_16x16x32_bf16 v[118:121], v[144:147], v[184:187], v[118:121]
	v_mfma_f32_16x16x32_bf16 v[110:113], v[152:155], v[184:187], v[110:113]
	v_mfma_f32_16x16x32_bf16 v[102:105], v[144:147], v[192:195], v[102:105]
	v_mfma_f32_16x16x32_bf16 v[94:97], v[152:155], v[192:195], v[94:97]
	v_mfma_f32_16x16x32_bf16 v[86:89], v[144:147], v[208:211], v[86:89]
	v_mfma_f32_16x16x32_bf16 v[78:81], v[152:155], v[208:211], v[78:81]
	v_mfma_f32_16x16x32_bf16 v[126:129], v[148:151], v[180:183], v[126:129]
	v_mfma_f32_16x16x32_bf16 v[122:125], v[156:159], v[180:183], v[122:125]
	v_mfma_f32_16x16x32_bf16 v[118:121], v[148:151], v[188:191], v[118:121]
	v_mfma_f32_16x16x32_bf16 v[110:113], v[156:159], v[188:191], v[110:113]
	v_mfma_f32_16x16x32_bf16 v[102:105], v[148:151], v[196:199], v[102:105]
	v_mfma_f32_16x16x32_bf16 v[94:97], v[156:159], v[196:199], v[94:97]
	v_mfma_f32_16x16x32_bf16 v[86:89], v[148:151], v[212:215], v[86:89]
	v_mfma_f32_16x16x32_bf16 v[78:81], v[156:159], v[212:215], v[78:81]
	v_mfma_f32_16x16x32_bf16 v[114:117], v[160:163], v[176:179], v[114:117]
	v_mfma_f32_16x16x32_bf16 v[106:109], v[168:171], v[176:179], v[106:109]
	v_mfma_f32_16x16x32_bf16 v[98:101], v[160:163], v[184:187], v[98:101]
	v_mfma_f32_16x16x32_bf16 v[90:93], v[168:171], v[184:187], v[90:93]
	v_mfma_f32_16x16x32_bf16 v[82:85], v[160:163], v[192:195], v[82:85]
	v_mfma_f32_16x16x32_bf16 v[74:77], v[168:171], v[192:195], v[74:77]
	v_mfma_f32_16x16x32_bf16 v[70:73], v[160:163], v[208:211], v[70:73]
	v_mfma_f32_16x16x32_bf16 v[66:69], v[168:171], v[208:211], v[66:69]
	v_mfma_f32_16x16x32_bf16 v[114:117], v[164:167], v[180:183], v[114:117]
	v_mfma_f32_16x16x32_bf16 v[106:109], v[172:175], v[180:183], v[106:109]
	v_mfma_f32_16x16x32_bf16 v[98:101], v[164:167], v[188:191], v[98:101]
	v_mfma_f32_16x16x32_bf16 v[90:93], v[172:175], v[188:191], v[90:93]
	v_mfma_f32_16x16x32_bf16 v[82:85], v[164:167], v[196:199], v[82:85]
	v_mfma_f32_16x16x32_bf16 v[74:77], v[172:175], v[196:199], v[74:77]
	v_mfma_f32_16x16x32_bf16 v[70:73], v[164:167], v[212:215], v[70:73]
	v_mfma_f32_16x16x32_bf16 v[66:69], v[172:175], v[212:215], v[66:69]
	s_setprio 0
	s_barrier
	s_mov_b32 m0, s57
	v_lshl_add_u64 v[138:139], s[26:27], 0, v[202:203]
	ds_read_b128 v[176:179], v142 offset:16384
	ds_read_b128 v[180:183], v142 offset:17408
	ds_read_b128 v[184:187], v142 offset:18432
	ds_read_b128 v[188:191], v142 offset:19456
	ds_read_b128 v[192:195], v142 offset:20480
	ds_read_b128 v[196:199], v142 offset:21504
	ds_read_b128 v[208:211], v142 offset:22528
	ds_read_b128 v[212:215], v142 offset:23552
	global_load_lds_dwordx4 v[138:139], off
	v_lshl_add_u64 v[200:201], s[26:27], 0, v[130:131]
	s_mov_b32 m0, s63
	v_lshl_add_u64 v[204:205], s[28:29], 0, v[202:203]
	global_load_lds_dwordx4 v[200:201], off
	s_mov_b32 m0, s33
	v_lshl_add_u64 v[206:207], s[24:25], 0, v[132:133]
	global_load_lds_dwordx4 v[204:205], off
	v_lshl_add_u64 v[204:205], s[28:29], 0, v[130:131]
	s_mov_b32 m0, s56
	s_nop 0
	global_load_lds_dwordx4 v[204:205], off
	v_lshl_add_u64 v[204:205], s[24:25], 0, v[134:135]
	s_mov_b32 m0, s37
	s_nop 0
	global_load_lds_dwordx4 v[204:205], off
	s_mov_b32 m0, s38
	s_nop 0
	global_load_lds_dwordx4 v[206:207], off
	s_waitcnt vmcnt(8)
	s_waitcnt lgkmcnt(0)
	s_barrier
	s_setprio 1
	s_waitcnt lgkmcnt(0)
	v_mfma_f32_16x16x32_bf16 v[62:65], v[144:147], v[176:179], v[62:65]
	v_mfma_f32_16x16x32_bf16 v[58:61], v[152:155], v[176:179], v[58:61]
	v_mfma_f32_16x16x32_bf16 v[54:57], v[144:147], v[184:187], v[54:57]
	v_mfma_f32_16x16x32_bf16 v[46:49], v[152:155], v[184:187], v[46:49]
	v_mfma_f32_16x16x32_bf16 v[38:41], v[144:147], v[192:195], v[38:41]
	v_mfma_f32_16x16x32_bf16 v[30:33], v[152:155], v[192:195], v[30:33]
	v_mfma_f32_16x16x32_bf16 v[22:25], v[144:147], v[208:211], v[22:25]
	v_mfma_f32_16x16x32_bf16 v[14:17], v[152:155], v[208:211], v[14:17]
	v_mfma_f32_16x16x32_bf16 v[62:65], v[148:151], v[180:183], v[62:65]
	v_mfma_f32_16x16x32_bf16 v[58:61], v[156:159], v[180:183], v[58:61]
	v_mfma_f32_16x16x32_bf16 v[54:57], v[148:151], v[188:191], v[54:57]
	v_mfma_f32_16x16x32_bf16 v[46:49], v[156:159], v[188:191], v[46:49]
	v_mfma_f32_16x16x32_bf16 v[38:41], v[148:151], v[196:199], v[38:41]
	v_mfma_f32_16x16x32_bf16 v[30:33], v[156:159], v[196:199], v[30:33]
	v_mfma_f32_16x16x32_bf16 v[22:25], v[148:151], v[212:215], v[22:25]
	v_mfma_f32_16x16x32_bf16 v[14:17], v[156:159], v[212:215], v[14:17]
	v_mfma_f32_16x16x32_bf16 v[50:53], v[160:163], v[176:179], v[50:53]
	v_mfma_f32_16x16x32_bf16 v[42:45], v[168:171], v[176:179], v[42:45]
	v_mfma_f32_16x16x32_bf16 v[34:37], v[160:163], v[184:187], v[34:37]
	v_mfma_f32_16x16x32_bf16 v[26:29], v[168:171], v[184:187], v[26:29]
	v_mfma_f32_16x16x32_bf16 v[18:21], v[160:163], v[192:195], v[18:21]
	v_mfma_f32_16x16x32_bf16 v[10:13], v[168:171], v[192:195], v[10:13]
	v_mfma_f32_16x16x32_bf16 v[6:9], v[160:163], v[208:211], v[6:9]
	v_mfma_f32_16x16x32_bf16 v[2:5], v[168:171], v[208:211], v[2:5]
	v_mfma_f32_16x16x32_bf16 v[50:53], v[164:167], v[180:183], v[50:53]
	v_mfma_f32_16x16x32_bf16 v[42:45], v[172:175], v[180:183], v[42:45]
	v_mfma_f32_16x16x32_bf16 v[34:37], v[164:167], v[188:191], v[34:37]
	v_mfma_f32_16x16x32_bf16 v[26:29], v[172:175], v[188:191], v[26:29]
	v_mfma_f32_16x16x32_bf16 v[18:21], v[164:167], v[196:199], v[18:21]
	v_mfma_f32_16x16x32_bf16 v[10:13], v[172:175], v[196:199], v[10:13]
	v_mfma_f32_16x16x32_bf16 v[6:9], v[164:167], v[212:215], v[6:9]
	v_mfma_f32_16x16x32_bf16 v[2:5], v[172:175], v[212:215], v[2:5]
	s_setprio 0
	s_barrier
	v_add_u32_e32 v143, vcc_lo, v141
	ds_read_b128 v[144:147], v143
	ds_read_b128 v[148:151], v143 offset:1024
	ds_read_b128 v[152:155], v143 offset:2048
	ds_read_b128 v[156:159], v143 offset:3072
	v_add_u32_e32 v143, vcc_hi, v141
	ds_read_b128 v[160:163], v143
	ds_read_b128 v[164:167], v143 offset:1024
	ds_read_b128 v[168:171], v143 offset:2048
	ds_read_b128 v[172:175], v143 offset:3072
	s_mov_b32 m0, s39
	v_lshl_add_u64 v[216:217], s[4:5], 0, v[134:135]
	ds_read_b128 v[176:179], v142 offset:32768
	ds_read_b128 v[180:183], v142 offset:33792
	ds_read_b128 v[184:187], v142 offset:34816
	ds_read_b128 v[188:191], v142 offset:35840
	ds_read_b128 v[192:195], v142 offset:36864
	ds_read_b128 v[196:199], v142 offset:37888
	ds_read_b128 v[208:211], v142 offset:38912
	ds_read_b128 v[212:215], v142 offset:39936
	global_load_lds_dwordx4 v[216:217], off
	v_lshl_add_u64 v[216:217], s[4:5], 0, v[132:133]
	s_mov_b32 m0, s40
	s_nop 0
	global_load_lds_dwordx4 v[216:217], off
	s_waitcnt vmcnt(8)
	s_waitcnt lgkmcnt(0)
	s_barrier
	s_setprio 1
	s_waitcnt lgkmcnt(0)
	v_mfma_f32_16x16x32_bf16 v[126:129], v[144:147], v[176:179], v[126:129]
	v_mfma_f32_16x16x32_bf16 v[122:125], v[152:155], v[176:179], v[122:125]
	v_mfma_f32_16x16x32_bf16 v[118:121], v[144:147], v[184:187], v[118:121]
	v_mfma_f32_16x16x32_bf16 v[110:113], v[152:155], v[184:187], v[110:113]
	v_mfma_f32_16x16x32_bf16 v[102:105], v[144:147], v[192:195], v[102:105]
	v_mfma_f32_16x16x32_bf16 v[94:97], v[152:155], v[192:195], v[94:97]
	v_mfma_f32_16x16x32_bf16 v[86:89], v[144:147], v[208:211], v[86:89]
	v_mfma_f32_16x16x32_bf16 v[78:81], v[152:155], v[208:211], v[78:81]
	v_mfma_f32_16x16x32_bf16 v[126:129], v[148:151], v[180:183], v[126:129]
	v_mfma_f32_16x16x32_bf16 v[122:125], v[156:159], v[180:183], v[122:125]
	v_mfma_f32_16x16x32_bf16 v[118:121], v[148:151], v[188:191], v[118:121]
	v_mfma_f32_16x16x32_bf16 v[110:113], v[156:159], v[188:191], v[110:113]
	v_mfma_f32_16x16x32_bf16 v[102:105], v[148:151], v[196:199], v[102:105]
	v_mfma_f32_16x16x32_bf16 v[94:97], v[156:159], v[196:199], v[94:97]
	v_mfma_f32_16x16x32_bf16 v[86:89], v[148:151], v[212:215], v[86:89]
	v_mfma_f32_16x16x32_bf16 v[78:81], v[156:159], v[212:215], v[78:81]
	v_mfma_f32_16x16x32_bf16 v[114:117], v[160:163], v[176:179], v[114:117]
	v_mfma_f32_16x16x32_bf16 v[106:109], v[168:171], v[176:179], v[106:109]
	v_mfma_f32_16x16x32_bf16 v[98:101], v[160:163], v[184:187], v[98:101]
	v_mfma_f32_16x16x32_bf16 v[90:93], v[168:171], v[184:187], v[90:93]
	v_mfma_f32_16x16x32_bf16 v[82:85], v[160:163], v[192:195], v[82:85]
	v_mfma_f32_16x16x32_bf16 v[74:77], v[168:171], v[192:195], v[74:77]
	v_mfma_f32_16x16x32_bf16 v[70:73], v[160:163], v[208:211], v[70:73]
	v_mfma_f32_16x16x32_bf16 v[66:69], v[168:171], v[208:211], v[66:69]
	v_mfma_f32_16x16x32_bf16 v[114:117], v[164:167], v[180:183], v[114:117]
	v_mfma_f32_16x16x32_bf16 v[106:109], v[172:175], v[180:183], v[106:109]
	v_mfma_f32_16x16x32_bf16 v[98:101], v[164:167], v[188:191], v[98:101]
	v_mfma_f32_16x16x32_bf16 v[90:93], v[172:175], v[188:191], v[90:93]
	v_mfma_f32_16x16x32_bf16 v[82:85], v[164:167], v[196:199], v[82:85]
	v_mfma_f32_16x16x32_bf16 v[74:77], v[172:175], v[196:199], v[74:77]
	v_mfma_f32_16x16x32_bf16 v[70:73], v[164:167], v[212:215], v[70:73]
	v_mfma_f32_16x16x32_bf16 v[66:69], v[172:175], v[212:215], v[66:69]
	s_setprio 0
	s_barrier
	s_mov_b32 m0, s61
	v_lshl_add_u64 v[138:139], v[138:139], 0, s[80:81]
	ds_read_b128 v[176:179], v142 offset:49152
	ds_read_b128 v[180:183], v142 offset:50176
	ds_read_b128 v[184:187], v142 offset:51200
	ds_read_b128 v[188:191], v142 offset:52224
	ds_read_b128 v[192:195], v142 offset:53248
	ds_read_b128 v[196:199], v142 offset:54272
	ds_read_b128 v[208:211], v142 offset:55296
	ds_read_b128 v[212:215], v142 offset:56320
	global_load_lds_dwordx4 v[138:139], off
	v_lshl_add_u64 v[138:139], v[200:201], 0, s[80:81]
	s_mov_b32 m0, s62
	s_nop 0
	global_load_lds_dwordx4 v[138:139], off
	v_lshl_add_u64 v[138:139], s[2:3], 0, v[202:203]
	s_mov_b32 m0, s55
	s_nop 0
	global_load_lds_dwordx4 v[138:139], off
	v_lshl_add_u64 v[138:139], s[2:3], 0, v[130:131]
	s_mov_b32 m0, s0
	s_nop 0
	global_load_lds_dwordx4 v[138:139], off
	v_lshl_add_u64 v[138:139], v[204:205], 0, s[80:81]
	s_mov_b32 m0, s41
	s_nop 0
	global_load_lds_dwordx4 v[138:139], off
	v_lshl_add_u64 v[138:139], v[206:207], 0, s[80:81]
	s_mov_b32 m0, s86
	s_nop 0
	global_load_lds_dwordx4 v[138:139], off
	s_waitcnt vmcnt(8)
	s_waitcnt lgkmcnt(0)
	s_barrier
	s_setprio 1
	s_waitcnt lgkmcnt(0)
	v_mfma_f32_16x16x32_bf16 v[62:65], v[144:147], v[176:179], v[62:65]
	v_mfma_f32_16x16x32_bf16 v[58:61], v[152:155], v[176:179], v[58:61]
	v_mfma_f32_16x16x32_bf16 v[54:57], v[144:147], v[184:187], v[54:57]
	v_mfma_f32_16x16x32_bf16 v[46:49], v[152:155], v[184:187], v[46:49]
	v_mfma_f32_16x16x32_bf16 v[38:41], v[144:147], v[192:195], v[38:41]
	v_mfma_f32_16x16x32_bf16 v[30:33], v[152:155], v[192:195], v[30:33]
	v_mfma_f32_16x16x32_bf16 v[22:25], v[144:147], v[208:211], v[22:25]
	v_mfma_f32_16x16x32_bf16 v[14:17], v[152:155], v[208:211], v[14:17]
	v_mfma_f32_16x16x32_bf16 v[62:65], v[148:151], v[180:183], v[62:65]
	v_mfma_f32_16x16x32_bf16 v[58:61], v[156:159], v[180:183], v[58:61]
	v_mfma_f32_16x16x32_bf16 v[54:57], v[148:151], v[188:191], v[54:57]
	v_mfma_f32_16x16x32_bf16 v[46:49], v[156:159], v[188:191], v[46:49]
	v_mfma_f32_16x16x32_bf16 v[38:41], v[148:151], v[196:199], v[38:41]
	v_mfma_f32_16x16x32_bf16 v[30:33], v[156:159], v[196:199], v[30:33]
	v_mfma_f32_16x16x32_bf16 v[22:25], v[148:151], v[212:215], v[22:25]
	v_mfma_f32_16x16x32_bf16 v[14:17], v[156:159], v[212:215], v[14:17]
	v_mfma_f32_16x16x32_bf16 v[50:53], v[160:163], v[176:179], v[50:53]
	v_mfma_f32_16x16x32_bf16 v[42:45], v[168:171], v[176:179], v[42:45]
	v_mfma_f32_16x16x32_bf16 v[34:37], v[160:163], v[184:187], v[34:37]
	v_mfma_f32_16x16x32_bf16 v[26:29], v[168:171], v[184:187], v[26:29]
	v_mfma_f32_16x16x32_bf16 v[18:21], v[160:163], v[192:195], v[18:21]
	v_mfma_f32_16x16x32_bf16 v[10:13], v[168:171], v[192:195], v[10:13]
	v_mfma_f32_16x16x32_bf16 v[6:9], v[160:163], v[208:211], v[6:9]
	v_mfma_f32_16x16x32_bf16 v[2:5], v[168:171], v[208:211], v[2:5]
	v_mfma_f32_16x16x32_bf16 v[50:53], v[164:167], v[180:183], v[50:53]
	v_mfma_f32_16x16x32_bf16 v[42:45], v[172:175], v[180:183], v[42:45]
	v_mfma_f32_16x16x32_bf16 v[34:37], v[164:167], v[188:191], v[34:37]
	v_mfma_f32_16x16x32_bf16 v[26:29], v[172:175], v[188:191], v[26:29]
	v_mfma_f32_16x16x32_bf16 v[18:21], v[164:167], v[196:199], v[18:21]
	v_mfma_f32_16x16x32_bf16 v[10:13], v[172:175], v[196:199], v[10:13]
	v_mfma_f32_16x16x32_bf16 v[6:9], v[164:167], v[212:215], v[6:9]
	v_mfma_f32_16x16x32_bf16 v[2:5], v[172:175], v[212:215], v[2:5]
	s_setprio 0
	s_barrier
	s_andn2_b64 vcc, exec, s[22:23]
	s_mov_b64 s[2:3], -1
	s_mov_b64 s[22:23], 0
	s_mov_b64 s[4:5], 0x100
	s_cbranch_vccz .LBB0_1242
	s_and_b64 vcc, exec, s[10:11]
	s_cbranch_vccz .LBB0_1245
	s_barrier

.LBB0_1363:
	s_add_u32 s0, s20, 0xfffe0080
	s_addc_u32 s1, s21, -1
	s_add_i32 s33, 0, 0x10000
	s_cmp_eq_u32 s59, 4
	s_cselect_b32 s5, s38, s1
	s_cselect_b32 s4, s39, s0
	v_add_u32_e32 v147, s33, v143
	s_cselect_b32 s3, s40, s58
	s_cselect_b32 s2, s41, s49
	s_add_i32 s55, 0, 0x14000
	ds_read_b128 v[148:151], v147
	ds_read_b128 v[152:155], v147 offset:1024
	ds_read_b128 v[156:159], v147 offset:2048
	ds_read_b128 v[160:163], v147 offset:3072
	v_add_u32_e32 v147, s55, v143
	ds_read_b128 v[164:167], v147
	ds_read_b128 v[168:171], v147 offset:1024
	ds_read_b128 v[172:175], v147 offset:2048
	ds_read_b128 v[176:179], v147 offset:3072
	v_lshl_add_u64 v[200:201], s[20:21], 0, v[138:139]
	s_add_i32 m0, s25, 0xc000
	ds_read_b128 v[180:183], v146
	ds_read_b128 v[184:187], v146 offset:1024
	ds_read_b128 v[188:191], v146 offset:2048
	ds_read_b128 v[192:195], v146 offset:3072
	ds_read_b128 v[196:199], v146 offset:4096
	ds_read_b128 v[208:211], v146 offset:5120
	ds_read_b128 v[212:215], v146 offset:6144
	ds_read_b128 v[216:219], v146 offset:7168
	global_load_lds_dwordx4 v[200:201], off
	v_lshl_add_u64 v[200:201], s[20:21], 0, v[140:141]
	s_add_i32 m0, s25, 0xe000
	s_nop 0
	global_load_lds_dwordx4 v[200:201], off
	s_waitcnt vmcnt(8)
	s_waitcnt lgkmcnt(0)
	s_barrier
	s_setprio 1
	s_waitcnt lgkmcnt(0)
	v_mfma_f32_16x16x32_bf16 v[126:129], v[148:151], v[180:183], v[126:129]
	v_mfma_f32_16x16x32_bf16 v[122:125], v[156:159], v[180:183], v[122:125]
	v_mfma_f32_16x16x32_bf16 v[110:113], v[148:151], v[188:191], v[110:113]
	v_mfma_f32_16x16x32_bf16 v[106:109], v[156:159], v[188:191], v[106:109]
	v_mfma_f32_16x16x32_bf16 v[94:97], v[148:151], v[196:199], v[94:97]
	v_mfma_f32_16x16x32_bf16 v[90:93], v[156:159], v[196:199], v[90:93]
	v_mfma_f32_16x16x32_bf16 v[78:81], v[148:151], v[212:215], v[78:81]
	v_mfma_f32_16x16x32_bf16 v[74:77], v[156:159], v[212:215], v[74:77]
	v_mfma_f32_16x16x32_bf16 v[126:129], v[152:155], v[184:187], v[126:129]
	v_mfma_f32_16x16x32_bf16 v[122:125], v[160:163], v[184:187], v[122:125]
	v_mfma_f32_16x16x32_bf16 v[110:113], v[152:155], v[192:195], v[110:113]
	v_mfma_f32_16x16x32_bf16 v[106:109], v[160:163], v[192:195], v[106:109]
	v_mfma_f32_16x16x32_bf16 v[94:97], v[152:155], v[208:211], v[94:97]
	v_mfma_f32_16x16x32_bf16 v[90:93], v[160:163], v[208:211], v[90:93]
	v_mfma_f32_16x16x32_bf16 v[78:81], v[152:155], v[216:219], v[78:81]
	v_mfma_f32_16x16x32_bf16 v[74:77], v[160:163], v[216:219], v[74:77]
	v_mfma_f32_16x16x32_bf16 v[118:121], v[164:167], v[180:183], v[118:121]
	v_mfma_f32_16x16x32_bf16 v[114:117], v[172:175], v[180:183], v[114:117]
	v_mfma_f32_16x16x32_bf16 v[102:105], v[164:167], v[188:191], v[102:105]
	v_mfma_f32_16x16x32_bf16 v[98:101], v[172:175], v[188:191], v[98:101]
	v_mfma_f32_16x16x32_bf16 v[86:89], v[164:167], v[196:199], v[86:89]
	v_mfma_f32_16x16x32_bf16 v[82:85], v[172:175], v[196:199], v[82:85]
	v_mfma_f32_16x16x32_bf16 v[70:73], v[164:167], v[212:215], v[70:73]
	v_mfma_f32_16x16x32_bf16 v[66:69], v[172:175], v[212:215], v[66:69]
	v_mfma_f32_16x16x32_bf16 v[118:121], v[168:171], v[184:187], v[118:121]
	v_mfma_f32_16x16x32_bf16 v[114:117], v[176:179], v[184:187], v[114:117]
	v_mfma_f32_16x16x32_bf16 v[102:105], v[168:171], v[192:195], v[102:105]
	v_mfma_f32_16x16x32_bf16 v[98:101], v[176:179], v[192:195], v[98:101]
	v_mfma_f32_16x16x32_bf16 v[86:89], v[168:171], v[208:211], v[86:89]
	v_mfma_f32_16x16x32_bf16 v[82:85], v[176:179], v[208:211], v[82:85]
	v_mfma_f32_16x16x32_bf16 v[70:73], v[168:171], v[216:219], v[70:73]
	v_mfma_f32_16x16x32_bf16 v[66:69], v[176:179], v[216:219], v[66:69]
	s_setprio 0
	s_barrier
	s_add_i32 s0, s33, s24
	v_lshl_add_u64 v[200:201], s[2:3], 0, v[134:135]
	s_mov_b32 m0, s0
	ds_read_b128 v[180:183], v146 offset:16384
	ds_read_b128 v[184:187], v146 offset:17408
	ds_read_b128 v[188:191], v146 offset:18432
	ds_read_b128 v[192:195], v146 offset:19456
	ds_read_b128 v[196:199], v146 offset:20480
	ds_read_b128 v[208:211], v146 offset:21504
	ds_read_b128 v[212:215], v146 offset:22528
	ds_read_b128 v[216:219], v146 offset:23552
	global_load_lds_dwordx4 v[200:201], off
	s_add_i32 m0, s0, 0x2000
	s_add_u32 s0, s2, 0x20000
	v_lshl_add_u64 v[204:205], s[2:3], 0, v[130:131]
	s_addc_u32 s1, s3, 0
	s_add_i32 s33, s55, s24
	global_load_lds_dwordx4 v[204:205], off
	v_lshl_add_u64 v[206:207], s[0:1], 0, v[134:135]
	s_mov_b32 m0, s33
	v_lshl_add_u64 v[220:221], s[4:5], 0, v[132:133]
	global_load_lds_dwordx4 v[206:207], off
	v_lshl_add_u64 v[206:207], s[0:1], 0, v[130:131]
	s_add_i32 m0, s33, 0x2000
	s_nop 0
	global_load_lds_dwordx4 v[206:207], off
	v_lshl_add_u64 v[206:207], s[4:5], 0, v[136:137]
	s_mov_b32 m0, s25
	s_nop 0
	global_load_lds_dwordx4 v[206:207], off
	s_mov_b32 m0, s26
	s_nop 0
	global_load_lds_dwordx4 v[220:221], off
	s_waitcnt vmcnt(8)
	s_waitcnt lgkmcnt(0)
	s_barrier
	s_setprio 1
	s_waitcnt lgkmcnt(0)
	v_mfma_f32_16x16x32_bf16 v[62:65], v[148:151], v[180:183], v[62:65]
	v_mfma_f32_16x16x32_bf16 v[58:61], v[156:159], v[180:183], v[58:61]
	v_mfma_f32_16x16x32_bf16 v[46:49], v[148:151], v[188:191], v[46:49]
	v_mfma_f32_16x16x32_bf16 v[42:45], v[156:159], v[188:191], v[42:45]
	v_mfma_f32_16x16x32_bf16 v[30:33], v[148:151], v[196:199], v[30:33]
	v_mfma_f32_16x16x32_bf16 v[26:29], v[156:159], v[196:199], v[26:29]
	v_mfma_f32_16x16x32_bf16 v[14:17], v[148:151], v[212:215], v[14:17]
	v_mfma_f32_16x16x32_bf16 v[10:13], v[156:159], v[212:215], v[10:13]
	v_mfma_f32_16x16x32_bf16 v[62:65], v[152:155], v[184:187], v[62:65]
	v_mfma_f32_16x16x32_bf16 v[58:61], v[160:163], v[184:187], v[58:61]
	v_mfma_f32_16x16x32_bf16 v[46:49], v[152:155], v[192:195], v[46:49]
	v_mfma_f32_16x16x32_bf16 v[42:45], v[160:163], v[192:195], v[42:45]
	v_mfma_f32_16x16x32_bf16 v[30:33], v[152:155], v[208:211], v[30:33]
	v_mfma_f32_16x16x32_bf16 v[26:29], v[160:163], v[208:211], v[26:29]
	v_mfma_f32_16x16x32_bf16 v[14:17], v[152:155], v[216:219], v[14:17]
	v_mfma_f32_16x16x32_bf16 v[10:13], v[160:163], v[216:219], v[10:13]
	v_mfma_f32_16x16x32_bf16 v[54:57], v[164:167], v[180:183], v[54:57]
	v_mfma_f32_16x16x32_bf16 v[50:53], v[172:175], v[180:183], v[50:53]
	v_mfma_f32_16x16x32_bf16 v[38:41], v[164:167], v[188:191], v[38:41]
	v_mfma_f32_16x16x32_bf16 v[34:37], v[172:175], v[188:191], v[34:37]
	v_mfma_f32_16x16x32_bf16 v[22:25], v[164:167], v[196:199], v[22:25]
	v_mfma_f32_16x16x32_bf16 v[18:21], v[172:175], v[196:199], v[18:21]
	v_mfma_f32_16x16x32_bf16 v[6:9], v[164:167], v[212:215], v[6:9]
	v_mfma_f32_16x16x32_bf16 v[2:5], v[172:175], v[212:215], v[2:5]
	v_mfma_f32_16x16x32_bf16 v[54:57], v[168:171], v[184:187], v[54:57]
	v_mfma_f32_16x16x32_bf16 v[50:53], v[176:179], v[184:187], v[50:53]
	v_mfma_f32_16x16x32_bf16 v[38:41], v[168:171], v[192:195], v[38:41]
	v_mfma_f32_16x16x32_bf16 v[34:37], v[176:179], v[192:195], v[34:37]
	v_mfma_f32_16x16x32_bf16 v[22:25], v[168:171], v[208:211], v[22:25]
	v_mfma_f32_16x16x32_bf16 v[18:21], v[176:179], v[208:211], v[18:21]
	v_mfma_f32_16x16x32_bf16 v[6:9], v[168:171], v[216:219], v[6:9]
	v_mfma_f32_16x16x32_bf16 v[2:5], v[176:179], v[216:219], v[2:5]
	s_setprio 0
	s_barrier
	s_add_i32 s33, 0, 0x18000
	v_add_u32_e32 v147, s33, v143
	s_add_i32 s55, 0, 0x1c000
	ds_read_b128 v[148:151], v147
	ds_read_b128 v[152:155], v147 offset:1024
	ds_read_b128 v[156:159], v147 offset:2048
	ds_read_b128 v[160:163], v147 offset:3072
	v_add_u32_e32 v147, s55, v143
	ds_read_b128 v[164:167], v147
	ds_read_b128 v[168:171], v147 offset:1024
	ds_read_b128 v[172:175], v147 offset:2048
	ds_read_b128 v[176:179], v147 offset:3072
	s_add_u32 s0, s4, 0x20000
	s_addc_u32 s1, s5, 0
	s_mov_b32 m0, s27
	v_lshl_add_u64 v[222:223], s[0:1], 0, v[136:137]
	ds_read_b128 v[180:183], v146 offset:32768
	ds_read_b128 v[184:187], v146 offset:33792
	ds_read_b128 v[188:191], v146 offset:34816
	ds_read_b128 v[192:195], v146 offset:35840
	ds_read_b128 v[196:199], v146 offset:36864
	ds_read_b128 v[208:211], v146 offset:37888
	ds_read_b128 v[212:215], v146 offset:38912
	ds_read_b128 v[216:219], v146 offset:39936
	global_load_lds_dwordx4 v[222:223], off
	v_lshl_add_u64 v[222:223], s[0:1], 0, v[132:133]
	s_mov_b32 m0, s28
	s_nop 0
	global_load_lds_dwordx4 v[222:223], off
	s_waitcnt vmcnt(8)
	s_waitcnt lgkmcnt(0)
	s_barrier
	s_setprio 1
	s_waitcnt lgkmcnt(0)
	v_mfma_f32_16x16x32_bf16 v[126:129], v[148:151], v[180:183], v[126:129]
	v_mfma_f32_16x16x32_bf16 v[122:125], v[156:159], v[180:183], v[122:125]
	v_mfma_f32_16x16x32_bf16 v[110:113], v[148:151], v[188:191], v[110:113]
	v_mfma_f32_16x16x32_bf16 v[106:109], v[156:159], v[188:191], v[106:109]
	v_mfma_f32_16x16x32_bf16 v[94:97], v[148:151], v[196:199], v[94:97]
	v_mfma_f32_16x16x32_bf16 v[90:93], v[156:159], v[196:199], v[90:93]
	v_mfma_f32_16x16x32_bf16 v[78:81], v[148:151], v[212:215], v[78:81]
	v_mfma_f32_16x16x32_bf16 v[74:77], v[156:159], v[212:215], v[74:77]
	v_mfma_f32_16x16x32_bf16 v[126:129], v[152:155], v[184:187], v[126:129]
	v_mfma_f32_16x16x32_bf16 v[122:125], v[160:163], v[184:187], v[122:125]
	v_mfma_f32_16x16x32_bf16 v[110:113], v[152:155], v[192:195], v[110:113]
	v_mfma_f32_16x16x32_bf16 v[106:109], v[160:163], v[192:195], v[106:109]
	v_mfma_f32_16x16x32_bf16 v[94:97], v[152:155], v[208:211], v[94:97]
	v_mfma_f32_16x16x32_bf16 v[90:93], v[160:163], v[208:211], v[90:93]
	v_mfma_f32_16x16x32_bf16 v[78:81], v[152:155], v[216:219], v[78:81]
	v_mfma_f32_16x16x32_bf16 v[74:77], v[160:163], v[216:219], v[74:77]
	v_mfma_f32_16x16x32_bf16 v[118:121], v[164:167], v[180:183], v[118:121]
	v_mfma_f32_16x16x32_bf16 v[114:117], v[172:175], v[180:183], v[114:117]
	v_mfma_f32_16x16x32_bf16 v[102:105], v[164:167], v[188:191], v[102:105]
	v_mfma_f32_16x16x32_bf16 v[98:101], v[172:175], v[188:191], v[98:101]
	v_mfma_f32_16x16x32_bf16 v[86:89], v[164:167], v[196:199], v[86:89]
	v_mfma_f32_16x16x32_bf16 v[82:85], v[172:175], v[196:199], v[82:85]
	v_mfma_f32_16x16x32_bf16 v[70:73], v[164:167], v[212:215], v[70:73]
	v_mfma_f32_16x16x32_bf16 v[66:69], v[172:175], v[212:215], v[66:69]
	v_mfma_f32_16x16x32_bf16 v[118:121], v[168:171], v[184:187], v[118:121]
	v_mfma_f32_16x16x32_bf16 v[114:117], v[176:179], v[184:187], v[114:117]
	v_mfma_f32_16x16x32_bf16 v[102:105], v[168:171], v[192:195], v[102:105]
	v_mfma_f32_16x16x32_bf16 v[98:101], v[176:179], v[192:195], v[98:101]
	v_mfma_f32_16x16x32_bf16 v[86:89], v[168:171], v[208:211], v[86:89]
	v_mfma_f32_16x16x32_bf16 v[82:85], v[176:179], v[208:211], v[82:85]
	v_mfma_f32_16x16x32_bf16 v[70:73], v[168:171], v[216:219], v[70:73]
	v_mfma_f32_16x16x32_bf16 v[66:69], v[176:179], v[216:219], v[66:69]
	s_setprio 0
	s_barrier
	s_add_i32 s0, s33, s24
	v_lshl_add_u64 v[200:201], v[200:201], 0, s[80:81]
	s_mov_b32 m0, s0
	ds_read_b128 v[180:183], v146 offset:49152
	ds_read_b128 v[184:187], v146 offset:50176
	ds_read_b128 v[188:191], v146 offset:51200
	ds_read_b128 v[192:195], v146 offset:52224
	ds_read_b128 v[196:199], v146 offset:53248
	ds_read_b128 v[208:211], v146 offset:54272
	ds_read_b128 v[212:215], v146 offset:55296
	ds_read_b128 v[216:219], v146 offset:56320
	global_load_lds_dwordx4 v[200:201], off
	s_add_i32 m0, s0, 0x2000
	s_add_u32 s0, s2, 0x20080
	v_lshl_add_u64 v[200:201], v[204:205], 0, s[80:81]
	s_addc_u32 s1, s3, 0
	s_add_i32 s2, s55, s24
	global_load_lds_dwordx4 v[200:201], off
	v_lshl_add_u64 v[200:201], s[0:1], 0, v[134:135]
	s_mov_b32 m0, s2
	s_nop 0
	global_load_lds_dwordx4 v[200:201], off
	v_lshl_add_u64 v[200:201], s[0:1], 0, v[130:131]
	s_add_i32 m0, s2, 0x2000
	s_nop 0
	global_load_lds_dwordx4 v[200:201], off
	v_lshl_add_u64 v[200:201], v[206:207], 0, s[80:81]
	s_mov_b32 m0, s29
	s_nop 0
	global_load_lds_dwordx4 v[200:201], off
	v_lshl_add_u64 v[200:201], v[220:221], 0, s[80:81]
	s_mov_b32 m0, s30
	s_nop 0
	global_load_lds_dwordx4 v[200:201], off
	s_waitcnt vmcnt(8)
	s_waitcnt lgkmcnt(0)
	s_barrier
	s_setprio 1
	s_waitcnt lgkmcnt(0)
	v_mfma_f32_16x16x32_bf16 v[62:65], v[148:151], v[180:183], v[62:65]
	v_mfma_f32_16x16x32_bf16 v[58:61], v[156:159], v[180:183], v[58:61]
	v_mfma_f32_16x16x32_bf16 v[46:49], v[148:151], v[188:191], v[46:49]
	v_mfma_f32_16x16x32_bf16 v[42:45], v[156:159], v[188:191], v[42:45]
	v_mfma_f32_16x16x32_bf16 v[30:33], v[148:151], v[196:199], v[30:33]
	v_mfma_f32_16x16x32_bf16 v[26:29], v[156:159], v[196:199], v[26:29]
	v_mfma_f32_16x16x32_bf16 v[14:17], v[148:151], v[212:215], v[14:17]
	v_mfma_f32_16x16x32_bf16 v[10:13], v[156:159], v[212:215], v[10:13]
	v_mfma_f32_16x16x32_bf16 v[62:65], v[152:155], v[184:187], v[62:65]
	v_mfma_f32_16x16x32_bf16 v[58:61], v[160:163], v[184:187], v[58:61]
	v_mfma_f32_16x16x32_bf16 v[46:49], v[152:155], v[192:195], v[46:49]
	v_mfma_f32_16x16x32_bf16 v[42:45], v[160:163], v[192:195], v[42:45]
	v_mfma_f32_16x16x32_bf16 v[30:33], v[152:155], v[208:211], v[30:33]
	v_mfma_f32_16x16x32_bf16 v[26:29], v[160:163], v[208:211], v[26:29]
	v_mfma_f32_16x16x32_bf16 v[14:17], v[152:155], v[216:219], v[14:17]
	v_mfma_f32_16x16x32_bf16 v[10:13], v[160:163], v[216:219], v[10:13]
	v_mfma_f32_16x16x32_bf16 v[54:57], v[164:167], v[180:183], v[54:57]
	v_mfma_f32_16x16x32_bf16 v[50:53], v[172:175], v[180:183], v[50:53]
	v_mfma_f32_16x16x32_bf16 v[38:41], v[164:167], v[188:191], v[38:41]
	v_mfma_f32_16x16x32_bf16 v[34:37], v[172:175], v[188:191], v[34:37]
	v_mfma_f32_16x16x32_bf16 v[22:25], v[164:167], v[196:199], v[22:25]
	v_mfma_f32_16x16x32_bf16 v[18:21], v[172:175], v[196:199], v[18:21]
	v_mfma_f32_16x16x32_bf16 v[6:9], v[164:167], v[212:215], v[6:9]
	v_mfma_f32_16x16x32_bf16 v[2:5], v[172:175], v[212:215], v[2:5]
	v_mfma_f32_16x16x32_bf16 v[54:57], v[168:171], v[184:187], v[54:57]
	v_mfma_f32_16x16x32_bf16 v[50:53], v[176:179], v[184:187], v[50:53]
	v_mfma_f32_16x16x32_bf16 v[38:41], v[168:171], v[192:195], v[38:41]
	v_mfma_f32_16x16x32_bf16 v[34:37], v[176:179], v[192:195], v[34:37]
	v_mfma_f32_16x16x32_bf16 v[22:25], v[168:171], v[208:211], v[22:25]
	v_mfma_f32_16x16x32_bf16 v[18:21], v[176:179], v[208:211], v[18:21]
	v_mfma_f32_16x16x32_bf16 v[6:9], v[168:171], v[216:219], v[6:9]
	v_mfma_f32_16x16x32_bf16 v[2:5], v[176:179], v[216:219], v[2:5]
	s_setprio 0
	s_barrier
	s_add_i32 s59, s59, 2
	s_add_u32 s20, s20, 0x100
	s_addc_u32 s21, s21, 0
	s_add_u32 s49, s49, 0x100
	s_addc_u32 s58, s58, 0
	s_cmp_gt_u32 s59, 5
	s_cbranch_scc0 .LBB0_1363
	s_and_b64 vcc, exec, s[14:15]
	s_cbranch_vccz .LBB0_1366
	s_barrier

.LBB0_1428:
	s_add_u32 s0, s26, 0xfff80080
	s_addc_u32 s1, s27, -1
	s_add_i32 s33, 0, 0x10000
	s_cmp_eq_u32 s61, 28
	s_cselect_b32 s5, s17, s1
	s_cselect_b32 s4, s49, s0
	s_cselect_b32 s3, s15, s60
	s_cselect_b32 s2, s58, s59
	s_add_i32 s55, 0, 0x14000
	v_add_u32_e32 v142, s33, v187
	v_add_u32_e32 v158, s55, v187
	ds_read_b128 v[126:129], v142
	ds_read_b128 v[134:137], v142 offset:1024
	ds_read_b128 v[138:141], v142 offset:2048
	ds_read_b128 v[142:145], v142 offset:3072
	ds_read_b128 v[146:149], v158
	ds_read_b128 v[150:153], v158 offset:1024
	ds_read_b128 v[154:157], v158 offset:2048
	ds_read_b128 v[158:161], v158 offset:3072
	v_lshl_add_u64 v[184:185], s[26:27], 0, v[168:169]
	s_add_i32 m0, s23, 0xc000
	ds_read_b128 v[172:175], v189
	ds_read_b128 v[176:179], v189 offset:1024
	ds_read_b128 v[180:183], v189 offset:2048
	ds_read_b128 v[190:193], v189 offset:3072
	ds_read_b128 v[194:197], v189 offset:4096
	ds_read_b128 v[198:201], v189 offset:5120
	ds_read_b128 v[208:211], v189 offset:6144
	ds_read_b128 v[212:215], v189 offset:7168
	global_load_lds_dwordx4 v[184:185], off
	v_lshl_add_u64 v[184:185], s[26:27], 0, v[170:171]
	s_add_i32 m0, s23, 0xe000
	s_nop 0
	global_load_lds_dwordx4 v[184:185], off
	s_waitcnt vmcnt(8)
	s_waitcnt lgkmcnt(0)
	s_barrier
	s_setprio 1
	s_waitcnt lgkmcnt(0)
	v_mfma_f32_16x16x32_bf16 v[130:133], v[126:129], v[172:175], v[130:133]
	v_mfma_f32_16x16x32_bf16 v[118:121], v[138:141], v[172:175], v[118:121]
	v_mfma_f32_16x16x32_bf16 v[110:113], v[126:129], v[180:183], v[110:113]
	v_mfma_f32_16x16x32_bf16 v[102:105], v[138:141], v[180:183], v[102:105]
	v_mfma_f32_16x16x32_bf16 v[94:97], v[126:129], v[194:197], v[94:97]
	v_mfma_f32_16x16x32_bf16 v[86:89], v[138:141], v[194:197], v[86:89]
	v_mfma_f32_16x16x32_bf16 v[78:81], v[126:129], v[208:211], v[78:81]
	v_mfma_f32_16x16x32_bf16 v[70:73], v[138:141], v[208:211], v[70:73]
	v_mfma_f32_16x16x32_bf16 v[130:133], v[134:137], v[176:179], v[130:133]
	v_mfma_f32_16x16x32_bf16 v[118:121], v[142:145], v[176:179], v[118:121]
	v_mfma_f32_16x16x32_bf16 v[110:113], v[134:137], v[190:193], v[110:113]
	v_mfma_f32_16x16x32_bf16 v[102:105], v[142:145], v[190:193], v[102:105]
	v_mfma_f32_16x16x32_bf16 v[94:97], v[134:137], v[198:201], v[94:97]
	v_mfma_f32_16x16x32_bf16 v[86:89], v[142:145], v[198:201], v[86:89]
	v_mfma_f32_16x16x32_bf16 v[78:81], v[134:137], v[212:215], v[78:81]
	v_mfma_f32_16x16x32_bf16 v[70:73], v[142:145], v[212:215], v[70:73]
	v_mfma_f32_16x16x32_bf16 v[122:125], v[146:149], v[172:175], v[122:125]
	v_mfma_f32_16x16x32_bf16 v[114:117], v[154:157], v[172:175], v[114:117]
	v_mfma_f32_16x16x32_bf16 v[106:109], v[146:149], v[180:183], v[106:109]
	v_mfma_f32_16x16x32_bf16 v[98:101], v[154:157], v[180:183], v[98:101]
	v_mfma_f32_16x16x32_bf16 v[90:93], v[146:149], v[194:197], v[90:93]
	v_mfma_f32_16x16x32_bf16 v[82:85], v[154:157], v[194:197], v[82:85]
	v_mfma_f32_16x16x32_bf16 v[74:77], v[146:149], v[208:211], v[74:77]
	v_mfma_f32_16x16x32_bf16 v[66:69], v[154:157], v[208:211], v[66:69]
	v_mfma_f32_16x16x32_bf16 v[122:125], v[150:153], v[176:179], v[122:125]
	v_mfma_f32_16x16x32_bf16 v[114:117], v[158:161], v[176:179], v[114:117]
	v_mfma_f32_16x16x32_bf16 v[106:109], v[150:153], v[190:193], v[106:109]
	v_mfma_f32_16x16x32_bf16 v[98:101], v[158:161], v[190:193], v[98:101]
	v_mfma_f32_16x16x32_bf16 v[90:93], v[150:153], v[198:201], v[90:93]
	v_mfma_f32_16x16x32_bf16 v[82:85], v[158:161], v[198:201], v[82:85]
	v_mfma_f32_16x16x32_bf16 v[74:77], v[150:153], v[212:215], v[74:77]
	v_mfma_f32_16x16x32_bf16 v[66:69], v[158:161], v[212:215], v[66:69]
	s_setprio 0
	s_barrier
	s_add_i32 s0, s33, s34
	v_lshl_add_u64 v[184:185], s[2:3], 0, v[202:203]
	s_mov_b32 m0, s0
	ds_read_b128 v[172:175], v189 offset:16384
	ds_read_b128 v[176:179], v189 offset:17408
	ds_read_b128 v[180:183], v189 offset:18432
	ds_read_b128 v[190:193], v189 offset:19456
	ds_read_b128 v[194:197], v189 offset:20480
	ds_read_b128 v[198:201], v189 offset:21504
	ds_read_b128 v[208:211], v189 offset:22528
	ds_read_b128 v[212:215], v189 offset:23552
	global_load_lds_dwordx4 v[184:185], off
	s_add_i32 m0, s0, 0x2000
	s_add_u32 s0, s2, 0x80000
	v_lshl_add_u64 v[204:205], s[2:3], 0, v[162:163]
	s_addc_u32 s1, s3, 0
	s_add_i32 s33, s55, s34
	global_load_lds_dwordx4 v[204:205], off
	v_lshl_add_u64 v[206:207], s[0:1], 0, v[202:203]
	s_mov_b32 m0, s33
	v_lshl_add_u64 v[216:217], s[4:5], 0, v[164:165]
	global_load_lds_dwordx4 v[206:207], off
	v_lshl_add_u64 v[206:207], s[0:1], 0, v[162:163]
	s_add_i32 m0, s33, 0x2000
	s_nop 0
	global_load_lds_dwordx4 v[206:207], off
	v_lshl_add_u64 v[206:207], s[4:5], 0, v[166:167]
	s_mov_b32 m0, s23
	s_nop 0
	global_load_lds_dwordx4 v[206:207], off
	s_mov_b32 m0, s25
	s_nop 0
	global_load_lds_dwordx4 v[216:217], off
	s_waitcnt vmcnt(8)
	s_waitcnt lgkmcnt(0)
	s_barrier
	s_setprio 1
	s_waitcnt lgkmcnt(0)
	v_mfma_f32_16x16x32_bf16 v[62:65], v[126:129], v[172:175], v[62:65]
	v_mfma_f32_16x16x32_bf16 v[54:57], v[138:141], v[172:175], v[54:57]
	v_mfma_f32_16x16x32_bf16 v[46:49], v[126:129], v[180:183], v[46:49]
	v_mfma_f32_16x16x32_bf16 v[38:41], v[138:141], v[180:183], v[38:41]
	v_mfma_f32_16x16x32_bf16 v[30:33], v[126:129], v[194:197], v[30:33]
	v_mfma_f32_16x16x32_bf16 v[22:25], v[138:141], v[194:197], v[22:25]
	v_mfma_f32_16x16x32_bf16 v[14:17], v[126:129], v[208:211], v[14:17]
	v_mfma_f32_16x16x32_bf16 v[6:9], v[138:141], v[208:211], v[6:9]
	v_mfma_f32_16x16x32_bf16 v[62:65], v[134:137], v[176:179], v[62:65]
	v_mfma_f32_16x16x32_bf16 v[54:57], v[142:145], v[176:179], v[54:57]
	v_mfma_f32_16x16x32_bf16 v[46:49], v[134:137], v[190:193], v[46:49]
	v_mfma_f32_16x16x32_bf16 v[38:41], v[142:145], v[190:193], v[38:41]
	v_mfma_f32_16x16x32_bf16 v[30:33], v[134:137], v[198:201], v[30:33]
	v_mfma_f32_16x16x32_bf16 v[22:25], v[142:145], v[198:201], v[22:25]
	v_mfma_f32_16x16x32_bf16 v[14:17], v[134:137], v[212:215], v[14:17]
	v_mfma_f32_16x16x32_bf16 v[6:9], v[142:145], v[212:215], v[6:9]
	v_mfma_f32_16x16x32_bf16 v[58:61], v[146:149], v[172:175], v[58:61]
	v_mfma_f32_16x16x32_bf16 v[50:53], v[154:157], v[172:175], v[50:53]
	v_mfma_f32_16x16x32_bf16 v[42:45], v[146:149], v[180:183], v[42:45]
	v_mfma_f32_16x16x32_bf16 v[34:37], v[154:157], v[180:183], v[34:37]
	v_mfma_f32_16x16x32_bf16 v[26:29], v[146:149], v[194:197], v[26:29]
	v_mfma_f32_16x16x32_bf16 v[18:21], v[154:157], v[194:197], v[18:21]
	v_mfma_f32_16x16x32_bf16 v[10:13], v[146:149], v[208:211], v[10:13]
	v_mfma_f32_16x16x32_bf16 v[2:5], v[154:157], v[208:211], v[2:5]
	v_mfma_f32_16x16x32_bf16 v[58:61], v[150:153], v[176:179], v[58:61]
	v_mfma_f32_16x16x32_bf16 v[50:53], v[158:161], v[176:179], v[50:53]
	v_mfma_f32_16x16x32_bf16 v[42:45], v[150:153], v[190:193], v[42:45]
	v_mfma_f32_16x16x32_bf16 v[34:37], v[158:161], v[190:193], v[34:37]
	v_mfma_f32_16x16x32_bf16 v[26:29], v[150:153], v[198:201], v[26:29]
	v_mfma_f32_16x16x32_bf16 v[18:21], v[158:161], v[198:201], v[18:21]
	v_mfma_f32_16x16x32_bf16 v[10:13], v[150:153], v[212:215], v[10:13]
	v_mfma_f32_16x16x32_bf16 v[2:5], v[158:161], v[212:215], v[2:5]
	s_setprio 0
	s_barrier
	s_add_i32 s33, 0, 0x18000
	s_add_i32 s55, 0, 0x1c000
	v_add_u32_e32 v142, s33, v187
	v_add_u32_e32 v158, s55, v187
	ds_read_b128 v[126:129], v142
	ds_read_b128 v[134:137], v142 offset:1024
	ds_read_b128 v[138:141], v142 offset:2048
	ds_read_b128 v[142:145], v142 offset:3072
	ds_read_b128 v[146:149], v158
	ds_read_b128 v[150:153], v158 offset:1024
	ds_read_b128 v[154:157], v158 offset:2048
	ds_read_b128 v[158:161], v158 offset:3072
	s_add_u32 s0, s4, 0x80000
	s_addc_u32 s1, s5, 0
	s_mov_b32 m0, s35
	v_lshl_add_u64 v[218:219], s[0:1], 0, v[166:167]
	ds_read_b128 v[172:175], v189 offset:32768
	ds_read_b128 v[176:179], v189 offset:33792
	ds_read_b128 v[180:183], v189 offset:34816
	ds_read_b128 v[190:193], v189 offset:35840
	ds_read_b128 v[194:197], v189 offset:36864
	ds_read_b128 v[198:201], v189 offset:37888
	ds_read_b128 v[208:211], v189 offset:38912
	ds_read_b128 v[212:215], v189 offset:39936
	global_load_lds_dwordx4 v[218:219], off
	v_lshl_add_u64 v[218:219], s[0:1], 0, v[164:165]
	s_mov_b32 m0, s36
	s_nop 0
	global_load_lds_dwordx4 v[218:219], off
	s_waitcnt vmcnt(8)
	s_waitcnt lgkmcnt(0)
	s_barrier
	s_setprio 1
	s_waitcnt lgkmcnt(0)
	v_mfma_f32_16x16x32_bf16 v[130:133], v[126:129], v[172:175], v[130:133]
	v_mfma_f32_16x16x32_bf16 v[118:121], v[138:141], v[172:175], v[118:121]
	v_mfma_f32_16x16x32_bf16 v[110:113], v[126:129], v[180:183], v[110:113]
	v_mfma_f32_16x16x32_bf16 v[102:105], v[138:141], v[180:183], v[102:105]
	v_mfma_f32_16x16x32_bf16 v[94:97], v[126:129], v[194:197], v[94:97]
	v_mfma_f32_16x16x32_bf16 v[86:89], v[138:141], v[194:197], v[86:89]
	v_mfma_f32_16x16x32_bf16 v[78:81], v[126:129], v[208:211], v[78:81]
	v_mfma_f32_16x16x32_bf16 v[70:73], v[138:141], v[208:211], v[70:73]
	v_mfma_f32_16x16x32_bf16 v[130:133], v[134:137], v[176:179], v[130:133]
	v_mfma_f32_16x16x32_bf16 v[118:121], v[142:145], v[176:179], v[118:121]
	v_mfma_f32_16x16x32_bf16 v[110:113], v[134:137], v[190:193], v[110:113]
	v_mfma_f32_16x16x32_bf16 v[102:105], v[142:145], v[190:193], v[102:105]
	v_mfma_f32_16x16x32_bf16 v[94:97], v[134:137], v[198:201], v[94:97]
	v_mfma_f32_16x16x32_bf16 v[86:89], v[142:145], v[198:201], v[86:89]
	v_mfma_f32_16x16x32_bf16 v[78:81], v[134:137], v[212:215], v[78:81]
	v_mfma_f32_16x16x32_bf16 v[70:73], v[142:145], v[212:215], v[70:73]
	v_mfma_f32_16x16x32_bf16 v[122:125], v[146:149], v[172:175], v[122:125]
	v_mfma_f32_16x16x32_bf16 v[114:117], v[154:157], v[172:175], v[114:117]
	v_mfma_f32_16x16x32_bf16 v[106:109], v[146:149], v[180:183], v[106:109]
	v_mfma_f32_16x16x32_bf16 v[98:101], v[154:157], v[180:183], v[98:101]
	v_mfma_f32_16x16x32_bf16 v[90:93], v[146:149], v[194:197], v[90:93]
	v_mfma_f32_16x16x32_bf16 v[82:85], v[154:157], v[194:197], v[82:85]
	v_mfma_f32_16x16x32_bf16 v[74:77], v[146:149], v[208:211], v[74:77]
	v_mfma_f32_16x16x32_bf16 v[66:69], v[154:157], v[208:211], v[66:69]
	v_mfma_f32_16x16x32_bf16 v[122:125], v[150:153], v[176:179], v[122:125]
	v_mfma_f32_16x16x32_bf16 v[114:117], v[158:161], v[176:179], v[114:117]
	v_mfma_f32_16x16x32_bf16 v[106:109], v[150:153], v[190:193], v[106:109]
	v_mfma_f32_16x16x32_bf16 v[98:101], v[158:161], v[190:193], v[98:101]
	v_mfma_f32_16x16x32_bf16 v[90:93], v[150:153], v[198:201], v[90:93]
	v_mfma_f32_16x16x32_bf16 v[82:85], v[158:161], v[198:201], v[82:85]
	v_mfma_f32_16x16x32_bf16 v[74:77], v[150:153], v[212:215], v[74:77]
	v_mfma_f32_16x16x32_bf16 v[66:69], v[158:161], v[212:215], v[66:69]
	s_setprio 0
	s_barrier
	s_add_i32 s0, s33, s34
	v_lshl_add_u64 v[184:185], v[184:185], 0, s[80:81]
	s_mov_b32 m0, s0
	ds_read_b128 v[172:175], v189 offset:49152
	ds_read_b128 v[176:179], v189 offset:50176
	ds_read_b128 v[180:183], v189 offset:51200
	ds_read_b128 v[190:193], v189 offset:52224
	ds_read_b128 v[194:197], v189 offset:53248
	ds_read_b128 v[198:201], v189 offset:54272
	ds_read_b128 v[208:211], v189 offset:55296
	ds_read_b128 v[212:215], v189 offset:56320
	global_load_lds_dwordx4 v[184:185], off
	s_add_i32 m0, s0, 0x2000
	s_add_u32 s0, s2, 0x80080
	v_lshl_add_u64 v[184:185], v[204:205], 0, s[80:81]
	s_addc_u32 s1, s3, 0
	s_add_i32 s2, s55, s34
	global_load_lds_dwordx4 v[184:185], off
	v_lshl_add_u64 v[184:185], s[0:1], 0, v[202:203]
	s_mov_b32 m0, s2
	s_nop 0
	global_load_lds_dwordx4 v[184:185], off
	v_lshl_add_u64 v[184:185], s[0:1], 0, v[162:163]
	s_add_i32 m0, s2, 0x2000
	s_nop 0
	global_load_lds_dwordx4 v[184:185], off
	v_lshl_add_u64 v[184:185], v[206:207], 0, s[80:81]
	s_mov_b32 m0, s39
	s_nop 0
	global_load_lds_dwordx4 v[184:185], off
	v_lshl_add_u64 v[184:185], v[216:217], 0, s[80:81]
	s_mov_b32 m0, s40
	s_nop 0
	global_load_lds_dwordx4 v[184:185], off
	s_waitcnt vmcnt(8)
	s_waitcnt lgkmcnt(0)
	s_barrier
	s_setprio 1
	s_waitcnt lgkmcnt(0)
	v_mfma_f32_16x16x32_bf16 v[62:65], v[126:129], v[172:175], v[62:65]
	v_mfma_f32_16x16x32_bf16 v[54:57], v[138:141], v[172:175], v[54:57]
	v_mfma_f32_16x16x32_bf16 v[46:49], v[126:129], v[180:183], v[46:49]
	v_mfma_f32_16x16x32_bf16 v[38:41], v[138:141], v[180:183], v[38:41]
	v_mfma_f32_16x16x32_bf16 v[30:33], v[126:129], v[194:197], v[30:33]
	v_mfma_f32_16x16x32_bf16 v[22:25], v[138:141], v[194:197], v[22:25]
	v_mfma_f32_16x16x32_bf16 v[14:17], v[126:129], v[208:211], v[14:17]
	v_mfma_f32_16x16x32_bf16 v[6:9], v[138:141], v[208:211], v[6:9]
	v_mfma_f32_16x16x32_bf16 v[62:65], v[134:137], v[176:179], v[62:65]
	v_mfma_f32_16x16x32_bf16 v[54:57], v[142:145], v[176:179], v[54:57]
	v_mfma_f32_16x16x32_bf16 v[46:49], v[134:137], v[190:193], v[46:49]
	v_mfma_f32_16x16x32_bf16 v[38:41], v[142:145], v[190:193], v[38:41]
	v_mfma_f32_16x16x32_bf16 v[30:33], v[134:137], v[198:201], v[30:33]
	v_mfma_f32_16x16x32_bf16 v[22:25], v[142:145], v[198:201], v[22:25]
	v_mfma_f32_16x16x32_bf16 v[14:17], v[134:137], v[212:215], v[14:17]
	v_mfma_f32_16x16x32_bf16 v[6:9], v[142:145], v[212:215], v[6:9]
	v_mfma_f32_16x16x32_bf16 v[58:61], v[146:149], v[172:175], v[58:61]
	v_mfma_f32_16x16x32_bf16 v[50:53], v[154:157], v[172:175], v[50:53]
	v_mfma_f32_16x16x32_bf16 v[42:45], v[146:149], v[180:183], v[42:45]
	v_mfma_f32_16x16x32_bf16 v[34:37], v[154:157], v[180:183], v[34:37]
	v_mfma_f32_16x16x32_bf16 v[26:29], v[146:149], v[194:197], v[26:29]
	v_mfma_f32_16x16x32_bf16 v[18:21], v[154:157], v[194:197], v[18:21]
	v_mfma_f32_16x16x32_bf16 v[10:13], v[146:149], v[208:211], v[10:13]
	v_mfma_f32_16x16x32_bf16 v[2:5], v[154:157], v[208:211], v[2:5]
	v_mfma_f32_16x16x32_bf16 v[58:61], v[150:153], v[176:179], v[58:61]
	v_mfma_f32_16x16x32_bf16 v[50:53], v[158:161], v[176:179], v[50:53]
	v_mfma_f32_16x16x32_bf16 v[42:45], v[150:153], v[190:193], v[42:45]
	v_mfma_f32_16x16x32_bf16 v[34:37], v[158:161], v[190:193], v[34:37]
	v_mfma_f32_16x16x32_bf16 v[26:29], v[150:153], v[198:201], v[26:29]
	v_mfma_f32_16x16x32_bf16 v[18:21], v[158:161], v[198:201], v[18:21]
	v_mfma_f32_16x16x32_bf16 v[10:13], v[150:153], v[212:215], v[10:13]
	v_mfma_f32_16x16x32_bf16 v[2:5], v[158:161], v[212:215], v[2:5]
	s_setprio 0
	s_barrier
	s_add_i32 s61, s61, 2
	s_add_u32 s26, s26, 0x100
	s_addc_u32 s27, s27, 0
	s_add_u32 s59, s59, 0x100
	s_addc_u32 s60, s60, 0
	s_cmp_gt_u32 s61, 29
	s_cbranch_scc0 .LBB0_1428
	s_and_b64 vcc, exec, s[10:11]
	s_cbranch_vccz .LBB0_1431
	s_barrier

.LBB0_1594:
	s_add_u32 s0, s28, 0xfff80080
	s_addc_u32 s1, s29, -1
	s_add_i32 s33, 0, 0x10000
	s_cmp_eq_u32 s61, 28
	s_cselect_b32 s5, s19, s1
	s_cselect_b32 s4, s49, s0
	v_add_u32_e32 v140, s33, v143
	s_cselect_b32 s3, s17, s60
	s_cselect_b32 s2, s58, s59
	s_add_i32 s55, 0, 0x14000
	ds_read_b128 v[146:149], v140
	ds_read_b128 v[150:153], v140 offset:1024
	ds_read_b128 v[154:157], v140 offset:2048
	ds_read_b128 v[158:161], v140 offset:3072
	v_add_u32_e32 v140, s55, v143
	ds_read_b128 v[162:165], v140
	ds_read_b128 v[166:169], v140 offset:1024
	ds_read_b128 v[170:173], v140 offset:2048
	ds_read_b128 v[174:177], v140 offset:3072
	v_lshl_add_u64 v[140:141], s[28:29], 0, v[136:137]
	s_add_i32 m0, s25, 0xc000
	ds_read_b128 v[178:181], v145
	ds_read_b128 v[182:185], v145 offset:1024
	ds_read_b128 v[186:189], v145 offset:2048
	ds_read_b128 v[190:193], v145 offset:3072
	ds_read_b128 v[194:197], v145 offset:4096
	ds_read_b128 v[198:201], v145 offset:5120
	ds_read_b128 v[208:211], v145 offset:6144
	ds_read_b128 v[212:215], v145 offset:7168
	global_load_lds_dwordx4 v[140:141], off
	v_lshl_add_u64 v[140:141], s[28:29], 0, v[138:139]
	s_add_i32 m0, s25, 0xe000
	s_nop 0
	global_load_lds_dwordx4 v[140:141], off
	s_waitcnt vmcnt(8)
	s_waitcnt lgkmcnt(0)
	s_barrier
	s_setprio 1
	s_waitcnt lgkmcnt(0)
	v_mfma_f32_16x16x32_bf16 v[126:129], v[146:149], v[178:181], v[126:129]
	v_mfma_f32_16x16x32_bf16 v[118:121], v[154:157], v[178:181], v[118:121]
	v_mfma_f32_16x16x32_bf16 v[110:113], v[146:149], v[186:189], v[110:113]
	v_mfma_f32_16x16x32_bf16 v[102:105], v[154:157], v[186:189], v[102:105]
	v_mfma_f32_16x16x32_bf16 v[94:97], v[146:149], v[194:197], v[94:97]
	v_mfma_f32_16x16x32_bf16 v[86:89], v[154:157], v[194:197], v[86:89]
	v_mfma_f32_16x16x32_bf16 v[78:81], v[146:149], v[208:211], v[78:81]
	v_mfma_f32_16x16x32_bf16 v[70:73], v[154:157], v[208:211], v[70:73]
	v_mfma_f32_16x16x32_bf16 v[126:129], v[150:153], v[182:185], v[126:129]
	v_mfma_f32_16x16x32_bf16 v[118:121], v[158:161], v[182:185], v[118:121]
	v_mfma_f32_16x16x32_bf16 v[110:113], v[150:153], v[190:193], v[110:113]
	v_mfma_f32_16x16x32_bf16 v[102:105], v[158:161], v[190:193], v[102:105]
	v_mfma_f32_16x16x32_bf16 v[94:97], v[150:153], v[198:201], v[94:97]
	v_mfma_f32_16x16x32_bf16 v[86:89], v[158:161], v[198:201], v[86:89]
	v_mfma_f32_16x16x32_bf16 v[78:81], v[150:153], v[212:215], v[78:81]
	v_mfma_f32_16x16x32_bf16 v[70:73], v[158:161], v[212:215], v[70:73]
	v_mfma_f32_16x16x32_bf16 v[122:125], v[162:165], v[178:181], v[122:125]
	v_mfma_f32_16x16x32_bf16 v[114:117], v[170:173], v[178:181], v[114:117]
	v_mfma_f32_16x16x32_bf16 v[106:109], v[162:165], v[186:189], v[106:109]
	v_mfma_f32_16x16x32_bf16 v[98:101], v[170:173], v[186:189], v[98:101]
	v_mfma_f32_16x16x32_bf16 v[90:93], v[162:165], v[194:197], v[90:93]
	v_mfma_f32_16x16x32_bf16 v[82:85], v[170:173], v[194:197], v[82:85]
	v_mfma_f32_16x16x32_bf16 v[74:77], v[162:165], v[208:211], v[74:77]
	v_mfma_f32_16x16x32_bf16 v[66:69], v[170:173], v[208:211], v[66:69]
	v_mfma_f32_16x16x32_bf16 v[122:125], v[166:169], v[182:185], v[122:125]
	v_mfma_f32_16x16x32_bf16 v[114:117], v[174:177], v[182:185], v[114:117]
	v_mfma_f32_16x16x32_bf16 v[106:109], v[166:169], v[190:193], v[106:109]
	v_mfma_f32_16x16x32_bf16 v[98:101], v[174:177], v[190:193], v[98:101]
	v_mfma_f32_16x16x32_bf16 v[90:93], v[166:169], v[198:201], v[90:93]
	v_mfma_f32_16x16x32_bf16 v[82:85], v[174:177], v[198:201], v[82:85]
	v_mfma_f32_16x16x32_bf16 v[74:77], v[166:169], v[212:215], v[74:77]
	v_mfma_f32_16x16x32_bf16 v[66:69], v[174:177], v[212:215], v[66:69]
	s_setprio 0
	s_barrier
	s_add_i32 s0, s33, s36
	v_lshl_add_u64 v[140:141], s[2:3], 0, v[202:203]
	s_mov_b32 m0, s0
	ds_read_b128 v[178:181], v145 offset:16384
	ds_read_b128 v[182:185], v145 offset:17408
	ds_read_b128 v[186:189], v145 offset:18432
	ds_read_b128 v[190:193], v145 offset:19456
	ds_read_b128 v[194:197], v145 offset:20480
	ds_read_b128 v[198:201], v145 offset:21504
	ds_read_b128 v[208:211], v145 offset:22528
	ds_read_b128 v[212:215], v145 offset:23552
	global_load_lds_dwordx4 v[140:141], off
	s_add_i32 m0, s0, 0x2000
	s_add_u32 s0, s2, 0x80000
	v_lshl_add_u64 v[204:205], s[2:3], 0, v[130:131]
	s_addc_u32 s1, s3, 0
	s_add_i32 s33, s55, s36
	global_load_lds_dwordx4 v[204:205], off
	v_lshl_add_u64 v[206:207], s[0:1], 0, v[202:203]
	s_mov_b32 m0, s33
	v_lshl_add_u64 v[216:217], s[4:5], 0, v[132:133]
	global_load_lds_dwordx4 v[206:207], off
	v_lshl_add_u64 v[206:207], s[0:1], 0, v[130:131]
	s_add_i32 m0, s33, 0x2000
	s_nop 0
	global_load_lds_dwordx4 v[206:207], off
	v_lshl_add_u64 v[206:207], s[4:5], 0, v[134:135]
	s_mov_b32 m0, s25
	s_nop 0
	global_load_lds_dwordx4 v[206:207], off
	s_mov_b32 m0, s27
	s_nop 0
	global_load_lds_dwordx4 v[216:217], off
	s_waitcnt vmcnt(8)
	s_waitcnt lgkmcnt(0)
	s_barrier
	s_setprio 1
	s_waitcnt lgkmcnt(0)
	v_mfma_f32_16x16x32_bf16 v[62:65], v[146:149], v[178:181], v[62:65]
	v_mfma_f32_16x16x32_bf16 v[54:57], v[154:157], v[178:181], v[54:57]
	v_mfma_f32_16x16x32_bf16 v[46:49], v[146:149], v[186:189], v[46:49]
	v_mfma_f32_16x16x32_bf16 v[38:41], v[154:157], v[186:189], v[38:41]
	v_mfma_f32_16x16x32_bf16 v[30:33], v[146:149], v[194:197], v[30:33]
	v_mfma_f32_16x16x32_bf16 v[22:25], v[154:157], v[194:197], v[22:25]
	v_mfma_f32_16x16x32_bf16 v[14:17], v[146:149], v[208:211], v[14:17]
	v_mfma_f32_16x16x32_bf16 v[6:9], v[154:157], v[208:211], v[6:9]
	v_mfma_f32_16x16x32_bf16 v[62:65], v[150:153], v[182:185], v[62:65]
	v_mfma_f32_16x16x32_bf16 v[54:57], v[158:161], v[182:185], v[54:57]
	v_mfma_f32_16x16x32_bf16 v[46:49], v[150:153], v[190:193], v[46:49]
	v_mfma_f32_16x16x32_bf16 v[38:41], v[158:161], v[190:193], v[38:41]
	v_mfma_f32_16x16x32_bf16 v[30:33], v[150:153], v[198:201], v[30:33]
	v_mfma_f32_16x16x32_bf16 v[22:25], v[158:161], v[198:201], v[22:25]
	v_mfma_f32_16x16x32_bf16 v[14:17], v[150:153], v[212:215], v[14:17]
	v_mfma_f32_16x16x32_bf16 v[6:9], v[158:161], v[212:215], v[6:9]
	v_mfma_f32_16x16x32_bf16 v[58:61], v[162:165], v[178:181], v[58:61]
	v_mfma_f32_16x16x32_bf16 v[50:53], v[170:173], v[178:181], v[50:53]
	v_mfma_f32_16x16x32_bf16 v[42:45], v[162:165], v[186:189], v[42:45]
	v_mfma_f32_16x16x32_bf16 v[34:37], v[170:173], v[186:189], v[34:37]
	v_mfma_f32_16x16x32_bf16 v[26:29], v[162:165], v[194:197], v[26:29]
	v_mfma_f32_16x16x32_bf16 v[18:21], v[170:173], v[194:197], v[18:21]
	v_mfma_f32_16x16x32_bf16 v[10:13], v[162:165], v[208:211], v[10:13]
	v_mfma_f32_16x16x32_bf16 v[2:5], v[170:173], v[208:211], v[2:5]
	v_mfma_f32_16x16x32_bf16 v[58:61], v[166:169], v[182:185], v[58:61]
	v_mfma_f32_16x16x32_bf16 v[50:53], v[174:177], v[182:185], v[50:53]
	v_mfma_f32_16x16x32_bf16 v[42:45], v[166:169], v[190:193], v[42:45]
	v_mfma_f32_16x16x32_bf16 v[34:37], v[174:177], v[190:193], v[34:37]
	v_mfma_f32_16x16x32_bf16 v[26:29], v[166:169], v[198:201], v[26:29]
	v_mfma_f32_16x16x32_bf16 v[18:21], v[174:177], v[198:201], v[18:21]
	v_mfma_f32_16x16x32_bf16 v[10:13], v[166:169], v[212:215], v[10:13]
	v_mfma_f32_16x16x32_bf16 v[2:5], v[174:177], v[212:215], v[2:5]
	s_setprio 0
	s_barrier
	s_add_i32 s33, 0, 0x18000
	s_add_i32 s55, 0, 0x1c000
	v_add_u32_e32 v158, s33, v143
	v_add_u32_e32 v174, s55, v143
	ds_read_b128 v[146:149], v158
	ds_read_b128 v[150:153], v158 offset:1024
	ds_read_b128 v[154:157], v158 offset:2048
	ds_read_b128 v[158:161], v158 offset:3072
	ds_read_b128 v[162:165], v174
	ds_read_b128 v[166:169], v174 offset:1024
	ds_read_b128 v[170:173], v174 offset:2048
	ds_read_b128 v[174:177], v174 offset:3072
	s_add_u32 s0, s4, 0x80000
	s_addc_u32 s1, s5, 0
	s_mov_b32 m0, s37
	v_lshl_add_u64 v[218:219], s[0:1], 0, v[134:135]
	ds_read_b128 v[178:181], v145 offset:32768
	ds_read_b128 v[182:185], v145 offset:33792
	ds_read_b128 v[186:189], v145 offset:34816
	ds_read_b128 v[190:193], v145 offset:35840
	ds_read_b128 v[194:197], v145 offset:36864
	ds_read_b128 v[198:201], v145 offset:37888
	ds_read_b128 v[208:211], v145 offset:38912
	ds_read_b128 v[212:215], v145 offset:39936
	global_load_lds_dwordx4 v[218:219], off
	v_lshl_add_u64 v[218:219], s[0:1], 0, v[132:133]
	s_mov_b32 m0, s38
	s_nop 0
	global_load_lds_dwordx4 v[218:219], off
	s_waitcnt vmcnt(8)
	s_waitcnt lgkmcnt(0)
	s_barrier
	s_setprio 1
	s_waitcnt lgkmcnt(0)
	v_mfma_f32_16x16x32_bf16 v[126:129], v[146:149], v[178:181], v[126:129]
	v_mfma_f32_16x16x32_bf16 v[118:121], v[154:157], v[178:181], v[118:121]
	v_mfma_f32_16x16x32_bf16 v[110:113], v[146:149], v[186:189], v[110:113]
	v_mfma_f32_16x16x32_bf16 v[102:105], v[154:157], v[186:189], v[102:105]
	v_mfma_f32_16x16x32_bf16 v[94:97], v[146:149], v[194:197], v[94:97]
	v_mfma_f32_16x16x32_bf16 v[86:89], v[154:157], v[194:197], v[86:89]
	v_mfma_f32_16x16x32_bf16 v[78:81], v[146:149], v[208:211], v[78:81]
	v_mfma_f32_16x16x32_bf16 v[70:73], v[154:157], v[208:211], v[70:73]
	v_mfma_f32_16x16x32_bf16 v[126:129], v[150:153], v[182:185], v[126:129]
	v_mfma_f32_16x16x32_bf16 v[118:121], v[158:161], v[182:185], v[118:121]
	v_mfma_f32_16x16x32_bf16 v[110:113], v[150:153], v[190:193], v[110:113]
	v_mfma_f32_16x16x32_bf16 v[102:105], v[158:161], v[190:193], v[102:105]
	v_mfma_f32_16x16x32_bf16 v[94:97], v[150:153], v[198:201], v[94:97]
	v_mfma_f32_16x16x32_bf16 v[86:89], v[158:161], v[198:201], v[86:89]
	v_mfma_f32_16x16x32_bf16 v[78:81], v[150:153], v[212:215], v[78:81]
	v_mfma_f32_16x16x32_bf16 v[70:73], v[158:161], v[212:215], v[70:73]
	v_mfma_f32_16x16x32_bf16 v[122:125], v[162:165], v[178:181], v[122:125]
	v_mfma_f32_16x16x32_bf16 v[114:117], v[170:173], v[178:181], v[114:117]
	v_mfma_f32_16x16x32_bf16 v[106:109], v[162:165], v[186:189], v[106:109]
	v_mfma_f32_16x16x32_bf16 v[98:101], v[170:173], v[186:189], v[98:101]
	v_mfma_f32_16x16x32_bf16 v[90:93], v[162:165], v[194:197], v[90:93]
	v_mfma_f32_16x16x32_bf16 v[82:85], v[170:173], v[194:197], v[82:85]
	v_mfma_f32_16x16x32_bf16 v[74:77], v[162:165], v[208:211], v[74:77]
	v_mfma_f32_16x16x32_bf16 v[66:69], v[170:173], v[208:211], v[66:69]
	v_mfma_f32_16x16x32_bf16 v[122:125], v[166:169], v[182:185], v[122:125]
	v_mfma_f32_16x16x32_bf16 v[114:117], v[174:177], v[182:185], v[114:117]
	v_mfma_f32_16x16x32_bf16 v[106:109], v[166:169], v[190:193], v[106:109]
	v_mfma_f32_16x16x32_bf16 v[98:101], v[174:177], v[190:193], v[98:101]
	v_mfma_f32_16x16x32_bf16 v[90:93], v[166:169], v[198:201], v[90:93]
	v_mfma_f32_16x16x32_bf16 v[82:85], v[174:177], v[198:201], v[82:85]
	v_mfma_f32_16x16x32_bf16 v[74:77], v[166:169], v[212:215], v[74:77]
	v_mfma_f32_16x16x32_bf16 v[66:69], v[174:177], v[212:215], v[66:69]
	s_setprio 0
	s_barrier
	s_add_i32 s0, s33, s36
	v_lshl_add_u64 v[140:141], v[140:141], 0, s[80:81]
	s_mov_b32 m0, s0
	ds_read_b128 v[178:181], v145 offset:49152
	ds_read_b128 v[182:185], v145 offset:50176
	ds_read_b128 v[186:189], v145 offset:51200
	ds_read_b128 v[190:193], v145 offset:52224
	ds_read_b128 v[194:197], v145 offset:53248
	ds_read_b128 v[198:201], v145 offset:54272
	ds_read_b128 v[208:211], v145 offset:55296
	ds_read_b128 v[212:215], v145 offset:56320
	global_load_lds_dwordx4 v[140:141], off
	s_add_i32 m0, s0, 0x2000
	s_add_u32 s0, s2, 0x80080
	v_lshl_add_u64 v[140:141], v[204:205], 0, s[80:81]
	s_addc_u32 s1, s3, 0
	s_add_i32 s2, s55, s36
	global_load_lds_dwordx4 v[140:141], off
	v_lshl_add_u64 v[140:141], s[0:1], 0, v[202:203]
	s_mov_b32 m0, s2
	s_nop 0
	global_load_lds_dwordx4 v[140:141], off
	v_lshl_add_u64 v[140:141], s[0:1], 0, v[130:131]
	s_add_i32 m0, s2, 0x2000
	s_nop 0
	global_load_lds_dwordx4 v[140:141], off
	v_lshl_add_u64 v[140:141], v[206:207], 0, s[80:81]
	s_mov_b32 m0, s39
	s_nop 0
	global_load_lds_dwordx4 v[140:141], off
	v_lshl_add_u64 v[140:141], v[216:217], 0, s[80:81]
	s_mov_b32 m0, s40
	s_nop 0
	global_load_lds_dwordx4 v[140:141], off
	s_waitcnt vmcnt(8)
	s_waitcnt lgkmcnt(0)
	s_barrier
	s_setprio 1
	s_waitcnt lgkmcnt(0)
	v_mfma_f32_16x16x32_bf16 v[62:65], v[146:149], v[178:181], v[62:65]
	v_mfma_f32_16x16x32_bf16 v[54:57], v[154:157], v[178:181], v[54:57]
	v_mfma_f32_16x16x32_bf16 v[46:49], v[146:149], v[186:189], v[46:49]
	v_mfma_f32_16x16x32_bf16 v[38:41], v[154:157], v[186:189], v[38:41]
	v_mfma_f32_16x16x32_bf16 v[30:33], v[146:149], v[194:197], v[30:33]
	v_mfma_f32_16x16x32_bf16 v[22:25], v[154:157], v[194:197], v[22:25]
	v_mfma_f32_16x16x32_bf16 v[14:17], v[146:149], v[208:211], v[14:17]
	v_mfma_f32_16x16x32_bf16 v[6:9], v[154:157], v[208:211], v[6:9]
	v_mfma_f32_16x16x32_bf16 v[62:65], v[150:153], v[182:185], v[62:65]
	v_mfma_f32_16x16x32_bf16 v[54:57], v[158:161], v[182:185], v[54:57]
	v_mfma_f32_16x16x32_bf16 v[46:49], v[150:153], v[190:193], v[46:49]
	v_mfma_f32_16x16x32_bf16 v[38:41], v[158:161], v[190:193], v[38:41]
	v_mfma_f32_16x16x32_bf16 v[30:33], v[150:153], v[198:201], v[30:33]
	v_mfma_f32_16x16x32_bf16 v[22:25], v[158:161], v[198:201], v[22:25]
	v_mfma_f32_16x16x32_bf16 v[14:17], v[150:153], v[212:215], v[14:17]
	v_mfma_f32_16x16x32_bf16 v[6:9], v[158:161], v[212:215], v[6:9]
	v_mfma_f32_16x16x32_bf16 v[58:61], v[162:165], v[178:181], v[58:61]
	v_mfma_f32_16x16x32_bf16 v[50:53], v[170:173], v[178:181], v[50:53]
	v_mfma_f32_16x16x32_bf16 v[42:45], v[162:165], v[186:189], v[42:45]
	v_mfma_f32_16x16x32_bf16 v[34:37], v[170:173], v[186:189], v[34:37]
	v_mfma_f32_16x16x32_bf16 v[26:29], v[162:165], v[194:197], v[26:29]
	v_mfma_f32_16x16x32_bf16 v[18:21], v[170:173], v[194:197], v[18:21]
	v_mfma_f32_16x16x32_bf16 v[10:13], v[162:165], v[208:211], v[10:13]
	v_mfma_f32_16x16x32_bf16 v[2:5], v[170:173], v[208:211], v[2:5]
	v_mfma_f32_16x16x32_bf16 v[58:61], v[166:169], v[182:185], v[58:61]
	v_mfma_f32_16x16x32_bf16 v[50:53], v[174:177], v[182:185], v[50:53]
	v_mfma_f32_16x16x32_bf16 v[42:45], v[166:169], v[190:193], v[42:45]
	v_mfma_f32_16x16x32_bf16 v[34:37], v[174:177], v[190:193], v[34:37]
	v_mfma_f32_16x16x32_bf16 v[26:29], v[166:169], v[198:201], v[26:29]
	v_mfma_f32_16x16x32_bf16 v[18:21], v[174:177], v[198:201], v[18:21]
	v_mfma_f32_16x16x32_bf16 v[10:13], v[166:169], v[212:215], v[10:13]
	v_mfma_f32_16x16x32_bf16 v[2:5], v[174:177], v[212:215], v[2:5]
	s_setprio 0
	s_barrier
	s_add_i32 s61, s61, 2
	s_add_u32 s28, s28, 0x100
	s_addc_u32 s29, s29, 0
	s_add_u32 s59, s59, 0x100
	s_addc_u32 s60, s60, 0
	s_cmp_gt_u32 s61, 29
	s_cbranch_scc0 .LBB0_1594
	s_and_b64 vcc, exec, s[14:15]
	s_cbranch_vccz .LBB0_1597
	s_barrier

.LBB0_1718:
	s_add_u32 s18, s4, 0x100
	s_addc_u32 s19, s5, 0
	s_add_i32 s0, 0, 0x10000
	s_cmpk_eq_i32 s59, 0x54
	s_cselect_b32 s23, s9, s19
	s_cselect_b32 s22, s8, s18
	s_cselect_b32 s21, s17, s58
	s_cselect_b32 s20, s16, s49
	s_add_i32 s33, 0, 0x14000
	v_add_u32_e32 v98, s0, v205
	v_add_u32_e32 v134, s33, v205
	ds_read_b128 v[78:81], v98
	ds_read_b128 v[82:85], v98 offset:1024
	ds_read_b128 v[94:97], v98 offset:2048
	ds_read_b128 v[98:101], v98 offset:3072
	ds_read_b128 v[106:109], v134
	ds_read_b128 v[110:113], v134 offset:1024
	ds_read_b128 v[126:129], v134 offset:2048
	ds_read_b128 v[134:137], v134 offset:3072
	v_lshl_add_u64 v[194:195], s[4:5], 0, v[214:215]
	s_add_i32 m0, s27, 0xc000
	ds_read_b128 v[146:149], v239
	ds_read_b128 v[158:161], v239 offset:1024
	ds_read_b128 v[166:169], v239 offset:2048
	ds_read_b128 v[174:177], v239 offset:3072
	ds_read_b128 v[178:181], v239 offset:4096
	ds_read_b128 v[182:185], v239 offset:5120
	ds_read_b128 v[186:189], v239 offset:6144
	ds_read_b128 v[190:193], v239 offset:7168
	global_load_lds_dwordx4 v[194:195], off
	v_lshl_add_u64 v[194:195], s[4:5], 0, v[216:217]
	s_add_i32 m0, s27, 0xe000
	s_nop 0
	global_load_lds_dwordx4 v[194:195], off
	s_waitcnt vmcnt(8)
	s_waitcnt lgkmcnt(0)
	s_barrier
	s_setprio 1
	s_waitcnt lgkmcnt(0)
	v_mfma_f32_16x16x32_bf16 v[170:173], v[78:81], v[146:149], v[170:173]
	v_mfma_f32_16x16x32_bf16 v[162:165], v[94:97], v[146:149], v[162:165]
	v_mfma_f32_16x16x32_bf16 v[142:145], v[78:81], v[166:169], v[142:145]
	v_mfma_f32_16x16x32_bf16 v[138:141], v[94:97], v[166:169], v[138:141]
	v_mfma_f32_16x16x32_bf16 v[118:121], v[78:81], v[178:181], v[118:121]
	v_mfma_f32_16x16x32_bf16 v[114:117], v[94:97], v[178:181], v[114:117]
	v_mfma_f32_16x16x32_bf16 v[86:89], v[78:81], v[186:189], v[86:89]
	v_mfma_f32_16x16x32_bf16 v[74:77], v[94:97], v[186:189], v[74:77]
	v_mfma_f32_16x16x32_bf16 v[170:173], v[82:85], v[158:161], v[170:173]
	v_mfma_f32_16x16x32_bf16 v[162:165], v[98:101], v[158:161], v[162:165]
	v_mfma_f32_16x16x32_bf16 v[142:145], v[82:85], v[174:177], v[142:145]
	v_mfma_f32_16x16x32_bf16 v[138:141], v[98:101], v[174:177], v[138:141]
	v_mfma_f32_16x16x32_bf16 v[118:121], v[82:85], v[182:185], v[118:121]
	v_mfma_f32_16x16x32_bf16 v[114:117], v[98:101], v[182:185], v[114:117]
	v_mfma_f32_16x16x32_bf16 v[86:89], v[82:85], v[190:193], v[86:89]
	v_mfma_f32_16x16x32_bf16 v[74:77], v[98:101], v[190:193], v[74:77]
	v_mfma_f32_16x16x32_bf16 v[154:157], v[106:109], v[146:149], v[154:157]
	v_mfma_f32_16x16x32_bf16 v[130:133], v[106:109], v[166:169], v[130:133]
	v_mfma_f32_16x16x32_bf16 v[122:125], v[126:129], v[166:169], v[122:125]
	v_mfma_f32_16x16x32_bf16 v[102:105], v[106:109], v[178:181], v[102:105]
	v_mfma_f32_16x16x32_bf16 v[90:93], v[126:129], v[178:181], v[90:93]
	v_mfma_f32_16x16x32_bf16 v[70:73], v[106:109], v[186:189], v[70:73]
	v_mfma_f32_16x16x32_bf16 v[66:69], v[126:129], v[186:189], v[66:69]
	v_mfma_f32_16x16x32_bf16 v[154:157], v[110:113], v[158:161], v[154:157]
	v_mfma_f32_16x16x32_bf16 v[146:149], v[126:129], v[146:149], v[150:153]
	v_mfma_f32_16x16x32_bf16 v[130:133], v[110:113], v[174:177], v[130:133]
	v_mfma_f32_16x16x32_bf16 v[122:125], v[134:137], v[174:177], v[122:125]
	v_mfma_f32_16x16x32_bf16 v[102:105], v[110:113], v[182:185], v[102:105]
	v_mfma_f32_16x16x32_bf16 v[90:93], v[134:137], v[182:185], v[90:93]
	v_mfma_f32_16x16x32_bf16 v[70:73], v[110:113], v[190:193], v[70:73]
	v_mfma_f32_16x16x32_bf16 v[66:69], v[134:137], v[190:193], v[66:69]
	v_mfma_f32_16x16x32_bf16 v[146:149], v[134:137], v[158:161], v[146:149]
	s_setprio 0
	s_barrier
	s_add_i32 s0, s0, s26
	v_lshl_add_u64 v[194:195], s[20:21], 0, v[202:203]
	s_mov_b32 m0, s0
	ds_read_b128 v[150:153], v239 offset:16384
	ds_read_b128 v[158:161], v239 offset:17408
	ds_read_b128 v[166:169], v239 offset:18432
	ds_read_b128 v[174:177], v239 offset:19456
	ds_read_b128 v[178:181], v239 offset:20480
	ds_read_b128 v[182:185], v239 offset:21504
	ds_read_b128 v[186:189], v239 offset:22528
	ds_read_b128 v[190:193], v239 offset:23552
	global_load_lds_dwordx4 v[194:195], off
	s_add_i32 m0, s0, 0x2000
	s_add_u32 s0, s20, 0x160000
	v_lshl_add_u64 v[196:197], s[20:21], 0, v[208:209]
	s_addc_u32 s1, s21, 0
	s_add_i32 s4, s33, s26
	global_load_lds_dwordx4 v[196:197], off
	v_lshl_add_u64 v[198:199], s[0:1], 0, v[202:203]
	s_mov_b32 m0, s4
	v_lshl_add_u64 v[200:201], s[22:23], 0, v[210:211]
	global_load_lds_dwordx4 v[198:199], off
	v_lshl_add_u64 v[198:199], s[0:1], 0, v[208:209]
	s_add_i32 m0, s4, 0x2000
	s_nop 0
	global_load_lds_dwordx4 v[198:199], off
	v_lshl_add_u64 v[198:199], s[22:23], 0, v[212:213]
	s_mov_b32 m0, s27
	s_nop 0
	global_load_lds_dwordx4 v[198:199], off
	s_mov_b32 m0, s28
	s_nop 0
	global_load_lds_dwordx4 v[200:201], off
	s_waitcnt vmcnt(8)
	s_waitcnt lgkmcnt(0)
	s_barrier
	s_setprio 1
	s_waitcnt lgkmcnt(0)
	v_mfma_f32_16x16x32_bf16 v[62:65], v[78:81], v[150:153], v[62:65]
	v_mfma_f32_16x16x32_bf16 v[58:61], v[94:97], v[150:153], v[58:61]
	v_mfma_f32_16x16x32_bf16 v[46:49], v[78:81], v[166:169], v[46:49]
	v_mfma_f32_16x16x32_bf16 v[42:45], v[94:97], v[166:169], v[42:45]
	v_mfma_f32_16x16x32_bf16 v[30:33], v[78:81], v[178:181], v[30:33]
	v_mfma_f32_16x16x32_bf16 v[26:29], v[94:97], v[178:181], v[26:29]
	v_mfma_f32_16x16x32_bf16 v[14:17], v[78:81], v[186:189], v[14:17]
	v_mfma_f32_16x16x32_bf16 v[10:13], v[94:97], v[186:189], v[10:13]
	v_mfma_f32_16x16x32_bf16 v[62:65], v[82:85], v[158:161], v[62:65]
	v_mfma_f32_16x16x32_bf16 v[58:61], v[98:101], v[158:161], v[58:61]
	v_mfma_f32_16x16x32_bf16 v[46:49], v[82:85], v[174:177], v[46:49]
	v_mfma_f32_16x16x32_bf16 v[42:45], v[98:101], v[174:177], v[42:45]
	v_mfma_f32_16x16x32_bf16 v[30:33], v[82:85], v[182:185], v[30:33]
	v_mfma_f32_16x16x32_bf16 v[26:29], v[98:101], v[182:185], v[26:29]
	v_mfma_f32_16x16x32_bf16 v[14:17], v[82:85], v[190:193], v[14:17]
	v_mfma_f32_16x16x32_bf16 v[10:13], v[98:101], v[190:193], v[10:13]
	v_mfma_f32_16x16x32_bf16 v[54:57], v[106:109], v[150:153], v[54:57]
	v_mfma_f32_16x16x32_bf16 v[50:53], v[126:129], v[150:153], v[50:53]
	v_mfma_f32_16x16x32_bf16 v[38:41], v[106:109], v[166:169], v[38:41]
	v_mfma_f32_16x16x32_bf16 v[34:37], v[126:129], v[166:169], v[34:37]
	v_mfma_f32_16x16x32_bf16 v[22:25], v[106:109], v[178:181], v[22:25]
	v_mfma_f32_16x16x32_bf16 v[18:21], v[126:129], v[178:181], v[18:21]
	v_mfma_f32_16x16x32_bf16 v[6:9], v[106:109], v[186:189], v[6:9]
	v_mfma_f32_16x16x32_bf16 v[2:5], v[126:129], v[186:189], v[2:5]
	v_mfma_f32_16x16x32_bf16 v[54:57], v[110:113], v[158:161], v[54:57]
	v_mfma_f32_16x16x32_bf16 v[50:53], v[134:137], v[158:161], v[50:53]
	v_mfma_f32_16x16x32_bf16 v[38:41], v[110:113], v[174:177], v[38:41]
	v_mfma_f32_16x16x32_bf16 v[34:37], v[134:137], v[174:177], v[34:37]
	v_mfma_f32_16x16x32_bf16 v[22:25], v[110:113], v[182:185], v[22:25]
	v_mfma_f32_16x16x32_bf16 v[18:21], v[134:137], v[182:185], v[18:21]
	v_mfma_f32_16x16x32_bf16 v[6:9], v[110:113], v[190:193], v[6:9]
	v_mfma_f32_16x16x32_bf16 v[2:5], v[134:137], v[190:193], v[2:5]
	s_setprio 0
	s_barrier
	s_add_i32 s4, 0, 0x18000
	s_add_i32 s5, 0, 0x1c000
	v_add_u32_e32 v98, s4, v205
	v_add_u32_e32 v134, s5, v205
	ds_read_b128 v[78:81], v98
	ds_read_b128 v[82:85], v98 offset:1024
	ds_read_b128 v[94:97], v98 offset:2048
	ds_read_b128 v[98:101], v98 offset:3072
	ds_read_b128 v[106:109], v134
	ds_read_b128 v[110:113], v134 offset:1024
	ds_read_b128 v[126:129], v134 offset:2048
	ds_read_b128 v[134:137], v134 offset:3072
	s_add_u32 s0, s22, 0x160000
	s_addc_u32 s1, s23, 0
	s_mov_b32 m0, s29
	v_lshl_add_u64 v[206:207], s[0:1], 0, v[212:213]
	ds_read_b128 v[150:153], v239 offset:32768
	ds_read_b128 v[158:161], v239 offset:33792
	ds_read_b128 v[166:169], v239 offset:34816
	ds_read_b128 v[174:177], v239 offset:35840
	ds_read_b128 v[178:181], v239 offset:36864
	ds_read_b128 v[182:185], v239 offset:37888
	ds_read_b128 v[186:189], v239 offset:38912
	ds_read_b128 v[190:193], v239 offset:39936
	global_load_lds_dwordx4 v[206:207], off
	v_lshl_add_u64 v[206:207], s[0:1], 0, v[210:211]
	s_mov_b32 m0, s30
	s_nop 0
	global_load_lds_dwordx4 v[206:207], off
	s_waitcnt vmcnt(8)
	s_waitcnt lgkmcnt(0)
	s_barrier
	s_setprio 1
	s_waitcnt lgkmcnt(0)
	v_mfma_f32_16x16x32_bf16 v[170:173], v[78:81], v[150:153], v[170:173]
	v_mfma_f32_16x16x32_bf16 v[162:165], v[94:97], v[150:153], v[162:165]
	v_mfma_f32_16x16x32_bf16 v[142:145], v[78:81], v[166:169], v[142:145]
	v_mfma_f32_16x16x32_bf16 v[138:141], v[94:97], v[166:169], v[138:141]
	v_mfma_f32_16x16x32_bf16 v[118:121], v[78:81], v[178:181], v[118:121]
	v_mfma_f32_16x16x32_bf16 v[114:117], v[94:97], v[178:181], v[114:117]
	v_mfma_f32_16x16x32_bf16 v[86:89], v[78:81], v[186:189], v[86:89]
	v_mfma_f32_16x16x32_bf16 v[74:77], v[94:97], v[186:189], v[74:77]
	v_mfma_f32_16x16x32_bf16 v[170:173], v[82:85], v[158:161], v[170:173]
	v_mfma_f32_16x16x32_bf16 v[162:165], v[98:101], v[158:161], v[162:165]
	v_mfma_f32_16x16x32_bf16 v[142:145], v[82:85], v[174:177], v[142:145]
	v_mfma_f32_16x16x32_bf16 v[138:141], v[98:101], v[174:177], v[138:141]
	v_mfma_f32_16x16x32_bf16 v[118:121], v[82:85], v[182:185], v[118:121]
	v_mfma_f32_16x16x32_bf16 v[114:117], v[98:101], v[182:185], v[114:117]
	v_mfma_f32_16x16x32_bf16 v[86:89], v[82:85], v[190:193], v[86:89]
	v_mfma_f32_16x16x32_bf16 v[74:77], v[98:101], v[190:193], v[74:77]
	v_mfma_f32_16x16x32_bf16 v[154:157], v[106:109], v[150:153], v[154:157]
	v_mfma_f32_16x16x32_bf16 v[146:149], v[126:129], v[150:153], v[146:149]
	v_mfma_f32_16x16x32_bf16 v[130:133], v[106:109], v[166:169], v[130:133]
	v_mfma_f32_16x16x32_bf16 v[122:125], v[126:129], v[166:169], v[122:125]
	v_mfma_f32_16x16x32_bf16 v[102:105], v[106:109], v[178:181], v[102:105]
	v_mfma_f32_16x16x32_bf16 v[90:93], v[126:129], v[178:181], v[90:93]
	v_mfma_f32_16x16x32_bf16 v[70:73], v[106:109], v[186:189], v[70:73]
	v_mfma_f32_16x16x32_bf16 v[66:69], v[126:129], v[186:189], v[66:69]
	v_mfma_f32_16x16x32_bf16 v[154:157], v[110:113], v[158:161], v[154:157]
	v_mfma_f32_16x16x32_bf16 v[150:153], v[134:137], v[158:161], v[146:149]
	v_mfma_f32_16x16x32_bf16 v[130:133], v[110:113], v[174:177], v[130:133]
	v_mfma_f32_16x16x32_bf16 v[122:125], v[134:137], v[174:177], v[122:125]
	v_mfma_f32_16x16x32_bf16 v[102:105], v[110:113], v[182:185], v[102:105]
	v_mfma_f32_16x16x32_bf16 v[90:93], v[134:137], v[182:185], v[90:93]
	v_mfma_f32_16x16x32_bf16 v[70:73], v[110:113], v[190:193], v[70:73]
	v_mfma_f32_16x16x32_bf16 v[66:69], v[134:137], v[190:193], v[66:69]
	s_setprio 0
	s_barrier
	s_add_i32 s0, s4, s26
	v_lshl_add_u64 v[194:195], v[194:195], 0, s[80:81]
	s_mov_b32 m0, s0
	ds_read_b128 v[146:149], v239 offset:49152
	ds_read_b128 v[158:161], v239 offset:50176
	ds_read_b128 v[166:169], v239 offset:51200
	ds_read_b128 v[174:177], v239 offset:52224
	ds_read_b128 v[178:181], v239 offset:53248
	ds_read_b128 v[182:185], v239 offset:54272
	ds_read_b128 v[186:189], v239 offset:55296
	ds_read_b128 v[190:193], v239 offset:56320
	global_load_lds_dwordx4 v[194:195], off
	s_add_i32 m0, s0, 0x2000
	s_add_u32 s0, s20, 0x160080
	v_lshl_add_u64 v[194:195], v[196:197], 0, s[80:81]
	s_addc_u32 s1, s21, 0
	s_add_i32 s4, s5, s26
	global_load_lds_dwordx4 v[194:195], off
	v_lshl_add_u64 v[194:195], s[0:1], 0, v[202:203]
	s_mov_b32 m0, s4
	s_nop 0
	global_load_lds_dwordx4 v[194:195], off
	v_lshl_add_u64 v[194:195], s[0:1], 0, v[208:209]
	s_add_i32 m0, s4, 0x2000
	s_nop 0
	global_load_lds_dwordx4 v[194:195], off
	v_lshl_add_u64 v[194:195], v[198:199], 0, s[80:81]
	s_mov_b32 m0, s35
	s_nop 0
	global_load_lds_dwordx4 v[194:195], off
	v_lshl_add_u64 v[194:195], v[200:201], 0, s[80:81]
	s_mov_b32 m0, s36
	s_nop 0
	global_load_lds_dwordx4 v[194:195], off
	s_waitcnt vmcnt(8)
	s_waitcnt lgkmcnt(0)
	s_barrier
	s_setprio 1
	s_waitcnt lgkmcnt(0)
	v_mfma_f32_16x16x32_bf16 v[62:65], v[78:81], v[146:149], v[62:65]
	v_mfma_f32_16x16x32_bf16 v[58:61], v[94:97], v[146:149], v[58:61]
	v_mfma_f32_16x16x32_bf16 v[46:49], v[78:81], v[166:169], v[46:49]
	v_mfma_f32_16x16x32_bf16 v[42:45], v[94:97], v[166:169], v[42:45]
	v_mfma_f32_16x16x32_bf16 v[30:33], v[78:81], v[178:181], v[30:33]
	v_mfma_f32_16x16x32_bf16 v[26:29], v[94:97], v[178:181], v[26:29]
	v_mfma_f32_16x16x32_bf16 v[14:17], v[78:81], v[186:189], v[14:17]
	v_mfma_f32_16x16x32_bf16 v[10:13], v[94:97], v[186:189], v[10:13]
	v_mfma_f32_16x16x32_bf16 v[62:65], v[82:85], v[158:161], v[62:65]
	v_mfma_f32_16x16x32_bf16 v[58:61], v[98:101], v[158:161], v[58:61]
	v_mfma_f32_16x16x32_bf16 v[46:49], v[82:85], v[174:177], v[46:49]
	v_mfma_f32_16x16x32_bf16 v[42:45], v[98:101], v[174:177], v[42:45]
	v_mfma_f32_16x16x32_bf16 v[30:33], v[82:85], v[182:185], v[30:33]
	v_mfma_f32_16x16x32_bf16 v[26:29], v[98:101], v[182:185], v[26:29]
	v_mfma_f32_16x16x32_bf16 v[14:17], v[82:85], v[190:193], v[14:17]
	v_mfma_f32_16x16x32_bf16 v[10:13], v[98:101], v[190:193], v[10:13]
	v_mfma_f32_16x16x32_bf16 v[54:57], v[106:109], v[146:149], v[54:57]
	v_mfma_f32_16x16x32_bf16 v[50:53], v[126:129], v[146:149], v[50:53]
	v_mfma_f32_16x16x32_bf16 v[38:41], v[106:109], v[166:169], v[38:41]
	v_mfma_f32_16x16x32_bf16 v[34:37], v[126:129], v[166:169], v[34:37]
	v_mfma_f32_16x16x32_bf16 v[22:25], v[106:109], v[178:181], v[22:25]
	v_mfma_f32_16x16x32_bf16 v[18:21], v[126:129], v[178:181], v[18:21]
	v_mfma_f32_16x16x32_bf16 v[6:9], v[106:109], v[186:189], v[6:9]
	v_mfma_f32_16x16x32_bf16 v[2:5], v[126:129], v[186:189], v[2:5]
	v_mfma_f32_16x16x32_bf16 v[54:57], v[110:113], v[158:161], v[54:57]
	v_mfma_f32_16x16x32_bf16 v[50:53], v[134:137], v[158:161], v[50:53]
	v_mfma_f32_16x16x32_bf16 v[38:41], v[110:113], v[174:177], v[38:41]
	v_mfma_f32_16x16x32_bf16 v[34:37], v[134:137], v[174:177], v[34:37]
	v_mfma_f32_16x16x32_bf16 v[22:25], v[110:113], v[182:185], v[22:25]
	v_mfma_f32_16x16x32_bf16 v[18:21], v[134:137], v[182:185], v[18:21]
	v_mfma_f32_16x16x32_bf16 v[6:9], v[110:113], v[190:193], v[6:9]
	v_mfma_f32_16x16x32_bf16 v[2:5], v[134:137], v[190:193], v[2:5]
	s_setprio 0
	s_barrier
	s_add_i32 s59, s59, 2
	s_add_u32 s49, s49, 0x100
	s_addc_u32 s58, s58, 0
	s_cmpk_gt_u32 s59, 0x55
	s_mov_b64 s[4:5], s[18:19]
	s_cbranch_scc0 .LBB0_1718
	s_and_b64 vcc, exec, s[14:15]
	s_cbranch_vccz .LBB0_1721
	s_barrier

.LBB0_1739:
	s_add_u32 s16, s14, 0x100
	s_addc_u32 s17, s15, 0
	s_add_i32 s0, 0, 0x10000
	s_cmp_eq_u32 s49, 4
	s_cselect_b32 s21, s9, s17
	s_cselect_b32 s20, s8, s16
	s_cselect_b32 s19, s11, s41
	s_cselect_b32 s18, s10, s40
	s_add_i32 s33, 0, 0x14000
	v_add_u32_e32 v152, s0, v136
	v_add_u32_e32 v168, s33, v136
	ds_read_b128 v[140:143], v152
	ds_read_b128 v[144:147], v152 offset:1024
	ds_read_b128 v[148:151], v152 offset:2048
	ds_read_b128 v[152:155], v152 offset:3072
	ds_read_b128 v[156:159], v168
	ds_read_b128 v[160:163], v168 offset:1024
	ds_read_b128 v[164:167], v168 offset:2048
	ds_read_b128 v[168:171], v168 offset:3072
	v_lshl_add_u64 v[200:201], s[14:15], 0, v[132:133]
	s_add_i32 m0, s23, 0xc000
	ds_read_b128 v[172:175], v139
	ds_read_b128 v[176:179], v139 offset:1024
	ds_read_b128 v[180:183], v139 offset:2048
	ds_read_b128 v[184:187], v139 offset:3072
	ds_read_b128 v[188:191], v139 offset:4096
	ds_read_b128 v[192:195], v139 offset:5120
	ds_read_b128 v[196:199], v139 offset:6144
	ds_read_b128 v[208:211], v139 offset:7168
	global_load_lds_dwordx4 v[200:201], off
	v_lshl_add_u64 v[200:201], s[14:15], 0, v[134:135]
	s_add_i32 m0, s23, 0xe000
	s_nop 0
	global_load_lds_dwordx4 v[200:201], off
	s_waitcnt vmcnt(8)
	s_waitcnt lgkmcnt(0)
	s_barrier
	s_setprio 1
	s_waitcnt lgkmcnt(0)
	v_mfma_f32_16x16x32_bf16 v[126:129], v[140:143], v[172:175], v[126:129]
	v_mfma_f32_16x16x32_bf16 v[122:125], v[148:151], v[172:175], v[122:125]
	v_mfma_f32_16x16x32_bf16 v[118:121], v[140:143], v[180:183], v[118:121]
	v_mfma_f32_16x16x32_bf16 v[114:117], v[148:151], v[180:183], v[114:117]
	v_mfma_f32_16x16x32_bf16 v[106:109], v[140:143], v[188:191], v[106:109]
	v_mfma_f32_16x16x32_bf16 v[98:101], v[148:151], v[188:191], v[98:101]
	v_mfma_f32_16x16x32_bf16 v[90:93], v[140:143], v[196:199], v[90:93]
	v_mfma_f32_16x16x32_bf16 v[82:85], v[148:151], v[196:199], v[82:85]
	v_mfma_f32_16x16x32_bf16 v[126:129], v[144:147], v[176:179], v[126:129]
	v_mfma_f32_16x16x32_bf16 v[122:125], v[152:155], v[176:179], v[122:125]
	v_mfma_f32_16x16x32_bf16 v[118:121], v[144:147], v[184:187], v[118:121]
	v_mfma_f32_16x16x32_bf16 v[114:117], v[152:155], v[184:187], v[114:117]
	v_mfma_f32_16x16x32_bf16 v[106:109], v[144:147], v[192:195], v[106:109]
	v_mfma_f32_16x16x32_bf16 v[98:101], v[152:155], v[192:195], v[98:101]
	v_mfma_f32_16x16x32_bf16 v[90:93], v[144:147], v[208:211], v[90:93]
	v_mfma_f32_16x16x32_bf16 v[82:85], v[152:155], v[208:211], v[82:85]
	v_mfma_f32_16x16x32_bf16 v[110:113], v[156:159], v[172:175], v[110:113]
	v_mfma_f32_16x16x32_bf16 v[102:105], v[164:167], v[172:175], v[102:105]
	v_mfma_f32_16x16x32_bf16 v[94:97], v[156:159], v[180:183], v[94:97]
	v_mfma_f32_16x16x32_bf16 v[86:89], v[164:167], v[180:183], v[86:89]
	v_mfma_f32_16x16x32_bf16 v[78:81], v[156:159], v[188:191], v[78:81]
	v_mfma_f32_16x16x32_bf16 v[74:77], v[164:167], v[188:191], v[74:77]
	v_mfma_f32_16x16x32_bf16 v[70:73], v[156:159], v[196:199], v[70:73]
	v_mfma_f32_16x16x32_bf16 v[66:69], v[164:167], v[196:199], v[66:69]
	v_mfma_f32_16x16x32_bf16 v[110:113], v[160:163], v[176:179], v[110:113]
	v_mfma_f32_16x16x32_bf16 v[102:105], v[168:171], v[176:179], v[102:105]
	v_mfma_f32_16x16x32_bf16 v[94:97], v[160:163], v[184:187], v[94:97]
	v_mfma_f32_16x16x32_bf16 v[86:89], v[168:171], v[184:187], v[86:89]
	v_mfma_f32_16x16x32_bf16 v[78:81], v[160:163], v[192:195], v[78:81]
	v_mfma_f32_16x16x32_bf16 v[74:77], v[168:171], v[192:195], v[74:77]
	v_mfma_f32_16x16x32_bf16 v[70:73], v[160:163], v[208:211], v[70:73]
	v_mfma_f32_16x16x32_bf16 v[66:69], v[168:171], v[208:211], v[66:69]
	s_setprio 0
	s_barrier
	s_add_i32 s0, s0, s22
	v_lshl_add_u64 v[200:201], s[18:19], 0, v[202:203]
	s_mov_b32 m0, s0
	ds_read_b128 v[172:175], v139 offset:16384
	ds_read_b128 v[176:179], v139 offset:17408
	ds_read_b128 v[180:183], v139 offset:18432
	ds_read_b128 v[184:187], v139 offset:19456
	ds_read_b128 v[188:191], v139 offset:20480
	ds_read_b128 v[192:195], v139 offset:21504
	ds_read_b128 v[196:199], v139 offset:22528
	ds_read_b128 v[208:211], v139 offset:23552
	global_load_lds_dwordx4 v[200:201], off
	s_add_i32 m0, s0, 0x2000
	s_add_u32 s0, s18, 0x160000
	v_lshl_add_u64 v[204:205], s[18:19], 0, v[130:131]
	s_addc_u32 s1, s19, 0
	s_add_i32 s14, s33, s22
	global_load_lds_dwordx4 v[204:205], off
	v_lshl_add_u64 v[206:207], s[0:1], 0, v[202:203]
	s_mov_b32 m0, s14
	v_lshl_add_u64 v[212:213], s[20:21], 0, v[130:131]
	global_load_lds_dwordx4 v[206:207], off
	v_lshl_add_u64 v[206:207], s[0:1], 0, v[130:131]
	s_add_i32 m0, s14, 0x2000
	s_nop 0
	global_load_lds_dwordx4 v[206:207], off
	v_lshl_add_u64 v[206:207], s[20:21], 0, v[202:203]
	s_mov_b32 m0, s23
	s_nop 0
	global_load_lds_dwordx4 v[206:207], off
	s_mov_b32 m0, s26
	s_nop 0
	global_load_lds_dwordx4 v[212:213], off
	s_waitcnt vmcnt(8)
	s_waitcnt lgkmcnt(0)
	s_barrier
	s_setprio 1
	s_waitcnt lgkmcnt(0)
	v_mfma_f32_16x16x32_bf16 v[62:65], v[140:143], v[172:175], v[62:65]
	v_mfma_f32_16x16x32_bf16 v[58:61], v[148:151], v[172:175], v[58:61]
	v_mfma_f32_16x16x32_bf16 v[54:57], v[140:143], v[180:183], v[54:57]
	v_mfma_f32_16x16x32_bf16 v[50:53], v[148:151], v[180:183], v[50:53]
	v_mfma_f32_16x16x32_bf16 v[38:41], v[140:143], v[188:191], v[38:41]
	v_mfma_f32_16x16x32_bf16 v[34:37], v[148:151], v[188:191], v[34:37]
	v_mfma_f32_16x16x32_bf16 v[22:25], v[140:143], v[196:199], v[22:25]
	v_mfma_f32_16x16x32_bf16 v[18:21], v[148:151], v[196:199], v[18:21]
	v_mfma_f32_16x16x32_bf16 v[62:65], v[144:147], v[176:179], v[62:65]
	v_mfma_f32_16x16x32_bf16 v[58:61], v[152:155], v[176:179], v[58:61]
	v_mfma_f32_16x16x32_bf16 v[54:57], v[144:147], v[184:187], v[54:57]
	v_mfma_f32_16x16x32_bf16 v[50:53], v[152:155], v[184:187], v[50:53]
	v_mfma_f32_16x16x32_bf16 v[38:41], v[144:147], v[192:195], v[38:41]
	v_mfma_f32_16x16x32_bf16 v[34:37], v[152:155], v[192:195], v[34:37]
	v_mfma_f32_16x16x32_bf16 v[22:25], v[144:147], v[208:211], v[22:25]
	v_mfma_f32_16x16x32_bf16 v[18:21], v[152:155], v[208:211], v[18:21]
	v_mfma_f32_16x16x32_bf16 v[46:49], v[156:159], v[172:175], v[46:49]
	v_mfma_f32_16x16x32_bf16 v[42:45], v[164:167], v[172:175], v[42:45]
	v_mfma_f32_16x16x32_bf16 v[30:33], v[156:159], v[180:183], v[30:33]
	v_mfma_f32_16x16x32_bf16 v[26:29], v[164:167], v[180:183], v[26:29]
	v_mfma_f32_16x16x32_bf16 v[14:17], v[156:159], v[188:191], v[14:17]
	v_mfma_f32_16x16x32_bf16 v[10:13], v[164:167], v[188:191], v[10:13]
	v_mfma_f32_16x16x32_bf16 v[6:9], v[156:159], v[196:199], v[6:9]
	v_mfma_f32_16x16x32_bf16 v[2:5], v[164:167], v[196:199], v[2:5]
	v_mfma_f32_16x16x32_bf16 v[46:49], v[160:163], v[176:179], v[46:49]
	v_mfma_f32_16x16x32_bf16 v[42:45], v[168:171], v[176:179], v[42:45]
	v_mfma_f32_16x16x32_bf16 v[30:33], v[160:163], v[184:187], v[30:33]
	v_mfma_f32_16x16x32_bf16 v[26:29], v[168:171], v[184:187], v[26:29]
	v_mfma_f32_16x16x32_bf16 v[14:17], v[160:163], v[192:195], v[14:17]
	v_mfma_f32_16x16x32_bf16 v[10:13], v[168:171], v[192:195], v[10:13]
	v_mfma_f32_16x16x32_bf16 v[6:9], v[160:163], v[208:211], v[6:9]
	v_mfma_f32_16x16x32_bf16 v[2:5], v[168:171], v[208:211], v[2:5]
	s_setprio 0
	s_barrier
	s_add_i32 s14, 0, 0x18000
	s_add_i32 s15, 0, 0x1c000
	v_add_u32_e32 v152, s14, v136
	v_add_u32_e32 v168, s15, v136
	ds_read_b128 v[140:143], v152
	ds_read_b128 v[144:147], v152 offset:1024
	ds_read_b128 v[148:151], v152 offset:2048
	ds_read_b128 v[152:155], v152 offset:3072
	ds_read_b128 v[156:159], v168
	ds_read_b128 v[160:163], v168 offset:1024
	ds_read_b128 v[164:167], v168 offset:2048
	ds_read_b128 v[168:171], v168 offset:3072
	s_add_u32 s0, s20, 0x160000
	s_addc_u32 s1, s21, 0
	s_mov_b32 m0, s27
	v_lshl_add_u64 v[214:215], s[0:1], 0, v[202:203]
	ds_read_b128 v[172:175], v139 offset:32768
	ds_read_b128 v[176:179], v139 offset:33792
	ds_read_b128 v[180:183], v139 offset:34816
	ds_read_b128 v[184:187], v139 offset:35840
	ds_read_b128 v[188:191], v139 offset:36864
	ds_read_b128 v[192:195], v139 offset:37888
	ds_read_b128 v[196:199], v139 offset:38912
	ds_read_b128 v[208:211], v139 offset:39936
	global_load_lds_dwordx4 v[214:215], off
	v_lshl_add_u64 v[214:215], s[0:1], 0, v[130:131]
	s_mov_b32 m0, s28
	s_nop 0
	global_load_lds_dwordx4 v[214:215], off
	s_waitcnt vmcnt(8)
	s_waitcnt lgkmcnt(0)
	s_barrier
	s_setprio 1
	s_waitcnt lgkmcnt(0)
	v_mfma_f32_16x16x32_bf16 v[126:129], v[140:143], v[172:175], v[126:129]
	v_mfma_f32_16x16x32_bf16 v[122:125], v[148:151], v[172:175], v[122:125]
	v_mfma_f32_16x16x32_bf16 v[118:121], v[140:143], v[180:183], v[118:121]
	v_mfma_f32_16x16x32_bf16 v[114:117], v[148:151], v[180:183], v[114:117]
	v_mfma_f32_16x16x32_bf16 v[106:109], v[140:143], v[188:191], v[106:109]
	v_mfma_f32_16x16x32_bf16 v[98:101], v[148:151], v[188:191], v[98:101]
	v_mfma_f32_16x16x32_bf16 v[90:93], v[140:143], v[196:199], v[90:93]
	v_mfma_f32_16x16x32_bf16 v[82:85], v[148:151], v[196:199], v[82:85]
	v_mfma_f32_16x16x32_bf16 v[126:129], v[144:147], v[176:179], v[126:129]
	v_mfma_f32_16x16x32_bf16 v[122:125], v[152:155], v[176:179], v[122:125]
	v_mfma_f32_16x16x32_bf16 v[118:121], v[144:147], v[184:187], v[118:121]
	v_mfma_f32_16x16x32_bf16 v[114:117], v[152:155], v[184:187], v[114:117]
	v_mfma_f32_16x16x32_bf16 v[106:109], v[144:147], v[192:195], v[106:109]
	v_mfma_f32_16x16x32_bf16 v[98:101], v[152:155], v[192:195], v[98:101]
	v_mfma_f32_16x16x32_bf16 v[90:93], v[144:147], v[208:211], v[90:93]
	v_mfma_f32_16x16x32_bf16 v[82:85], v[152:155], v[208:211], v[82:85]
	v_mfma_f32_16x16x32_bf16 v[110:113], v[156:159], v[172:175], v[110:113]
	v_mfma_f32_16x16x32_bf16 v[102:105], v[164:167], v[172:175], v[102:105]
	v_mfma_f32_16x16x32_bf16 v[94:97], v[156:159], v[180:183], v[94:97]
	v_mfma_f32_16x16x32_bf16 v[86:89], v[164:167], v[180:183], v[86:89]
	v_mfma_f32_16x16x32_bf16 v[78:81], v[156:159], v[188:191], v[78:81]
	v_mfma_f32_16x16x32_bf16 v[74:77], v[164:167], v[188:191], v[74:77]
	v_mfma_f32_16x16x32_bf16 v[70:73], v[156:159], v[196:199], v[70:73]
	v_mfma_f32_16x16x32_bf16 v[66:69], v[164:167], v[196:199], v[66:69]
	v_mfma_f32_16x16x32_bf16 v[110:113], v[160:163], v[176:179], v[110:113]
	v_mfma_f32_16x16x32_bf16 v[102:105], v[168:171], v[176:179], v[102:105]
	v_mfma_f32_16x16x32_bf16 v[94:97], v[160:163], v[184:187], v[94:97]
	v_mfma_f32_16x16x32_bf16 v[86:89], v[168:171], v[184:187], v[86:89]
	v_mfma_f32_16x16x32_bf16 v[78:81], v[160:163], v[192:195], v[78:81]
	v_mfma_f32_16x16x32_bf16 v[74:77], v[168:171], v[192:195], v[74:77]
	v_mfma_f32_16x16x32_bf16 v[70:73], v[160:163], v[208:211], v[70:73]
	v_mfma_f32_16x16x32_bf16 v[66:69], v[168:171], v[208:211], v[66:69]
	s_setprio 0
	s_barrier
	s_add_i32 s0, s14, s22
	v_lshl_add_u64 v[200:201], v[200:201], 0, s[80:81]
	s_mov_b32 m0, s0
	ds_read_b128 v[172:175], v139 offset:49152
	ds_read_b128 v[176:179], v139 offset:50176
	ds_read_b128 v[180:183], v139 offset:51200
	ds_read_b128 v[184:187], v139 offset:52224
	ds_read_b128 v[188:191], v139 offset:53248
	ds_read_b128 v[192:195], v139 offset:54272
	ds_read_b128 v[196:199], v139 offset:55296
	ds_read_b128 v[208:211], v139 offset:56320
	global_load_lds_dwordx4 v[200:201], off
	s_add_i32 m0, s0, 0x2000
	s_add_u32 s0, s18, 0x160080
	v_lshl_add_u64 v[200:201], v[204:205], 0, s[80:81]
	s_addc_u32 s1, s19, 0
	s_add_i32 s14, s15, s22
	global_load_lds_dwordx4 v[200:201], off
	v_lshl_add_u64 v[200:201], s[0:1], 0, v[202:203]
	s_mov_b32 m0, s14
	s_nop 0
	global_load_lds_dwordx4 v[200:201], off
	v_lshl_add_u64 v[200:201], s[0:1], 0, v[130:131]
	s_add_i32 m0, s14, 0x2000
	s_nop 0
	global_load_lds_dwordx4 v[200:201], off
	v_lshl_add_u64 v[200:201], v[206:207], 0, s[80:81]
	s_mov_b32 m0, s29
	s_nop 0
	global_load_lds_dwordx4 v[200:201], off
	v_lshl_add_u64 v[200:201], v[212:213], 0, s[80:81]
	s_mov_b32 m0, s30
	s_nop 0
	global_load_lds_dwordx4 v[200:201], off
	s_waitcnt vmcnt(8)
	s_waitcnt lgkmcnt(0)
	s_barrier
	s_setprio 1
	s_waitcnt lgkmcnt(0)
	v_mfma_f32_16x16x32_bf16 v[62:65], v[140:143], v[172:175], v[62:65]
	v_mfma_f32_16x16x32_bf16 v[58:61], v[148:151], v[172:175], v[58:61]
	v_mfma_f32_16x16x32_bf16 v[54:57], v[140:143], v[180:183], v[54:57]
	v_mfma_f32_16x16x32_bf16 v[50:53], v[148:151], v[180:183], v[50:53]
	v_mfma_f32_16x16x32_bf16 v[38:41], v[140:143], v[188:191], v[38:41]
	v_mfma_f32_16x16x32_bf16 v[34:37], v[148:151], v[188:191], v[34:37]
	v_mfma_f32_16x16x32_bf16 v[22:25], v[140:143], v[196:199], v[22:25]
	v_mfma_f32_16x16x32_bf16 v[18:21], v[148:151], v[196:199], v[18:21]
	v_mfma_f32_16x16x32_bf16 v[62:65], v[144:147], v[176:179], v[62:65]
	v_mfma_f32_16x16x32_bf16 v[58:61], v[152:155], v[176:179], v[58:61]
	v_mfma_f32_16x16x32_bf16 v[54:57], v[144:147], v[184:187], v[54:57]
	v_mfma_f32_16x16x32_bf16 v[50:53], v[152:155], v[184:187], v[50:53]
	v_mfma_f32_16x16x32_bf16 v[38:41], v[144:147], v[192:195], v[38:41]
	v_mfma_f32_16x16x32_bf16 v[34:37], v[152:155], v[192:195], v[34:37]
	v_mfma_f32_16x16x32_bf16 v[22:25], v[144:147], v[208:211], v[22:25]
	v_mfma_f32_16x16x32_bf16 v[18:21], v[152:155], v[208:211], v[18:21]
	v_mfma_f32_16x16x32_bf16 v[46:49], v[156:159], v[172:175], v[46:49]
	v_mfma_f32_16x16x32_bf16 v[42:45], v[164:167], v[172:175], v[42:45]
	v_mfma_f32_16x16x32_bf16 v[30:33], v[156:159], v[180:183], v[30:33]
	v_mfma_f32_16x16x32_bf16 v[26:29], v[164:167], v[180:183], v[26:29]
	v_mfma_f32_16x16x32_bf16 v[14:17], v[156:159], v[188:191], v[14:17]
	v_mfma_f32_16x16x32_bf16 v[10:13], v[164:167], v[188:191], v[10:13]
	v_mfma_f32_16x16x32_bf16 v[6:9], v[156:159], v[196:199], v[6:9]
	v_mfma_f32_16x16x32_bf16 v[2:5], v[164:167], v[196:199], v[2:5]
	v_mfma_f32_16x16x32_bf16 v[46:49], v[160:163], v[176:179], v[46:49]
	v_mfma_f32_16x16x32_bf16 v[42:45], v[168:171], v[176:179], v[42:45]
	v_mfma_f32_16x16x32_bf16 v[30:33], v[160:163], v[184:187], v[30:33]
	v_mfma_f32_16x16x32_bf16 v[26:29], v[168:171], v[184:187], v[26:29]
	v_mfma_f32_16x16x32_bf16 v[14:17], v[160:163], v[192:195], v[14:17]
	v_mfma_f32_16x16x32_bf16 v[10:13], v[168:171], v[192:195], v[10:13]
	v_mfma_f32_16x16x32_bf16 v[6:9], v[160:163], v[208:211], v[6:9]
	v_mfma_f32_16x16x32_bf16 v[2:5], v[168:171], v[208:211], v[2:5]
	s_setprio 0
	s_barrier
	s_add_i32 s49, s49, 2
	s_add_u32 s40, s40, 0x100
	s_addc_u32 s41, s41, 0
	s_cmp_gt_u32 s49, 5
	s_mov_b64 s[14:15], s[16:17]
	s_cbranch_scc0 .LBB0_1739
	s_and_b64 vcc, exec, s[6:7]
	s_cbranch_vccz .LBB0_1742
	s_barrier
